# stack2 + GEMM K-loop: s_setprio 1 moved ahead of the pre-MFMA barrier and the redundant post-barrier lgkmcnt(0) removed (shorter barrier->first-MFMA handoff)
# speedup vs baseline: 1.0065x; 1.0065x over previous
; #define PG8_SB(B) __builtin_amdgcn_rcpf(1.f + expneg(B))
; #define PG8_SB(B) __builtin_amdgcn_rcpf(1.f + expneg(B))
; #define PG8_STAGE(bufoff, gbase, voff) do { _Pragma("unroll") for (int _i = 0; _i < 2; ++_i) \
;         __builtin_amdgcn_global_load_lds((const unsigned*)((const char*)(gbase) + (size_t)_i * qstep + (voff)[0]), (PG8_LAS unsigned*)(lds + (bufoff) + ldsw + _i * 8192), 16, 0, 0); } while (0)
; #define PG8_LDA(dst, b, h) do { _Pragma("unroll") for (int m = 0; m < 4; ++m) _Pragma("unroll") for (int k = 0; k < 2; ++k) dst[m][k] = *(const PG8_LAS bf16x8*)(lds + PG8_SA(b, h) + aoff + m * 2048 + k * 1024); } while (0)
; #define PG8_LDB(dst, b, h) do { _Pragma("unroll") for (int n = 0; n < 2; ++n) _Pragma("unroll") for (int k = 0; k < 2; ++k) dst[n][k] = *(const PG8_LAS bf16x8*)(lds + PG8_SB(b, h) + boff + n * 2048 + k * 1024); } while (0)
; #define PG8_MMA(ai, bj, At, Bt) do { __builtin_amdgcn_s_setprio(1); _Pragma("unroll") for (int m = 0; m < 4; ++m) _Pragma("unroll") for (int n = 0; n < 2; ++n) _Pragma("unroll") for (int k = 0; k < 2; ++k) \
;         acc[ai][bj][m][n] = __builtin_amdgcn_mfma_f32_16x16x32_bf16(Bt[n][k], At[m][k], acc[ai][bj][m][n], 0, 0, 0); __builtin_amdgcn_s_setprio(0); } while (0)
; #define PG8_WAIT_V89() do { if constexpr (SLIVER) PG8_WAIT_V(9); else PG8_WAIT_V(8); } while (0)
; #define PG8_STAGE_S(b, gbase) do { if constexpr (SLIVER) __builtin_amdgcn_global_load_lds((const unsigned*)((const char*)(gbase) + voffS), (PG8_LAS unsigned*)(lds + STAGE_BYTES + (b) * 2048 + wid * 256), 4, 0, 0); } while (0)
; #define PG8_BAR __builtin_amdgcn_s_barrier()
; template <class Epi, class Sched, bool ALIGN_EPI = false, bool SP2 = false, bool SLIVER = false>
; __device__ __forceinline__ void gemm_phase(PG8_LAS unsigned char* lds, const Gemm g, const Sched& S, const Epi& E) {
;     ...
;             PG8_LDB(B0, 0, 0); PG8_LDB(B1, 0, 1); PG8_SCHED; PG8_LDA(At, 0, 0); PG8_STAGE(PG8_SA(1, 1), a1 + hstep, voffA); PG8_STAGE_S(1, s1);
;             PG8_WAIT_V89(); PG8_WAIT_L(0); PG8_BAR; PG8_MMA(0, 0, At, B0); PG8_MMA(0, 1, At, B1); PG8_BAR; PG8_SCHED;
;             PG8_LDA(At, 0, 1); PG8_LDS_S(0); PG8_STAGE(PG8_SB(0, 0), b2, voffB); PG8_STAGE(PG8_SB(0, 1), b2 + hstep, voffB); PG8_STAGE(PG8_SA(0, 0), a2, voffA);
;             PG8_WAIT_V89(); PG8_WAIT_L(0); PG8_BAR; PG8_MMA(1, 0, At, B0); PG8_MMA(1, 1, At, B1); PG8_MMA_S(); PG8_BAR; PG8_SCHED;
.Lgin_skipw0:
	s_waitcnt lgkmcnt(0)
	s_setprio 1
	s_barrier
	v_mfma_f32_16x16x32_bf16 v[126:129], v[136:139], v[174:177], v[126:129]
	v_mfma_f32_16x16x32_bf16 v[122:125], v[150:153], v[174:177], v[122:125]
	v_mfma_f32_16x16x32_bf16 v[114:117], v[136:139], v[184:187], v[114:117]
	v_mfma_f32_16x16x32_bf16 v[106:109], v[150:153], v[184:187], v[106:109]
	v_mfma_f32_16x16x32_bf16 v[98:101], v[136:139], v[192:195], v[98:101]
	v_mfma_f32_16x16x32_bf16 v[90:93], v[150:153], v[192:195], v[90:93]
	v_mfma_f32_16x16x32_bf16 v[82:85], v[136:139], v[200:203], v[82:85]
	v_mfma_f32_16x16x32_bf16 v[74:77], v[150:153], v[200:203], v[74:77]
	v_mfma_f32_16x16x32_bf16 v[126:129], v[140:143], v[180:183], v[126:129]
	v_mfma_f32_16x16x32_bf16 v[122:125], v[154:157], v[180:183], v[122:125]
	v_mfma_f32_16x16x32_bf16 v[114:117], v[140:143], v[188:191], v[114:117]
	v_mfma_f32_16x16x32_bf16 v[106:109], v[154:157], v[188:191], v[106:109]
	v_mfma_f32_16x16x32_bf16 v[98:101], v[140:143], v[196:199], v[98:101]
	v_mfma_f32_16x16x32_bf16 v[90:93], v[154:157], v[196:199], v[90:93]
	v_mfma_f32_16x16x32_bf16 v[82:85], v[140:143], v[210:213], v[82:85]
	v_mfma_f32_16x16x32_bf16 v[74:77], v[154:157], v[210:213], v[74:77]
	s_setprio 0
	s_setprio 1
	v_mfma_f32_16x16x32_bf16 v[118:121], v[158:161], v[174:177], v[118:121]
	v_mfma_f32_16x16x32_bf16 v[110:113], v[166:169], v[174:177], v[110:113]
	v_mfma_f32_16x16x32_bf16 v[102:105], v[158:161], v[184:187], v[102:105]
	v_mfma_f32_16x16x32_bf16 v[94:97], v[166:169], v[184:187], v[94:97]
	v_mfma_f32_16x16x32_bf16 v[86:89], v[158:161], v[192:195], v[86:89]
	v_mfma_f32_16x16x32_bf16 v[78:81], v[166:169], v[192:195], v[78:81]
	v_mfma_f32_16x16x32_bf16 v[70:73], v[158:161], v[200:203], v[70:73]
	v_mfma_f32_16x16x32_bf16 v[66:69], v[166:169], v[200:203], v[66:69]
	v_mfma_f32_16x16x32_bf16 v[118:121], v[162:165], v[180:183], v[118:121]
	v_mfma_f32_16x16x32_bf16 v[110:113], v[170:173], v[180:183], v[110:113]
	v_mfma_f32_16x16x32_bf16 v[102:105], v[162:165], v[188:191], v[102:105]
	v_mfma_f32_16x16x32_bf16 v[94:97], v[170:173], v[188:191], v[94:97]
	v_mfma_f32_16x16x32_bf16 v[86:89], v[162:165], v[196:199], v[86:89]
	v_mfma_f32_16x16x32_bf16 v[78:81], v[170:173], v[196:199], v[78:81]
	v_mfma_f32_16x16x32_bf16 v[70:73], v[162:165], v[210:213], v[70:73]
	v_mfma_f32_16x16x32_bf16 v[66:69], v[170:173], v[210:213], v[66:69]
	s_setprio 0
	s_barrier
	s_add_i32 s77, s77, s53
	v_lshl_add_u64 v[146:147], s[78:79], 0, v[132:133]
	s_mov_b32 m0, s77
	ds_read_b128 v[174:177], v149 offset:16384
	ds_read_b128 v[180:183], v149 offset:17408
	ds_read_b128 v[184:187], v149 offset:18432
	ds_read_b128 v[188:191], v149 offset:19456
	ds_read_b128 v[192:195], v149 offset:20480
	ds_read_b128 v[196:199], v149 offset:21504
	ds_read_b128 v[200:203], v149 offset:22528
	ds_read_b128 v[210:213], v149 offset:23552
	global_load_lds_dwordx4 v[146:147], off
	v_lshl_add_u64 v[214:215], v[146:147], 0, s[20:21]
	s_add_i32 m0, s77, 0x2000
	s_add_i32 s77, s80, s53
	global_load_lds_dwordx4 v[214:215], off
	v_lshl_add_u64 v[214:215], v[146:147], 0, s[22:23]
	s_mov_b32 m0, s77
	s_nop 0
	global_load_lds_dwordx4 v[214:215], off
	v_lshl_add_u64 v[214:215], v[146:147], 0, s[24:25]
	s_add_i32 m0, s77, 0x2000
	s_nop 0
	global_load_lds_dwordx4 v[214:215], off
	v_lshl_add_u64 v[214:215], s[62:63], 0, v[130:131]
	s_mov_b32 m0, s91
	v_lshl_add_u64 v[216:217], v[214:215], 0, s[20:21]
	global_load_lds_dwordx4 v[214:215], off
	s_mov_b32 m0, s50
	s_nop 0
	global_load_lds_dwordx4 v[216:217], off
	s_cmp_eq_u32 s76, s101
	s_cbranch_scc1 .Lgin_skipw1
	s_waitcnt vmcnt(8)
.Lgin_skipw1:
	s_waitcnt lgkmcnt(0)
	s_setprio 1
	s_barrier
	v_mfma_f32_16x16x32_bf16 v[62:65], v[136:139], v[174:177], v[62:65]
	v_mfma_f32_16x16x32_bf16 v[58:61], v[150:153], v[174:177], v[58:61]
	v_mfma_f32_16x16x32_bf16 v[50:53], v[136:139], v[184:187], v[50:53]
	v_mfma_f32_16x16x32_bf16 v[42:45], v[150:153], v[184:187], v[42:45]
	v_mfma_f32_16x16x32_bf16 v[34:37], v[136:139], v[192:195], v[34:37]
	v_mfma_f32_16x16x32_bf16 v[26:29], v[150:153], v[192:195], v[26:29]
	v_mfma_f32_16x16x32_bf16 v[18:21], v[136:139], v[200:203], v[18:21]
	v_mfma_f32_16x16x32_bf16 v[10:13], v[150:153], v[200:203], v[10:13]
	v_mfma_f32_16x16x32_bf16 v[62:65], v[140:143], v[180:183], v[62:65]
	v_mfma_f32_16x16x32_bf16 v[58:61], v[154:157], v[180:183], v[58:61]
	v_mfma_f32_16x16x32_bf16 v[50:53], v[140:143], v[188:191], v[50:53]
	v_mfma_f32_16x16x32_bf16 v[42:45], v[154:157], v[188:191], v[42:45]
	v_mfma_f32_16x16x32_bf16 v[34:37], v[140:143], v[196:199], v[34:37]
	v_mfma_f32_16x16x32_bf16 v[26:29], v[154:157], v[196:199], v[26:29]
	v_mfma_f32_16x16x32_bf16 v[18:21], v[140:143], v[210:213], v[18:21]
	v_mfma_f32_16x16x32_bf16 v[10:13], v[154:157], v[210:213], v[10:13]
	s_setprio 0
	s_setprio 1
	v_mfma_f32_16x16x32_bf16 v[54:57], v[158:161], v[174:177], v[54:57]
	v_mfma_f32_16x16x32_bf16 v[46:49], v[166:169], v[174:177], v[46:49]
	v_mfma_f32_16x16x32_bf16 v[38:41], v[158:161], v[184:187], v[38:41]
	v_mfma_f32_16x16x32_bf16 v[30:33], v[166:169], v[184:187], v[30:33]
	v_mfma_f32_16x16x32_bf16 v[22:25], v[158:161], v[192:195], v[22:25]
	v_mfma_f32_16x16x32_bf16 v[14:17], v[166:169], v[192:195], v[14:17]
	v_mfma_f32_16x16x32_bf16 v[6:9], v[158:161], v[200:203], v[6:9]
	v_mfma_f32_16x16x32_bf16 v[2:5], v[166:169], v[200:203], v[2:5]
	v_mfma_f32_16x16x32_bf16 v[54:57], v[162:165], v[180:183], v[54:57]
	v_mfma_f32_16x16x32_bf16 v[46:49], v[170:173], v[180:183], v[46:49]
	v_mfma_f32_16x16x32_bf16 v[38:41], v[162:165], v[188:191], v[38:41]
	v_mfma_f32_16x16x32_bf16 v[30:33], v[170:173], v[188:191], v[30:33]
	v_mfma_f32_16x16x32_bf16 v[22:25], v[162:165], v[196:199], v[22:25]
	v_mfma_f32_16x16x32_bf16 v[14:17], v[170:173], v[196:199], v[14:17]
	v_mfma_f32_16x16x32_bf16 v[6:9], v[162:165], v[210:213], v[6:9]
	v_mfma_f32_16x16x32_bf16 v[2:5], v[170:173], v[210:213], v[2:5]
	s_setprio 0
	s_barrier
; #define PG8_STAGE(bufoff, gbase, voff) do { _Pragma("unroll") for (int _i = 0; _i < 2; ++_i) \
;         __builtin_amdgcn_global_load_lds((const unsigned*)((const char*)(gbase) + (size_t)_i * qstep + (voff)[0]), (PG8_LAS unsigned*)(lds + (bufoff) + ldsw + _i * 8192), 16, 0, 0); } while (0)
; #define PG8_LDA(dst, b, h) do { _Pragma("unroll") for (int m = 0; m < 4; ++m) _Pragma("unroll") for (int k = 0; k < 2; ++k) dst[m][k] = *(const PG8_LAS bf16x8*)(lds + PG8_SA(b, h) + aoff + m * 2048 + k * 1024); } while (0)
; #define PG8_LDB(dst, b, h) do { _Pragma("unroll") for (int n = 0; n < 2; ++n) _Pragma("unroll") for (int k = 0; k < 2; ++k) dst[n][k] = *(const PG8_LAS bf16x8*)(lds + PG8_SB(b, h) + boff + n * 2048 + k * 1024); } while (0)
; #define PG8_MMA(ai, bj, At, Bt) do { __builtin_amdgcn_s_setprio(1); _Pragma("unroll") for (int m = 0; m < 4; ++m) _Pragma("unroll") for (int n = 0; n < 2; ++n) _Pragma("unroll") for (int k = 0; k < 2; ++k) \
;         acc[ai][bj][m][n] = __builtin_amdgcn_mfma_f32_16x16x32_bf16(Bt[n][k], At[m][k], acc[ai][bj][m][n], 0, 0, 0); __builtin_amdgcn_s_setprio(0); } while (0)
; #define PG8_WAIT_V89() do { if constexpr (SLIVER) PG8_WAIT_V(9); else PG8_WAIT_V(8); } while (0)
; #define PG8_STAGE_S(b, gbase) do { if constexpr (SLIVER) __builtin_amdgcn_global_load_lds((const unsigned*)((const char*)(gbase) + voffS), (PG8_LAS unsigned*)(lds + STAGE_BYTES + (b) * 2048 + wid * 256), 4, 0, 0); } while (0)
; #define PG8_WAIT_L(n) asm volatile("s_waitcnt lgkmcnt(" #n ")" ::: "memory")
; #define PG8_BAR __builtin_amdgcn_s_barrier()
; #define PG8_SCHED __builtin_amdgcn_sched_barrier(0)
; template <class Epi, class Sched, bool ALIGN_EPI = false, bool SP2 = false, bool SLIVER = false>
; __device__ __forceinline__ void gemm_phase(PG8_LAS unsigned char* lds, const Gemm g, const Sched& S, const Epi& E) {
;     ...
;             PG8_LDB(B0, 1, 0); PG8_LDB(B1, 1, 1); PG8_SCHED; PG8_LDA(At, 1, 0); PG8_STAGE(PG8_SA(0, 1), a2 + hstep, voffA); PG8_STAGE_S(0, s2);
;             PG8_WAIT_V89(); PG8_WAIT_L(0); PG8_BAR; PG8_MMA(0, 0, At, B0); PG8_MMA(0, 1, At, B1); PG8_BAR; PG8_SCHED;
	s_add_i32 s62, 0, 0x18000
	v_add_u32_e32 v144, s62, v145
	s_add_i32 s63, 0, 0x1c000
	ds_read_b128 v[136:139], v144
	ds_read_b128 v[140:143], v144 offset:1024
	ds_read_b128 v[150:153], v144 offset:2048
	ds_read_b128 v[154:157], v144 offset:3072
	v_add_u32_e32 v144, s63, v145
	ds_read_b128 v[158:161], v144
	ds_read_b128 v[162:165], v144 offset:1024
	ds_read_b128 v[166:169], v144 offset:2048
	ds_read_b128 v[170:173], v144 offset:3072
	s_mov_b32 m0, s51
	v_lshl_add_u64 v[216:217], v[214:215], 0, s[22:23]
	ds_read_b128 v[174:177], v149 offset:32768
	ds_read_b128 v[180:183], v149 offset:33792
	ds_read_b128 v[184:187], v149 offset:34816
	ds_read_b128 v[188:191], v149 offset:35840
	ds_read_b128 v[192:195], v149 offset:36864
	ds_read_b128 v[196:199], v149 offset:37888
	ds_read_b128 v[200:203], v149 offset:38912
	ds_read_b128 v[210:213], v149 offset:39936
	global_load_lds_dwordx4 v[216:217], off
	v_lshl_add_u64 v[216:217], v[214:215], 0, s[24:25]
	s_mov_b32 m0, s54
	s_nop 0
	global_load_lds_dwordx4 v[216:217], off
	s_waitcnt vmcnt(8)
	s_waitcnt lgkmcnt(0)
	s_setprio 1
	s_barrier
	v_mfma_f32_16x16x32_bf16 v[126:129], v[136:139], v[174:177], v[126:129]
	v_mfma_f32_16x16x32_bf16 v[122:125], v[150:153], v[174:177], v[122:125]
	v_mfma_f32_16x16x32_bf16 v[114:117], v[136:139], v[184:187], v[114:117]
	v_mfma_f32_16x16x32_bf16 v[106:109], v[150:153], v[184:187], v[106:109]
	v_mfma_f32_16x16x32_bf16 v[98:101], v[136:139], v[192:195], v[98:101]
	v_mfma_f32_16x16x32_bf16 v[90:93], v[150:153], v[192:195], v[90:93]
	v_mfma_f32_16x16x32_bf16 v[82:85], v[136:139], v[200:203], v[82:85]
	v_mfma_f32_16x16x32_bf16 v[74:77], v[150:153], v[200:203], v[74:77]
	v_mfma_f32_16x16x32_bf16 v[126:129], v[140:143], v[180:183], v[126:129]
	v_mfma_f32_16x16x32_bf16 v[122:125], v[154:157], v[180:183], v[122:125]
	v_mfma_f32_16x16x32_bf16 v[114:117], v[140:143], v[188:191], v[114:117]
	v_mfma_f32_16x16x32_bf16 v[106:109], v[154:157], v[188:191], v[106:109]
	v_mfma_f32_16x16x32_bf16 v[98:101], v[140:143], v[196:199], v[98:101]
	v_mfma_f32_16x16x32_bf16 v[90:93], v[154:157], v[196:199], v[90:93]
	v_mfma_f32_16x16x32_bf16 v[82:85], v[140:143], v[210:213], v[82:85]
	v_mfma_f32_16x16x32_bf16 v[74:77], v[154:157], v[210:213], v[74:77]
	s_setprio 0
	s_setprio 1
	v_mfma_f32_16x16x32_bf16 v[118:121], v[158:161], v[174:177], v[118:121]
	v_mfma_f32_16x16x32_bf16 v[110:113], v[166:169], v[174:177], v[110:113]
	v_mfma_f32_16x16x32_bf16 v[102:105], v[158:161], v[184:187], v[102:105]
	v_mfma_f32_16x16x32_bf16 v[94:97], v[166:169], v[184:187], v[94:97]
	v_mfma_f32_16x16x32_bf16 v[86:89], v[158:161], v[192:195], v[86:89]
	v_mfma_f32_16x16x32_bf16 v[78:81], v[166:169], v[192:195], v[78:81]
	v_mfma_f32_16x16x32_bf16 v[70:73], v[158:161], v[200:203], v[70:73]
	v_mfma_f32_16x16x32_bf16 v[66:69], v[166:169], v[200:203], v[66:69]
	v_mfma_f32_16x16x32_bf16 v[118:121], v[162:165], v[180:183], v[118:121]
	v_mfma_f32_16x16x32_bf16 v[110:113], v[170:173], v[180:183], v[110:113]
	v_mfma_f32_16x16x32_bf16 v[102:105], v[162:165], v[188:191], v[102:105]
	v_mfma_f32_16x16x32_bf16 v[94:97], v[170:173], v[188:191], v[94:97]
	v_mfma_f32_16x16x32_bf16 v[86:89], v[162:165], v[196:199], v[86:89]
	v_mfma_f32_16x16x32_bf16 v[78:81], v[170:173], v[196:199], v[78:81]
	v_mfma_f32_16x16x32_bf16 v[70:73], v[162:165], v[210:213], v[70:73]
	v_mfma_f32_16x16x32_bf16 v[66:69], v[170:173], v[210:213], v[66:69]
	s_setprio 0
	s_barrier
; #define PG8_SB(B) __builtin_amdgcn_rcpf(1.f + expneg(B))
; #define PG8_SB(B) __builtin_amdgcn_rcpf(1.f + expneg(B))
; #define PG8_STAGE(bufoff, gbase, voff) do { _Pragma("unroll") for (int _i = 0; _i < 2; ++_i) \
;         __builtin_amdgcn_global_load_lds((const unsigned*)((const char*)(gbase) + (size_t)_i * qstep + (voff)[0]), (PG8_LAS unsigned*)(lds + (bufoff) + ldsw + _i * 8192), 16, 0, 0); } while (0)
; #define PG8_LDA(dst, b, h) do { _Pragma("unroll") for (int m = 0; m < 4; ++m) _Pragma("unroll") for (int k = 0; k < 2; ++k) dst[m][k] = *(const PG8_LAS bf16x8*)(lds + PG8_SA(b, h) + aoff + m * 2048 + k * 1024); } while (0)
; #define PG8_MMA(ai, bj, At, Bt) do { __builtin_amdgcn_s_setprio(1); _Pragma("unroll") for (int m = 0; m < 4; ++m) _Pragma("unroll") for (int n = 0; n < 2; ++n) _Pragma("unroll") for (int k = 0; k < 2; ++k) \
;         acc[ai][bj][m][n] = __builtin_amdgcn_mfma_f32_16x16x32_bf16(Bt[n][k], At[m][k], acc[ai][bj][m][n], 0, 0, 0); __builtin_amdgcn_s_setprio(0); } while (0)
; #define PG8_WAIT_V89() do { if constexpr (SLIVER) PG8_WAIT_V(9); else PG8_WAIT_V(8); } while (0)
; #define PG8_LDS_S(b) do { if constexpr (SLIVER) { Sf[0] = *(const PG8_LAS bf16x8*)(lds + STAGE_BYTES + (b) * 2048 + soff0); Sf[1] = *(const PG8_LAS bf16x8*)(lds + STAGE_BYTES + (b) * 2048 + (soff0 ^ 64)); } } while (0)
; #define PG8_WAIT_L(n) asm volatile("s_waitcnt lgkmcnt(" #n ")" ::: "memory")
; #define PG8_BAR __builtin_amdgcn_s_barrier()
; #define PG8_SCHED __builtin_amdgcn_sched_barrier(0)
; template <class Epi, class Sched, bool ALIGN_EPI = false, bool SP2 = false, bool SLIVER = false>
; __device__ __forceinline__ void gemm_phase(PG8_LAS unsigned char* lds, const Gemm g, const Sched& S, const Epi& E) {
;     ...
;         for (int t = 0; t < nt; t += 2) {
;     ...
;             PG8_LDA(At, 1, 1); PG8_LDS_S(1); PG8_STAGE(PG8_SB(1, 0), b3, voffB); PG8_STAGE(PG8_SB(1, 1), b3 + hstep, voffB); PG8_STAGE(PG8_SA(1, 0), a3, voffA);
;             PG8_WAIT_V89(); PG8_WAIT_L(0); PG8_BAR; PG8_MMA(1, 0, At, B0); PG8_MMA(1, 1, At, B1); PG8_MMA_S(); PG8_BAR; PG8_SCHED;
;     ...
;         if constexpr (ALIGN_EPI) { if (wr == 0) PG8_BAR; }
	s_add_i32 s62, s62, s53
	v_lshl_add_u64 v[216:217], v[146:147], 0, s[26:27]
	s_mov_b32 m0, s62
	ds_read_b128 v[174:177], v149 offset:49152
	ds_read_b128 v[180:183], v149 offset:50176
	ds_read_b128 v[184:187], v149 offset:51200
	ds_read_b128 v[188:191], v149 offset:52224
	ds_read_b128 v[192:195], v149 offset:53248
	ds_read_b128 v[196:199], v149 offset:54272
	ds_read_b128 v[200:203], v149 offset:55296
	ds_read_b128 v[210:213], v149 offset:56320
	global_load_lds_dwordx4 v[216:217], off
	v_lshl_add_u64 v[216:217], v[146:147], 0, s[28:29]
	s_add_i32 m0, s62, 0x2000
	s_add_i32 s62, s63, s53
	global_load_lds_dwordx4 v[216:217], off
	v_lshl_add_u64 v[216:217], v[146:147], 0, s[30:31]
	s_mov_b32 m0, s62
	v_lshl_add_u64 v[146:147], v[146:147], 0, s[34:35]
	global_load_lds_dwordx4 v[216:217], off
	s_add_i32 m0, s62, 0x2000
	s_nop 0
	global_load_lds_dwordx4 v[146:147], off
	v_lshl_add_u64 v[146:147], v[214:215], 0, s[26:27]
	s_mov_b32 m0, s10
	s_nop 0
	global_load_lds_dwordx4 v[146:147], off
	v_lshl_add_u64 v[146:147], v[214:215], 0, s[28:29]
	s_mov_b32 m0, s55
	s_nop 0
	global_load_lds_dwordx4 v[146:147], off
	s_waitcnt vmcnt(8)
	s_waitcnt lgkmcnt(0)
	s_setprio 1
	s_barrier
	v_mfma_f32_16x16x32_bf16 v[62:65], v[136:139], v[174:177], v[62:65]
	v_mfma_f32_16x16x32_bf16 v[58:61], v[150:153], v[174:177], v[58:61]
	v_mfma_f32_16x16x32_bf16 v[50:53], v[136:139], v[184:187], v[50:53]
	v_mfma_f32_16x16x32_bf16 v[42:45], v[150:153], v[184:187], v[42:45]
	v_mfma_f32_16x16x32_bf16 v[34:37], v[136:139], v[192:195], v[34:37]
	v_mfma_f32_16x16x32_bf16 v[26:29], v[150:153], v[192:195], v[26:29]
	v_mfma_f32_16x16x32_bf16 v[18:21], v[136:139], v[200:203], v[18:21]
	v_mfma_f32_16x16x32_bf16 v[10:13], v[150:153], v[200:203], v[10:13]
	v_mfma_f32_16x16x32_bf16 v[62:65], v[140:143], v[180:183], v[62:65]
	v_mfma_f32_16x16x32_bf16 v[58:61], v[154:157], v[180:183], v[58:61]
	v_mfma_f32_16x16x32_bf16 v[50:53], v[140:143], v[188:191], v[50:53]
	v_mfma_f32_16x16x32_bf16 v[42:45], v[154:157], v[188:191], v[42:45]
	v_mfma_f32_16x16x32_bf16 v[34:37], v[140:143], v[196:199], v[34:37]
	v_mfma_f32_16x16x32_bf16 v[26:29], v[154:157], v[196:199], v[26:29]
	v_mfma_f32_16x16x32_bf16 v[18:21], v[140:143], v[210:213], v[18:21]
	v_mfma_f32_16x16x32_bf16 v[10:13], v[154:157], v[210:213], v[10:13]
	s_setprio 0
	s_setprio 1
	v_mfma_f32_16x16x32_bf16 v[54:57], v[158:161], v[174:177], v[54:57]
	v_mfma_f32_16x16x32_bf16 v[46:49], v[166:169], v[174:177], v[46:49]
	v_mfma_f32_16x16x32_bf16 v[38:41], v[158:161], v[184:187], v[38:41]
	v_mfma_f32_16x16x32_bf16 v[30:33], v[166:169], v[184:187], v[30:33]
	v_mfma_f32_16x16x32_bf16 v[22:25], v[158:161], v[192:195], v[22:25]
	v_mfma_f32_16x16x32_bf16 v[14:17], v[166:169], v[192:195], v[14:17]
	v_mfma_f32_16x16x32_bf16 v[6:9], v[158:161], v[200:203], v[6:9]
	v_mfma_f32_16x16x32_bf16 v[2:5], v[166:169], v[200:203], v[2:5]
	v_mfma_f32_16x16x32_bf16 v[54:57], v[162:165], v[180:183], v[54:57]
	v_mfma_f32_16x16x32_bf16 v[46:49], v[170:173], v[180:183], v[46:49]
	v_mfma_f32_16x16x32_bf16 v[38:41], v[162:165], v[188:191], v[38:41]
	v_mfma_f32_16x16x32_bf16 v[30:33], v[170:173], v[188:191], v[30:33]
	v_mfma_f32_16x16x32_bf16 v[22:25], v[162:165], v[196:199], v[22:25]
	v_mfma_f32_16x16x32_bf16 v[14:17], v[170:173], v[196:199], v[14:17]
	v_mfma_f32_16x16x32_bf16 v[6:9], v[162:165], v[210:213], v[6:9]
	v_mfma_f32_16x16x32_bf16 v[2:5], v[170:173], v[210:213], v[2:5]
	s_setprio 0
	s_barrier
	s_add_i32 s76, s76, 2
	s_add_u32 s40, s40, 0x100
	s_addc_u32 s41, s41, 0
	s_add_u32 s68, s68, 0x100
	s_addc_u32 s69, s69, 0
	s_cmp_gt_u32 s76, 29
	s_cbranch_scc0 .LBB0_153
	s_and_b64 vcc, exec, s[48:49]
	s_cbranch_vccz .LBB0_156
	s_barrier

; #define PG8_STAGE(bufoff, gbase, voff) do { _Pragma("unroll") for (int _i = 0; _i < 2; ++_i) \
;         __builtin_amdgcn_global_load_lds((const unsigned*)((const char*)(gbase) + (size_t)_i * qstep + (voff)[0]), (PG8_LAS unsigned*)(lds + (bufoff) + ldsw + _i * 8192), 16, 0, 0); } while (0)
; #define PG8_LDA(dst, b, h) do { _Pragma("unroll") for (int m = 0; m < 4; ++m) _Pragma("unroll") for (int k = 0; k < 2; ++k) dst[m][k] = *(const PG8_LAS bf16x8*)(lds + PG8_SA(b, h) + aoff + m * 2048 + k * 1024); } while (0)
; #define PG8_LDB(dst, b, h) do { _Pragma("unroll") for (int n = 0; n < 2; ++n) _Pragma("unroll") for (int k = 0; k < 2; ++k) dst[n][k] = *(const PG8_LAS bf16x8*)(lds + PG8_SB(b, h) + boff + n * 2048 + k * 1024); } while (0)
; #define PG8_MMA(ai, bj, At, Bt) do { __builtin_amdgcn_s_setprio(1); _Pragma("unroll") for (int m = 0; m < 4; ++m) _Pragma("unroll") for (int n = 0; n < 2; ++n) _Pragma("unroll") for (int k = 0; k < 2; ++k) \
;         acc[ai][bj][m][n] = __builtin_amdgcn_mfma_f32_16x16x32_bf16(Bt[n][k], At[m][k], acc[ai][bj][m][n], 0, 0, 0); __builtin_amdgcn_s_setprio(0); } while (0)
; #define PG8_WAIT_V89() do { if constexpr (SLIVER) PG8_WAIT_V(9); else PG8_WAIT_V(8); } while (0)
; #define PG8_STAGE_S(b, gbase) do { if constexpr (SLIVER) __builtin_amdgcn_global_load_lds((const unsigned*)((const char*)(gbase) + voffS), (PG8_LAS unsigned*)(lds + STAGE_BYTES + (b) * 2048 + wid * 256), 4, 0, 0); } while (0)
; #define PG8_WAIT_L(n) asm volatile("s_waitcnt lgkmcnt(" #n ")" ::: "memory")
; #define PG8_BAR __builtin_amdgcn_s_barrier()
; #define PG8_SCHED __builtin_amdgcn_sched_barrier(0)
; template <class Epi, class Sched, bool ALIGN_EPI = false, bool SP2 = false, bool SLIVER = false>
; __device__ __forceinline__ void gemm_phase(PG8_LAS unsigned char* lds, const Gemm g, const Sched& S, const Epi& E) {
;     ...
;             PG8_LDB(B0, 0, 0); PG8_LDB(B1, 0, 1); PG8_SCHED; PG8_LDA(At, 0, 0); PG8_STAGE(PG8_SA(1, 1), a1 + hstep, voffA); PG8_STAGE_S(1, s1);
;             PG8_WAIT_V89(); PG8_WAIT_L(0); PG8_BAR; PG8_MMA(0, 0, At, B0); PG8_MMA(0, 1, At, B1); PG8_BAR; PG8_SCHED;
.LBB0_498:
	s_cmp_eq_u32 s66, s80
	s_cselect_b64 s[86:87], -1, 0
	s_add_u32 s40, s16, s80
	s_addc_u32 s41, s17, s81
	s_add_u32 s68, s40, 0x100
	s_addc_u32 s69, s41, 0
	s_and_b64 s[40:41], s[86:87], exec
	s_cselect_b32 s41, s55, s69
	s_cselect_b32 s40, s54, s68
	s_add_u32 s76, s12, s80
	s_addc_u32 s77, s13, s81
	s_add_i32 s78, 0, 0x10000
	s_and_b64 s[68:69], s[86:87], exec
	v_add_u32_e32 v138, s78, v239
	s_cselect_b32 s69, s83, s77
	s_cselect_b32 s68, s82, s76
	s_add_i32 s76, 0, 0x14000
	ds_read_b128 v[146:149], v138
	ds_read_b128 v[150:153], v138 offset:1024
	ds_read_b128 v[154:157], v138 offset:2048
	ds_read_b128 v[158:161], v138 offset:3072
	v_add_u32_e32 v138, s76, v239
	ds_read_b128 v[166:169], v138
	ds_read_b128 v[170:173], v138 offset:1024
	ds_read_b128 v[174:177], v138 offset:2048
	ds_read_b128 v[162:165], v138 offset:3072
	v_lshl_add_u64 v[208:209], v[188:189], 0, s[80:81]
	v_lshl_add_u64 v[224:225], v[208:209], 0, s[34:35]
	s_add_i32 m0, s96, 0xc000
	s_mov_b64 s[88:89], 0x120080
	ds_read_b128 v[138:141], v242
	ds_read_b128 v[142:145], v242 offset:1024
	ds_read_b128 v[180:183], v242 offset:2048
	ds_read_b128 v[184:187], v242 offset:3072
	ds_read_b128 v[192:195], v242 offset:4096
	ds_read_b128 v[196:199], v242 offset:5120
	ds_read_b128 v[200:203], v242 offset:6144
	ds_read_b128 v[220:223], v242 offset:7168
	global_load_lds_dwordx4 v[224:225], off
	v_lshl_add_u64 v[208:209], v[208:209], 0, s[88:89]
	s_add_i32 m0, s96, 0xe000
	s_nop 0
	global_load_lds_dwordx4 v[208:209], off
	v_lshl_add_u64 v[208:209], v[190:191], 0, s[80:81]
	s_add_i32 m0, s94, 0x20800
	s_nop 0
	global_load_lds_dword v[208:209], off
	s_waitcnt vmcnt(9)
	s_waitcnt lgkmcnt(0)
	s_setprio 1
	s_barrier
	v_mfma_f32_16x16x32_bf16 v[134:137], v[146:149], v[138:141], v[134:137]
	v_mfma_f32_16x16x32_bf16 v[130:133], v[154:157], v[138:141], v[130:133]
	v_mfma_f32_16x16x32_bf16 v[126:129], v[146:149], v[180:183], v[126:129]
	v_mfma_f32_16x16x32_bf16 v[122:125], v[154:157], v[180:183], v[122:125]
	v_mfma_f32_16x16x32_bf16 v[118:121], v[146:149], v[192:195], v[118:121]
	v_mfma_f32_16x16x32_bf16 v[114:117], v[154:157], v[192:195], v[114:117]
	v_mfma_f32_16x16x32_bf16 v[110:113], v[146:149], v[200:203], v[110:113]
	v_mfma_f32_16x16x32_bf16 v[106:109], v[154:157], v[200:203], v[106:109]
	v_mfma_f32_16x16x32_bf16 v[134:137], v[150:153], v[142:145], v[134:137]
	v_mfma_f32_16x16x32_bf16 v[130:133], v[158:161], v[142:145], v[130:133]
	v_mfma_f32_16x16x32_bf16 v[126:129], v[150:153], v[184:187], v[126:129]
	v_mfma_f32_16x16x32_bf16 v[122:125], v[158:161], v[184:187], v[122:125]
	v_mfma_f32_16x16x32_bf16 v[118:121], v[150:153], v[196:199], v[118:121]
	v_mfma_f32_16x16x32_bf16 v[114:117], v[158:161], v[196:199], v[114:117]
	v_mfma_f32_16x16x32_bf16 v[110:113], v[150:153], v[220:223], v[110:113]
	v_mfma_f32_16x16x32_bf16 v[106:109], v[158:161], v[220:223], v[106:109]
	s_setprio 0
	s_setprio 1
	v_mfma_f32_16x16x32_bf16 v[102:105], v[166:169], v[138:141], v[102:105]
	v_mfma_f32_16x16x32_bf16 v[98:101], v[174:177], v[138:141], v[98:101]
	v_mfma_f32_16x16x32_bf16 v[90:93], v[166:169], v[180:183], v[90:93]
	v_mfma_f32_16x16x32_bf16 v[86:89], v[174:177], v[180:183], v[86:89]
	v_mfma_f32_16x16x32_bf16 v[78:81], v[166:169], v[192:195], v[78:81]
	v_mfma_f32_16x16x32_bf16 v[74:77], v[174:177], v[192:195], v[74:77]
	v_mfma_f32_16x16x32_bf16 v[70:73], v[166:169], v[200:203], v[70:73]
	v_mfma_f32_16x16x32_bf16 v[66:69], v[174:177], v[200:203], v[66:69]
	v_mfma_f32_16x16x32_bf16 v[102:105], v[170:173], v[142:145], v[102:105]
	v_mfma_f32_16x16x32_bf16 v[98:101], v[162:165], v[142:145], v[98:101]
	v_mfma_f32_16x16x32_bf16 v[90:93], v[170:173], v[184:187], v[90:93]
	v_mfma_f32_16x16x32_bf16 v[86:89], v[162:165], v[184:187], v[86:89]
	v_mfma_f32_16x16x32_bf16 v[78:81], v[170:173], v[196:199], v[78:81]
	v_mfma_f32_16x16x32_bf16 v[74:77], v[162:165], v[196:199], v[74:77]
	v_mfma_f32_16x16x32_bf16 v[70:73], v[170:173], v[220:223], v[70:73]
	v_mfma_f32_16x16x32_bf16 v[66:69], v[162:165], v[220:223], v[66:69]
	s_setprio 0
	s_barrier
; #define PG8_SB(B) __builtin_amdgcn_rcpf(1.f + expneg(B))
; #define PG8_SB(B) __builtin_amdgcn_rcpf(1.f + expneg(B))
; #define PG8_STAGE(bufoff, gbase, voff) do { _Pragma("unroll") for (int _i = 0; _i < 2; ++_i) \
;         __builtin_amdgcn_global_load_lds((const unsigned*)((const char*)(gbase) + (size_t)_i * qstep + (voff)[0]), (PG8_LAS unsigned*)(lds + (bufoff) + ldsw + _i * 8192), 16, 0, 0); } while (0)
; #define PG8_LDA(dst, b, h) do { _Pragma("unroll") for (int m = 0; m < 4; ++m) _Pragma("unroll") for (int k = 0; k < 2; ++k) dst[m][k] = *(const PG8_LAS bf16x8*)(lds + PG8_SA(b, h) + aoff + m * 2048 + k * 1024); } while (0)
; #define PG8_MMA(ai, bj, At, Bt) do { __builtin_amdgcn_s_setprio(1); _Pragma("unroll") for (int m = 0; m < 4; ++m) _Pragma("unroll") for (int n = 0; n < 2; ++n) _Pragma("unroll") for (int k = 0; k < 2; ++k) \
;         acc[ai][bj][m][n] = __builtin_amdgcn_mfma_f32_16x16x32_bf16(Bt[n][k], At[m][k], acc[ai][bj][m][n], 0, 0, 0); __builtin_amdgcn_s_setprio(0); } while (0)
; #define PG8_WAIT_V89() do { if constexpr (SLIVER) PG8_WAIT_V(9); else PG8_WAIT_V(8); } while (0)
; #define PG8_LDS_S(b) do { if constexpr (SLIVER) { Sf[0] = *(const PG8_LAS bf16x8*)(lds + STAGE_BYTES + (b) * 2048 + soff0); Sf[1] = *(const PG8_LAS bf16x8*)(lds + STAGE_BYTES + (b) * 2048 + (soff0 ^ 64)); } } while (0)
; #define PG8_WAIT_L(n) asm volatile("s_waitcnt lgkmcnt(" #n ")" ::: "memory")
; #define PG8_BAR __builtin_amdgcn_s_barrier()
; #define PG8_SCHED __builtin_amdgcn_sched_barrier(0)
; template <class Epi, class Sched, bool ALIGN_EPI = false, bool SP2 = false, bool SLIVER = false>
; __device__ __forceinline__ void gemm_phase(PG8_LAS unsigned char* lds, const Gemm g, const Sched& S, const Epi& E) {
;     ...
;             PG8_LDA(At, 0, 1); PG8_LDS_S(0); PG8_STAGE(PG8_SB(0, 0), b2, voffB); PG8_STAGE(PG8_SB(0, 1), b2 + hstep, voffB); PG8_STAGE(PG8_SA(0, 0), a2, voffA);
;             PG8_WAIT_V89(); PG8_WAIT_L(0); PG8_BAR; PG8_MMA(1, 0, At, B0); PG8_MMA(1, 1, At, B1); PG8_MMA_S(); PG8_BAR; PG8_SCHED;
	s_add_i32 s77, 0, 0x20000
	v_lshl_add_u64 v[192:193], s[68:69], 0, v[212:213]
	s_add_i32 s68, s78, s95
	v_add_u32_e32 v178, s77, v240
	v_add_u32_e32 v184, s77, v241
	s_mov_b32 m0, s68
	s_mov_b64 s[88:89], 0x60000
	ds_read_b128 v[138:141], v242 offset:16384
	ds_read_b128 v[142:145], v242 offset:17408
	ds_read_b128 v[196:199], v242 offset:18432
	ds_read_b128 v[200:203], v242 offset:19456
	ds_read_b128 v[220:223], v242 offset:20480
	ds_read_b128 v[224:227], v242 offset:21504
	ds_read_b128 v[228:231], v242 offset:22528
	ds_read_b128 v[232:235], v242 offset:23552
	ds_read_b128 v[180:183], v178
	ds_read_b128 v[184:187], v184
	global_load_lds_dwordx4 v[192:193], off
	v_lshl_add_u64 v[194:195], v[192:193], 0, s[88:89]
	s_add_i32 m0, s68, 0x2000
	s_add_i32 s68, s76, s95
	global_load_lds_dwordx4 v[194:195], off
	v_lshl_add_u64 v[194:195], v[192:193], 0, s[24:25]
	s_mov_b32 m0, s68
	s_nop 0
	global_load_lds_dwordx4 v[194:195], off
	v_lshl_add_u64 v[194:195], v[192:193], 0, s[14:15]
	s_add_i32 m0, s68, 0x2000
	s_nop 0
	global_load_lds_dwordx4 v[194:195], off
	v_lshl_add_u64 v[194:195], s[40:41], 0, v[210:211]
	s_mov_b32 m0, s96
	v_lshl_add_u64 v[208:209], v[194:195], 0, s[88:89]
	global_load_lds_dwordx4 v[194:195], off
	s_mov_b32 m0, s19
	s_nop 0
	global_load_lds_dwordx4 v[208:209], off
	s_waitcnt vmcnt(9)
	s_waitcnt lgkmcnt(0)
	s_setprio 1
	s_barrier
	v_mfma_f32_16x16x32_bf16 v[62:65], v[146:149], v[138:141], v[62:65]
	v_mfma_f32_16x16x32_bf16 v[58:61], v[154:157], v[138:141], v[58:61]
	v_mfma_f32_16x16x32_bf16 v[54:57], v[146:149], v[196:199], v[54:57]
	v_mfma_f32_16x16x32_bf16 v[50:53], v[154:157], v[196:199], v[50:53]
	v_mfma_f32_16x16x32_bf16 v[46:49], v[146:149], v[220:223], v[46:49]
	v_mfma_f32_16x16x32_bf16 v[42:45], v[154:157], v[220:223], v[42:45]
	v_mfma_f32_16x16x32_bf16 v[38:41], v[146:149], v[228:231], v[38:41]
	v_mfma_f32_16x16x32_bf16 v[34:37], v[154:157], v[228:231], v[34:37]
	v_mfma_f32_16x16x32_bf16 v[62:65], v[150:153], v[142:145], v[62:65]
	v_mfma_f32_16x16x32_bf16 v[58:61], v[158:161], v[142:145], v[58:61]
	v_mfma_f32_16x16x32_bf16 v[54:57], v[150:153], v[200:203], v[54:57]
	v_mfma_f32_16x16x32_bf16 v[50:53], v[158:161], v[200:203], v[50:53]
	v_mfma_f32_16x16x32_bf16 v[46:49], v[150:153], v[224:227], v[46:49]
	v_mfma_f32_16x16x32_bf16 v[42:45], v[158:161], v[224:227], v[42:45]
	v_mfma_f32_16x16x32_bf16 v[38:41], v[150:153], v[232:235], v[38:41]
	v_mfma_f32_16x16x32_bf16 v[34:37], v[158:161], v[232:235], v[34:37]
	s_setprio 0
	s_setprio 1
	v_mfma_f32_16x16x32_bf16 v[30:33], v[166:169], v[138:141], v[30:33]
	v_mfma_f32_16x16x32_bf16 v[26:29], v[174:177], v[138:141], v[26:29]
	v_mfma_f32_16x16x32_bf16 v[22:25], v[166:169], v[196:199], v[22:25]
	v_mfma_f32_16x16x32_bf16 v[18:21], v[174:177], v[196:199], v[18:21]
	v_mfma_f32_16x16x32_bf16 v[14:17], v[166:169], v[220:223], v[14:17]
	v_mfma_f32_16x16x32_bf16 v[10:13], v[174:177], v[220:223], v[10:13]
	v_mfma_f32_16x16x32_bf16 v[6:9], v[166:169], v[228:231], v[6:9]
	v_mfma_f32_16x16x32_bf16 v[2:5], v[174:177], v[228:231], v[2:5]
	v_mfma_f32_16x16x32_bf16 v[30:33], v[170:173], v[142:145], v[30:33]
	v_mfma_f32_16x16x32_bf16 v[26:29], v[162:165], v[142:145], v[26:29]
	v_mfma_f32_16x16x32_bf16 v[22:25], v[170:173], v[200:203], v[22:25]
	v_mfma_f32_16x16x32_bf16 v[18:21], v[162:165], v[200:203], v[18:21]
	v_mfma_f32_16x16x32_bf16 v[14:17], v[170:173], v[224:227], v[14:17]
	v_mfma_f32_16x16x32_bf16 v[10:13], v[162:165], v[224:227], v[10:13]
	v_mfma_f32_16x16x32_bf16 v[6:9], v[170:173], v[232:235], v[6:9]
	v_mfma_f32_16x16x32_bf16 v[2:5], v[162:165], v[232:235], v[2:5]
	s_setprio 0
	s_setprio 1
	v_cndmask_b32_e64 v138, 0, 1, s[52:53]
	v_cmp_ne_u32_e64 s[40:41], 1, v138
	s_andn2_b64 vcc, exec, s[52:53]
	s_mov_b64 s[88:89], -1
	s_cbranch_vccnz .LBB0_500
	v_mfma_f32_16x16x32_bf16 v[138:141], v[166:169], v[180:183], v[82:85]
	s_mov_b64 s[88:89], 0
	v_mfma_f32_16x16x32_bf16 v[142:145], v[174:177], v[180:183], v[94:97]
	v_mfma_f32_16x16x32_bf16 v[138:141], v[170:173], v[184:187], v[138:141]
	v_mfma_f32_16x16x32_bf16 v[142:145], v[162:165], v[184:187], v[142:145]

; #define PG8_STAGE(bufoff, gbase, voff) do { _Pragma("unroll") for (int _i = 0; _i < 2; ++_i) \
;         __builtin_amdgcn_global_load_lds((const unsigned*)((const char*)(gbase) + (size_t)_i * qstep + (voff)[0]), (PG8_LAS unsigned*)(lds + (bufoff) + ldsw + _i * 8192), 16, 0, 0); } while (0)
; #define PG8_LDA(dst, b, h) do { _Pragma("unroll") for (int m = 0; m < 4; ++m) _Pragma("unroll") for (int k = 0; k < 2; ++k) dst[m][k] = *(const PG8_LAS bf16x8*)(lds + PG8_SA(b, h) + aoff + m * 2048 + k * 1024); } while (0)
; #define PG8_LDB(dst, b, h) do { _Pragma("unroll") for (int n = 0; n < 2; ++n) _Pragma("unroll") for (int k = 0; k < 2; ++k) dst[n][k] = *(const PG8_LAS bf16x8*)(lds + PG8_SB(b, h) + boff + n * 2048 + k * 1024); } while (0)
; #define PG8_MMA(ai, bj, At, Bt) do { __builtin_amdgcn_s_setprio(1); _Pragma("unroll") for (int m = 0; m < 4; ++m) _Pragma("unroll") for (int n = 0; n < 2; ++n) _Pragma("unroll") for (int k = 0; k < 2; ++k) \
;         acc[ai][bj][m][n] = __builtin_amdgcn_mfma_f32_16x16x32_bf16(Bt[n][k], At[m][k], acc[ai][bj][m][n], 0, 0, 0); __builtin_amdgcn_s_setprio(0); } while (0)
; #define PG8_WAIT_V89() do { if constexpr (SLIVER) PG8_WAIT_V(9); else PG8_WAIT_V(8); } while (0)
; #define PG8_STAGE_S(b, gbase) do { if constexpr (SLIVER) __builtin_amdgcn_global_load_lds((const unsigned*)((const char*)(gbase) + voffS), (PG8_LAS unsigned*)(lds + STAGE_BYTES + (b) * 2048 + wid * 256), 4, 0, 0); } while (0)
; #define PG8_WAIT_L(n) asm volatile("s_waitcnt lgkmcnt(" #n ")" ::: "memory")
; #define PG8_BAR __builtin_amdgcn_s_barrier()
; #define PG8_SCHED __builtin_amdgcn_sched_barrier(0)
; template <class Epi, class Sched, bool ALIGN_EPI = false, bool SP2 = false, bool SLIVER = false>
; __device__ __forceinline__ void gemm_phase(PG8_LAS unsigned char* lds, const Gemm g, const Sched& S, const Epi& E) {
;     ...
;             PG8_LDB(B0, 1, 0); PG8_LDB(B1, 1, 1); PG8_SCHED; PG8_LDA(At, 1, 0); PG8_STAGE(PG8_SA(0, 1), a2 + hstep, voffA); PG8_STAGE_S(0, s2);
;             PG8_WAIT_V89(); PG8_WAIT_L(0); PG8_BAR; PG8_MMA(0, 0, At, B0); PG8_MMA(0, 1, At, B1); PG8_BAR; PG8_SCHED;
.LBB0_502:
	s_add_u32 s68, s62, s80
	s_addc_u32 s69, s63, s81
	s_add_u32 s76, s68, 0x100
	s_addc_u32 s77, s69, 0
	s_and_b64 s[68:69], s[86:87], exec
	s_cselect_b32 s69, s85, s77
	s_cselect_b32 s68, s84, s76
	s_setprio 0
	s_barrier
	s_add_i32 s76, 0, 0x18000
	v_add_u32_e32 v82, s76, v239
	s_add_i32 s77, 0, 0x1c000
	ds_read_b128 v[146:149], v82
	ds_read_b128 v[150:153], v82 offset:1024
	ds_read_b128 v[154:157], v82 offset:2048
	ds_read_b128 v[158:161], v82 offset:3072
	v_add_u32_e32 v82, s77, v239
	ds_read_b128 v[166:169], v82
	ds_read_b128 v[170:173], v82 offset:1024
	ds_read_b128 v[174:177], v82 offset:2048
	ds_read_b128 v[162:165], v82 offset:3072
	s_mov_b32 m0, s91
	v_lshl_add_u64 v[208:209], v[194:195], 0, s[24:25]
	ds_read_b128 v[82:85], v242 offset:32768
	ds_read_b128 v[94:97], v242 offset:33792
	ds_read_b128 v[180:183], v242 offset:34816
	ds_read_b128 v[184:187], v242 offset:35840
	ds_read_b128 v[196:199], v242 offset:36864
	ds_read_b128 v[200:203], v242 offset:37888
	ds_read_b128 v[220:223], v242 offset:38912
	ds_read_b128 v[224:227], v242 offset:39936
	global_load_lds_dwordx4 v[208:209], off
	v_lshl_add_u64 v[208:209], v[194:195], 0, s[14:15]
	s_mov_b32 m0, s92
	s_nop 0
	global_load_lds_dwordx4 v[208:209], off
	v_lshl_add_u64 v[208:209], s[68:69], 0, v[214:215]
	s_mov_b32 m0, s93
	s_nop 0
	global_load_lds_dword v[208:209], off
	s_waitcnt vmcnt(9)
	s_waitcnt lgkmcnt(0)
	s_setprio 1
	s_barrier
	v_mfma_f32_16x16x32_bf16 v[134:137], v[146:149], v[82:85], v[134:137]
	v_mfma_f32_16x16x32_bf16 v[130:133], v[154:157], v[82:85], v[130:133]
	v_mfma_f32_16x16x32_bf16 v[126:129], v[146:149], v[180:183], v[126:129]
	v_mfma_f32_16x16x32_bf16 v[122:125], v[154:157], v[180:183], v[122:125]
	v_mfma_f32_16x16x32_bf16 v[118:121], v[146:149], v[196:199], v[118:121]
	v_mfma_f32_16x16x32_bf16 v[114:117], v[154:157], v[196:199], v[114:117]
	v_mfma_f32_16x16x32_bf16 v[110:113], v[146:149], v[220:223], v[110:113]
	v_mfma_f32_16x16x32_bf16 v[106:109], v[154:157], v[220:223], v[106:109]
	v_mfma_f32_16x16x32_bf16 v[134:137], v[150:153], v[94:97], v[134:137]
	v_mfma_f32_16x16x32_bf16 v[130:133], v[158:161], v[94:97], v[130:133]
	v_mfma_f32_16x16x32_bf16 v[126:129], v[150:153], v[184:187], v[126:129]
	v_mfma_f32_16x16x32_bf16 v[122:125], v[158:161], v[184:187], v[122:125]
	v_mfma_f32_16x16x32_bf16 v[118:121], v[150:153], v[200:203], v[118:121]
	v_mfma_f32_16x16x32_bf16 v[114:117], v[158:161], v[200:203], v[114:117]
	v_mfma_f32_16x16x32_bf16 v[110:113], v[150:153], v[224:227], v[110:113]
	v_mfma_f32_16x16x32_bf16 v[106:109], v[158:161], v[224:227], v[106:109]
	s_setprio 0
	s_setprio 1
	v_mfma_f32_16x16x32_bf16 v[102:105], v[166:169], v[82:85], v[102:105]
	v_mfma_f32_16x16x32_bf16 v[82:85], v[174:177], v[82:85], v[98:101]
	v_mfma_f32_16x16x32_bf16 v[98:101], v[162:165], v[94:97], v[82:85]
	v_mfma_f32_16x16x32_bf16 v[82:85], v[166:169], v[180:183], v[90:93]
	v_mfma_f32_16x16x32_bf16 v[90:93], v[170:173], v[184:187], v[82:85]
	v_mfma_f32_16x16x32_bf16 v[82:85], v[174:177], v[180:183], v[86:89]
	v_mfma_f32_16x16x32_bf16 v[78:81], v[166:169], v[196:199], v[78:81]
	v_mfma_f32_16x16x32_bf16 v[74:77], v[174:177], v[196:199], v[74:77]
	v_mfma_f32_16x16x32_bf16 v[70:73], v[166:169], v[220:223], v[70:73]
	v_mfma_f32_16x16x32_bf16 v[66:69], v[174:177], v[220:223], v[66:69]
	v_mfma_f32_16x16x32_bf16 v[102:105], v[170:173], v[94:97], v[102:105]
	v_mfma_f32_16x16x32_bf16 v[86:89], v[162:165], v[184:187], v[82:85]
	v_mfma_f32_16x16x32_bf16 v[78:81], v[170:173], v[200:203], v[78:81]
	v_mfma_f32_16x16x32_bf16 v[74:77], v[162:165], v[200:203], v[74:77]
	v_mfma_f32_16x16x32_bf16 v[70:73], v[170:173], v[224:227], v[70:73]
	v_mfma_f32_16x16x32_bf16 v[66:69], v[162:165], v[224:227], v[66:69]
	s_setprio 0
	s_barrier
; #define PG8_SB(B) __builtin_amdgcn_rcpf(1.f + expneg(B))
; #define PG8_SB(B) __builtin_amdgcn_rcpf(1.f + expneg(B))
; #define PG8_STAGE(bufoff, gbase, voff) do { _Pragma("unroll") for (int _i = 0; _i < 2; ++_i) \
;         __builtin_amdgcn_global_load_lds((const unsigned*)((const char*)(gbase) + (size_t)_i * qstep + (voff)[0]), (PG8_LAS unsigned*)(lds + (bufoff) + ldsw + _i * 8192), 16, 0, 0); } while (0)
; #define PG8_LDA(dst, b, h) do { _Pragma("unroll") for (int m = 0; m < 4; ++m) _Pragma("unroll") for (int k = 0; k < 2; ++k) dst[m][k] = *(const PG8_LAS bf16x8*)(lds + PG8_SA(b, h) + aoff + m * 2048 + k * 1024); } while (0)
; #define PG8_MMA(ai, bj, At, Bt) do { __builtin_amdgcn_s_setprio(1); _Pragma("unroll") for (int m = 0; m < 4; ++m) _Pragma("unroll") for (int n = 0; n < 2; ++n) _Pragma("unroll") for (int k = 0; k < 2; ++k) \
;         acc[ai][bj][m][n] = __builtin_amdgcn_mfma_f32_16x16x32_bf16(Bt[n][k], At[m][k], acc[ai][bj][m][n], 0, 0, 0); __builtin_amdgcn_s_setprio(0); } while (0)
; #define PG8_WAIT_V89() do { if constexpr (SLIVER) PG8_WAIT_V(9); else PG8_WAIT_V(8); } while (0)
; #define PG8_LDS_S(b) do { if constexpr (SLIVER) { Sf[0] = *(const PG8_LAS bf16x8*)(lds + STAGE_BYTES + (b) * 2048 + soff0); Sf[1] = *(const PG8_LAS bf16x8*)(lds + STAGE_BYTES + (b) * 2048 + (soff0 ^ 64)); } } while (0)
; #define PG8_WAIT_L(n) asm volatile("s_waitcnt lgkmcnt(" #n ")" ::: "memory")
; #define PG8_BAR __builtin_amdgcn_s_barrier()
; #define PG8_SCHED __builtin_amdgcn_sched_barrier(0)
; template <class Epi, class Sched, bool ALIGN_EPI = false, bool SP2 = false, bool SLIVER = false>
; __device__ __forceinline__ void gemm_phase(PG8_LAS unsigned char* lds, const Gemm g, const Sched& S, const Epi& E) {
;     ...
;             PG8_LDA(At, 1, 1); PG8_LDS_S(1); PG8_STAGE(PG8_SB(1, 0), b3, voffB); PG8_STAGE(PG8_SB(1, 1), b3 + hstep, voffB); PG8_STAGE(PG8_SA(1, 0), a3, voffA);
;             PG8_WAIT_V89(); PG8_WAIT_L(0); PG8_BAR; PG8_MMA(1, 0, At, B0); PG8_MMA(1, 1, At, B1); PG8_MMA_S(); PG8_BAR; PG8_SCHED;
	s_add_i32 s68, 0, 0x20800
	v_add_u32_e32 v178, s68, v240
	v_add_u32_e32 v184, s68, v241
	s_add_i32 s68, s76, s95
	v_lshl_add_u64 v[208:209], v[192:193], 0, s[26:27]
	s_mov_b32 m0, s68
	ds_read_b128 v[82:85], v242 offset:49152
	ds_read_b128 v[94:97], v242 offset:50176
	ds_read_b128 v[196:199], v242 offset:51200
	ds_read_b128 v[200:203], v242 offset:52224
	ds_read_b128 v[220:223], v242 offset:53248
	ds_read_b128 v[224:227], v242 offset:54272
	ds_read_b128 v[228:231], v242 offset:55296
	ds_read_b128 v[232:235], v242 offset:56320
	ds_read_b128 v[180:183], v178
	ds_read_b128 v[184:187], v184
	global_load_lds_dwordx4 v[208:209], off
	v_lshl_add_u64 v[208:209], v[192:193], 0, s[72:73]
	s_add_i32 m0, s68, 0x2000
	s_add_i32 s68, s77, s95
	global_load_lds_dwordx4 v[208:209], off
	v_lshl_add_u64 v[208:209], v[192:193], 0, s[34:35]
	s_mov_b32 m0, s68
	s_mov_b64 s[76:77], 0x120080
	global_load_lds_dwordx4 v[208:209], off
	v_lshl_add_u64 v[192:193], v[192:193], 0, s[76:77]
	s_add_i32 m0, s68, 0x2000
	s_nop 0
	global_load_lds_dwordx4 v[192:193], off
	v_lshl_add_u64 v[192:193], v[194:195], 0, s[26:27]
	s_mov_b32 m0, s97
	s_nop 0
	global_load_lds_dwordx4 v[192:193], off
	v_lshl_add_u64 v[192:193], v[194:195], 0, s[72:73]
	s_mov_b32 m0, s18
	s_nop 0
	global_load_lds_dwordx4 v[192:193], off
	s_waitcnt vmcnt(9)
	s_waitcnt lgkmcnt(0)
	s_setprio 1
	s_barrier
	v_mfma_f32_16x16x32_bf16 v[62:65], v[146:149], v[82:85], v[62:65]
	v_mfma_f32_16x16x32_bf16 v[58:61], v[154:157], v[82:85], v[58:61]
	v_mfma_f32_16x16x32_bf16 v[54:57], v[146:149], v[196:199], v[54:57]
	v_mfma_f32_16x16x32_bf16 v[50:53], v[154:157], v[196:199], v[50:53]
	v_mfma_f32_16x16x32_bf16 v[46:49], v[146:149], v[220:223], v[46:49]
	v_mfma_f32_16x16x32_bf16 v[42:45], v[154:157], v[220:223], v[42:45]
	v_mfma_f32_16x16x32_bf16 v[38:41], v[146:149], v[228:231], v[38:41]
	v_mfma_f32_16x16x32_bf16 v[34:37], v[154:157], v[228:231], v[34:37]
	v_mfma_f32_16x16x32_bf16 v[62:65], v[150:153], v[94:97], v[62:65]
	v_mfma_f32_16x16x32_bf16 v[58:61], v[158:161], v[94:97], v[58:61]
	v_mfma_f32_16x16x32_bf16 v[54:57], v[150:153], v[200:203], v[54:57]
	v_mfma_f32_16x16x32_bf16 v[50:53], v[158:161], v[200:203], v[50:53]
	v_mfma_f32_16x16x32_bf16 v[46:49], v[150:153], v[224:227], v[46:49]
	v_mfma_f32_16x16x32_bf16 v[42:45], v[158:161], v[224:227], v[42:45]
	v_mfma_f32_16x16x32_bf16 v[38:41], v[150:153], v[232:235], v[38:41]
	v_mfma_f32_16x16x32_bf16 v[34:37], v[158:161], v[232:235], v[34:37]
	s_setprio 0
	s_setprio 1
	v_mfma_f32_16x16x32_bf16 v[30:33], v[166:169], v[82:85], v[30:33]
	v_mfma_f32_16x16x32_bf16 v[26:29], v[174:177], v[82:85], v[26:29]
	v_mfma_f32_16x16x32_bf16 v[22:25], v[166:169], v[196:199], v[22:25]
	v_mfma_f32_16x16x32_bf16 v[18:21], v[174:177], v[196:199], v[18:21]
	v_mfma_f32_16x16x32_bf16 v[14:17], v[166:169], v[220:223], v[14:17]
	v_mfma_f32_16x16x32_bf16 v[10:13], v[174:177], v[220:223], v[10:13]
	v_mfma_f32_16x16x32_bf16 v[6:9], v[166:169], v[228:231], v[6:9]
	v_mfma_f32_16x16x32_bf16 v[2:5], v[174:177], v[228:231], v[2:5]
	v_mfma_f32_16x16x32_bf16 v[30:33], v[170:173], v[94:97], v[30:33]
	v_mfma_f32_16x16x32_bf16 v[26:29], v[162:165], v[94:97], v[26:29]
	v_mfma_f32_16x16x32_bf16 v[22:25], v[170:173], v[200:203], v[22:25]
	v_mfma_f32_16x16x32_bf16 v[18:21], v[162:165], v[200:203], v[18:21]
	v_mfma_f32_16x16x32_bf16 v[14:17], v[170:173], v[224:227], v[14:17]
	v_mfma_f32_16x16x32_bf16 v[10:13], v[162:165], v[224:227], v[10:13]
	v_mfma_f32_16x16x32_bf16 v[6:9], v[170:173], v[232:235], v[6:9]
	v_mfma_f32_16x16x32_bf16 v[2:5], v[162:165], v[232:235], v[2:5]
	s_setprio 0
	s_setprio 1
	s_and_b64 vcc, exec, s[40:41]
	s_mov_b64 s[40:41], -1
	s_mov_b64 s[86:87], 0x4000400
	s_mov_b64 s[88:89], 0x4000800
	s_cbranch_vccnz .LBB0_504
	v_mfma_f32_16x16x32_bf16 v[82:85], v[166:169], v[180:183], v[138:141]
	s_mov_b64 s[40:41], 0
	v_mfma_f32_16x16x32_bf16 v[94:97], v[174:177], v[180:183], v[142:145]
	v_mfma_f32_16x16x32_bf16 v[82:85], v[170:173], v[184:187], v[82:85]
	v_mfma_f32_16x16x32_bf16 v[94:97], v[162:165], v[184:187], v[94:97]

; #define PG8_STAGE(bufoff, gbase, voff) do { _Pragma("unroll") for (int _i = 0; _i < 2; ++_i) \
;         __builtin_amdgcn_global_load_lds((const unsigned*)((const char*)(gbase) + (size_t)_i * qstep + (voff)[0]), (PG8_LAS unsigned*)(lds + (bufoff) + ldsw + _i * 8192), 16, 0, 0); } while (0)
; #define PG8_LDA(dst, b, h) do { _Pragma("unroll") for (int m = 0; m < 4; ++m) _Pragma("unroll") for (int k = 0; k < 2; ++k) dst[m][k] = *(const PG8_LAS bf16x8*)(lds + PG8_SA(b, h) + aoff + m * 2048 + k * 1024); } while (0)
; #define PG8_LDB(dst, b, h) do { _Pragma("unroll") for (int n = 0; n < 2; ++n) _Pragma("unroll") for (int k = 0; k < 2; ++k) dst[n][k] = *(const PG8_LAS bf16x8*)(lds + PG8_SB(b, h) + boff + n * 2048 + k * 1024); } while (0)
; #define PG8_MMA(ai, bj, At, Bt) do { __builtin_amdgcn_s_setprio(1); _Pragma("unroll") for (int m = 0; m < 4; ++m) _Pragma("unroll") for (int n = 0; n < 2; ++n) _Pragma("unroll") for (int k = 0; k < 2; ++k) \
;         acc[ai][bj][m][n] = __builtin_amdgcn_mfma_f32_16x16x32_bf16(Bt[n][k], At[m][k], acc[ai][bj][m][n], 0, 0, 0); __builtin_amdgcn_s_setprio(0); } while (0)
; #define PG8_WAIT_V89() do { if constexpr (SLIVER) PG8_WAIT_V(9); else PG8_WAIT_V(8); } while (0)
; #define PG8_STAGE_S(b, gbase) do { if constexpr (SLIVER) __builtin_amdgcn_global_load_lds((const unsigned*)((const char*)(gbase) + voffS), (PG8_LAS unsigned*)(lds + STAGE_BYTES + (b) * 2048 + wid * 256), 4, 0, 0); } while (0)
; #define PG8_WAIT_L(n) asm volatile("s_waitcnt lgkmcnt(" #n ")" ::: "memory")
; #define PG8_BAR __builtin_amdgcn_s_barrier()
; #define PG8_SCHED __builtin_amdgcn_sched_barrier(0)
; template <class Epi, class Sched, bool ALIGN_EPI = false, bool SP2 = false, bool SLIVER = false>
; __device__ __forceinline__ void gemm_phase(PG8_LAS unsigned char* lds, const Gemm g, const Sched& S, const Epi& E) {
;     ...
;             PG8_LDB(B0, 0, 0); PG8_LDB(B1, 0, 1); PG8_SCHED; PG8_LDA(At, 0, 0); PG8_STAGE(PG8_SA(1, 1), a1 + hstep, voffA); PG8_STAGE_S(1, s1);
;             PG8_WAIT_V89(); PG8_WAIT_L(0); PG8_BAR; PG8_MMA(0, 0, At, B0); PG8_MMA(0, 1, At, B1); PG8_BAR; PG8_SCHED;
.LBB0_598:
	s_add_u32 s40, s92, s62
	s_addc_u32 s41, s93, s63
	s_add_u32 s77, s40, 0x100
	s_addc_u32 s78, s41, 0
	s_add_u32 s83, s68, s62
	s_addc_u32 s79, s69, s63
	s_add_i32 s96, 0, 0x10000
	s_cmpk_eq_i32 s62, 0xf00
	s_cselect_b64 s[80:81], -1, 0
	s_and_b64 s[40:41], s[80:81], exec
	s_cselect_b32 s41, s12, s78
	s_cselect_b32 s40, s13, s77
	v_add_u32_e32 v138, s96, v212
	s_cselect_b32 s79, s17, s79
	s_cselect_b32 s78, s55, s83
	s_add_i32 s77, 0, 0x14000
	ds_read_b128 v[146:149], v138
	ds_read_b128 v[150:153], v138 offset:1024
	ds_read_b128 v[154:157], v138 offset:2048
	ds_read_b128 v[158:161], v138 offset:3072
	v_add_u32_e32 v138, s77, v212
	ds_read_b128 v[166:169], v138
	ds_read_b128 v[170:173], v138 offset:1024
	ds_read_b128 v[174:177], v138 offset:2048
	ds_read_b128 v[162:165], v138 offset:3072
	v_lshl_add_u64 v[202:203], v[200:201], 0, s[62:63]
	v_lshl_add_u64 v[208:209], v[202:203], 0, s[30:31]
	s_add_i32 m0, s85, 0xc000
	ds_read_b128 v[138:141], v215
	ds_read_b128 v[142:145], v215 offset:1024
	ds_read_b128 v[180:183], v215 offset:2048
	ds_read_b128 v[184:187], v215 offset:3072
	ds_read_b128 v[216:219], v215 offset:4096
	ds_read_b128 v[220:223], v215 offset:5120
	ds_read_b128 v[224:227], v215 offset:6144
	ds_read_b128 v[228:231], v215 offset:7168
	global_load_lds_dwordx4 v[208:209], off
	v_lshl_add_u64 v[202:203], v[202:203], 0, s[34:35]
	s_add_i32 m0, s85, 0xe000
	s_nop 0
	global_load_lds_dwordx4 v[202:203], off
	v_lshl_add_u64 v[202:203], v[198:199], 0, s[62:63]
	s_add_i32 m0, s45, 0x20800
	s_nop 0
	global_load_lds_dword v[202:203], off
	s_waitcnt vmcnt(9)
	s_waitcnt lgkmcnt(0)
	s_setprio 1
	s_barrier
	v_mfma_f32_16x16x32_bf16 v[134:137], v[146:149], v[138:141], v[134:137]
	v_mfma_f32_16x16x32_bf16 v[130:133], v[154:157], v[138:141], v[130:133]
	v_mfma_f32_16x16x32_bf16 v[118:121], v[146:149], v[180:183], v[118:121]
	v_mfma_f32_16x16x32_bf16 v[114:117], v[154:157], v[180:183], v[114:117]
	v_mfma_f32_16x16x32_bf16 v[102:105], v[146:149], v[216:219], v[102:105]
	v_mfma_f32_16x16x32_bf16 v[98:101], v[154:157], v[216:219], v[98:101]
	v_mfma_f32_16x16x32_bf16 v[86:89], v[146:149], v[224:227], v[86:89]
	v_mfma_f32_16x16x32_bf16 v[82:85], v[154:157], v[224:227], v[82:85]
	v_mfma_f32_16x16x32_bf16 v[134:137], v[150:153], v[142:145], v[134:137]
	v_mfma_f32_16x16x32_bf16 v[130:133], v[158:161], v[142:145], v[130:133]
	v_mfma_f32_16x16x32_bf16 v[118:121], v[150:153], v[184:187], v[118:121]
	v_mfma_f32_16x16x32_bf16 v[114:117], v[158:161], v[184:187], v[114:117]
	v_mfma_f32_16x16x32_bf16 v[102:105], v[150:153], v[220:223], v[102:105]
	v_mfma_f32_16x16x32_bf16 v[98:101], v[158:161], v[220:223], v[98:101]
	v_mfma_f32_16x16x32_bf16 v[86:89], v[150:153], v[228:231], v[86:89]
	v_mfma_f32_16x16x32_bf16 v[82:85], v[158:161], v[228:231], v[82:85]
	s_setprio 0
	s_setprio 1
	v_mfma_f32_16x16x32_bf16 v[126:129], v[166:169], v[138:141], v[126:129]
	v_mfma_f32_16x16x32_bf16 v[122:125], v[174:177], v[138:141], v[122:125]
	v_mfma_f32_16x16x32_bf16 v[110:113], v[166:169], v[180:183], v[110:113]
	v_mfma_f32_16x16x32_bf16 v[106:109], v[174:177], v[180:183], v[106:109]
	v_mfma_f32_16x16x32_bf16 v[94:97], v[166:169], v[216:219], v[94:97]
	v_mfma_f32_16x16x32_bf16 v[90:93], v[174:177], v[216:219], v[90:93]
	v_mfma_f32_16x16x32_bf16 v[78:81], v[166:169], v[224:227], v[78:81]
	v_mfma_f32_16x16x32_bf16 v[74:77], v[174:177], v[224:227], v[74:77]
	v_mfma_f32_16x16x32_bf16 v[126:129], v[170:173], v[142:145], v[126:129]
	v_mfma_f32_16x16x32_bf16 v[122:125], v[162:165], v[142:145], v[122:125]
	v_mfma_f32_16x16x32_bf16 v[110:113], v[170:173], v[184:187], v[110:113]
	v_mfma_f32_16x16x32_bf16 v[106:109], v[162:165], v[184:187], v[106:109]
	v_mfma_f32_16x16x32_bf16 v[94:97], v[170:173], v[220:223], v[94:97]
	v_mfma_f32_16x16x32_bf16 v[90:93], v[162:165], v[220:223], v[90:93]
	v_mfma_f32_16x16x32_bf16 v[78:81], v[170:173], v[228:231], v[78:81]
	v_mfma_f32_16x16x32_bf16 v[74:77], v[162:165], v[228:231], v[74:77]
	s_setprio 0
	s_barrier
; #define PG8_SB(B) __builtin_amdgcn_rcpf(1.f + expneg(B))
; #define PG8_SB(B) __builtin_amdgcn_rcpf(1.f + expneg(B))
; #define PG8_STAGE(bufoff, gbase, voff) do { _Pragma("unroll") for (int _i = 0; _i < 2; ++_i) \
;         __builtin_amdgcn_global_load_lds((const unsigned*)((const char*)(gbase) + (size_t)_i * qstep + (voff)[0]), (PG8_LAS unsigned*)(lds + (bufoff) + ldsw + _i * 8192), 16, 0, 0); } while (0)
; #define PG8_LDA(dst, b, h) do { _Pragma("unroll") for (int m = 0; m < 4; ++m) _Pragma("unroll") for (int k = 0; k < 2; ++k) dst[m][k] = *(const PG8_LAS bf16x8*)(lds + PG8_SA(b, h) + aoff + m * 2048 + k * 1024); } while (0)
; #define PG8_MMA(ai, bj, At, Bt) do { __builtin_amdgcn_s_setprio(1); _Pragma("unroll") for (int m = 0; m < 4; ++m) _Pragma("unroll") for (int n = 0; n < 2; ++n) _Pragma("unroll") for (int k = 0; k < 2; ++k) \
;         acc[ai][bj][m][n] = __builtin_amdgcn_mfma_f32_16x16x32_bf16(Bt[n][k], At[m][k], acc[ai][bj][m][n], 0, 0, 0); __builtin_amdgcn_s_setprio(0); } while (0)
; #define PG8_WAIT_V89() do { if constexpr (SLIVER) PG8_WAIT_V(9); else PG8_WAIT_V(8); } while (0)
; #define PG8_LDS_S(b) do { if constexpr (SLIVER) { Sf[0] = *(const PG8_LAS bf16x8*)(lds + STAGE_BYTES + (b) * 2048 + soff0); Sf[1] = *(const PG8_LAS bf16x8*)(lds + STAGE_BYTES + (b) * 2048 + (soff0 ^ 64)); } } while (0)
; #define PG8_WAIT_L(n) asm volatile("s_waitcnt lgkmcnt(" #n ")" ::: "memory")
; #define PG8_BAR __builtin_amdgcn_s_barrier()
; #define PG8_SCHED __builtin_amdgcn_sched_barrier(0)
; template <class Epi, class Sched, bool ALIGN_EPI = false, bool SP2 = false, bool SLIVER = false>
; __device__ __forceinline__ void gemm_phase(PG8_LAS unsigned char* lds, const Gemm g, const Sched& S, const Epi& E) {
;     ...
;             PG8_LDA(At, 0, 1); PG8_LDS_S(0); PG8_STAGE(PG8_SB(0, 0), b2, voffB); PG8_STAGE(PG8_SB(0, 1), b2 + hstep, voffB); PG8_STAGE(PG8_SA(0, 0), a2, voffA);
;             PG8_WAIT_V89(); PG8_WAIT_L(0); PG8_BAR; PG8_MMA(1, 0, At, B0); PG8_MMA(1, 1, At, B1); PG8_MMA_S(); PG8_BAR; PG8_SCHED;
	s_add_i32 s83, 0, 0x20000
	v_lshl_add_u64 v[202:203], s[78:79], 0, v[190:191]
	s_add_i32 s78, s96, s18
	v_add_u32_e32 v178, s83, v213
	v_add_u32_e32 v184, s83, v214
	s_mov_b32 m0, s78
	ds_read_b128 v[138:141], v215 offset:16384
	ds_read_b128 v[142:145], v215 offset:17408
	ds_read_b128 v[216:219], v215 offset:18432
	ds_read_b128 v[220:223], v215 offset:19456
	ds_read_b128 v[224:227], v215 offset:20480
	ds_read_b128 v[228:231], v215 offset:21504
	ds_read_b128 v[232:235], v215 offset:22528
	ds_read_b128 v[240:243], v215 offset:23552
	ds_read_b128 v[180:183], v178
	ds_read_b128 v[184:187], v184
	global_load_lds_dwordx4 v[202:203], off
	v_lshl_add_u64 v[208:209], v[202:203], 0, s[20:21]
	s_add_i32 m0, s78, 0x2000
	s_add_i32 s77, s77, s18
	global_load_lds_dwordx4 v[208:209], off
	v_lshl_add_u64 v[208:209], v[202:203], 0, s[22:23]
	s_mov_b32 m0, s77
	v_lshl_add_u64 v[210:211], s[40:41], 0, v[188:189]
	global_load_lds_dwordx4 v[208:209], off
	v_lshl_add_u64 v[208:209], v[202:203], 0, s[24:25]
	s_add_i32 m0, s77, 0x2000
	s_nop 0
	global_load_lds_dwordx4 v[208:209], off
	s_mov_b32 m0, s85
	v_lshl_add_u64 v[208:209], v[210:211], 0, s[20:21]
	global_load_lds_dwordx4 v[210:211], off
	s_mov_b32 m0, s19
	s_nop 0
	global_load_lds_dwordx4 v[208:209], off
	s_waitcnt vmcnt(9)
	s_waitcnt lgkmcnt(0)
	s_setprio 1
	s_barrier
	v_mfma_f32_16x16x32_bf16 v[70:73], v[146:149], v[138:141], v[70:73]
	v_mfma_f32_16x16x32_bf16 v[66:69], v[154:157], v[138:141], v[66:69]
	v_mfma_f32_16x16x32_bf16 v[54:57], v[146:149], v[216:219], v[54:57]
	v_mfma_f32_16x16x32_bf16 v[50:53], v[154:157], v[216:219], v[50:53]
	v_mfma_f32_16x16x32_bf16 v[38:41], v[146:149], v[224:227], v[38:41]
	v_mfma_f32_16x16x32_bf16 v[34:37], v[154:157], v[224:227], v[34:37]
	v_mfma_f32_16x16x32_bf16 v[22:25], v[146:149], v[232:235], v[22:25]
	v_mfma_f32_16x16x32_bf16 v[18:21], v[154:157], v[232:235], v[18:21]
	v_mfma_f32_16x16x32_bf16 v[70:73], v[150:153], v[142:145], v[70:73]
	v_mfma_f32_16x16x32_bf16 v[66:69], v[158:161], v[142:145], v[66:69]
	v_mfma_f32_16x16x32_bf16 v[54:57], v[150:153], v[220:223], v[54:57]
	v_mfma_f32_16x16x32_bf16 v[50:53], v[158:161], v[220:223], v[50:53]
	v_mfma_f32_16x16x32_bf16 v[38:41], v[150:153], v[228:231], v[38:41]
	v_mfma_f32_16x16x32_bf16 v[34:37], v[158:161], v[228:231], v[34:37]
	v_mfma_f32_16x16x32_bf16 v[22:25], v[150:153], v[240:243], v[22:25]
	v_mfma_f32_16x16x32_bf16 v[18:21], v[158:161], v[240:243], v[18:21]
	s_setprio 0
	s_setprio 1
	v_mfma_f32_16x16x32_bf16 v[62:65], v[166:169], v[138:141], v[62:65]
	v_mfma_f32_16x16x32_bf16 v[58:61], v[174:177], v[138:141], v[58:61]
	v_mfma_f32_16x16x32_bf16 v[46:49], v[166:169], v[216:219], v[46:49]
	v_mfma_f32_16x16x32_bf16 v[42:45], v[174:177], v[216:219], v[42:45]
	v_mfma_f32_16x16x32_bf16 v[30:33], v[166:169], v[224:227], v[30:33]
	v_mfma_f32_16x16x32_bf16 v[26:29], v[174:177], v[224:227], v[26:29]
	v_mfma_f32_16x16x32_bf16 v[14:17], v[166:169], v[232:235], v[14:17]
	v_mfma_f32_16x16x32_bf16 v[10:13], v[174:177], v[232:235], v[10:13]
	v_mfma_f32_16x16x32_bf16 v[62:65], v[170:173], v[142:145], v[62:65]
	v_mfma_f32_16x16x32_bf16 v[58:61], v[162:165], v[142:145], v[58:61]
	v_mfma_f32_16x16x32_bf16 v[46:49], v[170:173], v[220:223], v[46:49]
	v_mfma_f32_16x16x32_bf16 v[42:45], v[162:165], v[220:223], v[42:45]
	v_mfma_f32_16x16x32_bf16 v[30:33], v[170:173], v[228:231], v[30:33]
	v_mfma_f32_16x16x32_bf16 v[26:29], v[162:165], v[228:231], v[26:29]
	v_mfma_f32_16x16x32_bf16 v[14:17], v[170:173], v[240:243], v[14:17]
	v_mfma_f32_16x16x32_bf16 v[10:13], v[162:165], v[240:243], v[10:13]
	s_setprio 0
	s_setprio 1
	v_cndmask_b32_e64 v138, 0, 1, s[52:53]
	v_cmp_ne_u32_e64 s[40:41], 1, v138
	s_andn2_b64 vcc, exec, s[52:53]
	s_mov_b64 s[96:97], -1
	s_cbranch_vccnz .LBB0_600
	v_mfma_f32_16x16x32_bf16 v[138:141], v[166:169], v[180:183], v[6:9]
	s_mov_b64 s[96:97], 0
	v_mfma_f32_16x16x32_bf16 v[142:145], v[174:177], v[180:183], v[2:5]
	v_mfma_f32_16x16x32_bf16 v[138:141], v[170:173], v[184:187], v[138:141]
	v_mfma_f32_16x16x32_bf16 v[142:145], v[162:165], v[184:187], v[142:145]

; #define PG8_STAGE(bufoff, gbase, voff) do { _Pragma("unroll") for (int _i = 0; _i < 2; ++_i) \
;         __builtin_amdgcn_global_load_lds((const unsigned*)((const char*)(gbase) + (size_t)_i * qstep + (voff)[0]), (PG8_LAS unsigned*)(lds + (bufoff) + ldsw + _i * 8192), 16, 0, 0); } while (0)
; #define PG8_LDA(dst, b, h) do { _Pragma("unroll") for (int m = 0; m < 4; ++m) _Pragma("unroll") for (int k = 0; k < 2; ++k) dst[m][k] = *(const PG8_LAS bf16x8*)(lds + PG8_SA(b, h) + aoff + m * 2048 + k * 1024); } while (0)
; #define PG8_LDB(dst, b, h) do { _Pragma("unroll") for (int n = 0; n < 2; ++n) _Pragma("unroll") for (int k = 0; k < 2; ++k) dst[n][k] = *(const PG8_LAS bf16x8*)(lds + PG8_SB(b, h) + boff + n * 2048 + k * 1024); } while (0)
; #define PG8_MMA(ai, bj, At, Bt) do { __builtin_amdgcn_s_setprio(1); _Pragma("unroll") for (int m = 0; m < 4; ++m) _Pragma("unroll") for (int n = 0; n < 2; ++n) _Pragma("unroll") for (int k = 0; k < 2; ++k) \
;         acc[ai][bj][m][n] = __builtin_amdgcn_mfma_f32_16x16x32_bf16(Bt[n][k], At[m][k], acc[ai][bj][m][n], 0, 0, 0); __builtin_amdgcn_s_setprio(0); } while (0)
; #define PG8_WAIT_V89() do { if constexpr (SLIVER) PG8_WAIT_V(9); else PG8_WAIT_V(8); } while (0)
; #define PG8_STAGE_S(b, gbase) do { if constexpr (SLIVER) __builtin_amdgcn_global_load_lds((const unsigned*)((const char*)(gbase) + voffS), (PG8_LAS unsigned*)(lds + STAGE_BYTES + (b) * 2048 + wid * 256), 4, 0, 0); } while (0)
; #define PG8_WAIT_L(n) asm volatile("s_waitcnt lgkmcnt(" #n ")" ::: "memory")
; #define PG8_BAR __builtin_amdgcn_s_barrier()
; #define PG8_SCHED __builtin_amdgcn_sched_barrier(0)
; template <class Epi, class Sched, bool ALIGN_EPI = false, bool SP2 = false, bool SLIVER = false>
; __device__ __forceinline__ void gemm_phase(PG8_LAS unsigned char* lds, const Gemm g, const Sched& S, const Epi& E) {
;     ...
;             PG8_LDB(B0, 1, 0); PG8_LDB(B1, 1, 1); PG8_SCHED; PG8_LDA(At, 1, 0); PG8_STAGE(PG8_SA(0, 1), a2 + hstep, voffA); PG8_STAGE_S(0, s2);
;             PG8_WAIT_V89(); PG8_WAIT_L(0); PG8_BAR; PG8_MMA(0, 0, At, B0); PG8_MMA(0, 1, At, B1); PG8_BAR; PG8_SCHED;
.LBB0_602:
	s_add_u32 s77, s94, s62
	s_addc_u32 s78, s95, s63
	s_add_u32 s77, s77, 0x100
	s_addc_u32 s83, s78, 0
	s_and_b64 s[78:79], s[80:81], exec
	s_cselect_b32 s79, s66, s83
	s_cselect_b32 s78, s67, s77
	s_setprio 0
	s_barrier
	s_add_i32 s77, 0, 0x18000
	v_add_u32_e32 v2, s77, v212
	s_add_i32 s80, 0, 0x1c000
	ds_read_b128 v[146:149], v2
	ds_read_b128 v[150:153], v2 offset:1024
	ds_read_b128 v[154:157], v2 offset:2048
	ds_read_b128 v[158:161], v2 offset:3072
	v_add_u32_e32 v2, s80, v212
	ds_read_b128 v[166:169], v2
	ds_read_b128 v[170:173], v2 offset:1024
	ds_read_b128 v[174:177], v2 offset:2048
	ds_read_b128 v[162:165], v2 offset:3072
	s_mov_b32 m0, s49
	v_lshl_add_u64 v[208:209], v[210:211], 0, s[22:23]
	ds_read_b128 v[2:5], v215 offset:32768
	ds_read_b128 v[6:9], v215 offset:33792
	ds_read_b128 v[180:183], v215 offset:34816
	ds_read_b128 v[184:187], v215 offset:35840
	ds_read_b128 v[216:219], v215 offset:36864
	ds_read_b128 v[220:223], v215 offset:37888
	ds_read_b128 v[224:227], v215 offset:38912
	ds_read_b128 v[228:231], v215 offset:39936
	global_load_lds_dwordx4 v[208:209], off
	v_lshl_add_u64 v[208:209], v[210:211], 0, s[24:25]
	s_mov_b32 m0, s50
	s_nop 0
	global_load_lds_dwordx4 v[208:209], off
	v_lshl_add_u64 v[208:209], s[78:79], 0, v[192:193]
	s_mov_b32 m0, s51
	s_nop 0
	global_load_lds_dword v[208:209], off
	s_waitcnt vmcnt(9)
	s_waitcnt lgkmcnt(0)
	s_setprio 1
	s_barrier
	v_mfma_f32_16x16x32_bf16 v[134:137], v[146:149], v[2:5], v[134:137]
	v_mfma_f32_16x16x32_bf16 v[130:133], v[154:157], v[2:5], v[130:133]
	v_mfma_f32_16x16x32_bf16 v[118:121], v[146:149], v[180:183], v[118:121]
	v_mfma_f32_16x16x32_bf16 v[114:117], v[154:157], v[180:183], v[114:117]
	v_mfma_f32_16x16x32_bf16 v[102:105], v[146:149], v[216:219], v[102:105]
	v_mfma_f32_16x16x32_bf16 v[98:101], v[154:157], v[216:219], v[98:101]
	v_mfma_f32_16x16x32_bf16 v[86:89], v[146:149], v[224:227], v[86:89]
	v_mfma_f32_16x16x32_bf16 v[82:85], v[154:157], v[224:227], v[82:85]
	v_mfma_f32_16x16x32_bf16 v[134:137], v[150:153], v[6:9], v[134:137]
	v_mfma_f32_16x16x32_bf16 v[130:133], v[158:161], v[6:9], v[130:133]
	v_mfma_f32_16x16x32_bf16 v[118:121], v[150:153], v[184:187], v[118:121]
	v_mfma_f32_16x16x32_bf16 v[114:117], v[158:161], v[184:187], v[114:117]
	v_mfma_f32_16x16x32_bf16 v[102:105], v[150:153], v[220:223], v[102:105]
	v_mfma_f32_16x16x32_bf16 v[98:101], v[158:161], v[220:223], v[98:101]
	v_mfma_f32_16x16x32_bf16 v[86:89], v[150:153], v[228:231], v[86:89]
	v_mfma_f32_16x16x32_bf16 v[82:85], v[158:161], v[228:231], v[82:85]
	s_setprio 0
	s_setprio 1
	v_mfma_f32_16x16x32_bf16 v[126:129], v[166:169], v[2:5], v[126:129]
	v_mfma_f32_16x16x32_bf16 v[2:5], v[174:177], v[2:5], v[122:125]
	v_mfma_f32_16x16x32_bf16 v[122:125], v[162:165], v[6:9], v[2:5]
	v_mfma_f32_16x16x32_bf16 v[2:5], v[166:169], v[180:183], v[110:113]
	v_mfma_f32_16x16x32_bf16 v[110:113], v[170:173], v[184:187], v[2:5]
	v_mfma_f32_16x16x32_bf16 v[2:5], v[174:177], v[180:183], v[106:109]
	v_mfma_f32_16x16x32_bf16 v[106:109], v[162:165], v[184:187], v[2:5]
	v_mfma_f32_16x16x32_bf16 v[2:5], v[166:169], v[216:219], v[94:97]
	v_mfma_f32_16x16x32_bf16 v[94:97], v[170:173], v[220:223], v[2:5]
	v_mfma_f32_16x16x32_bf16 v[2:5], v[174:177], v[216:219], v[90:93]
	v_mfma_f32_16x16x32_bf16 v[90:93], v[162:165], v[220:223], v[2:5]
	v_mfma_f32_16x16x32_bf16 v[2:5], v[166:169], v[224:227], v[78:81]
	v_mfma_f32_16x16x32_bf16 v[78:81], v[170:173], v[228:231], v[2:5]
	v_mfma_f32_16x16x32_bf16 v[2:5], v[174:177], v[224:227], v[74:77]
	v_mfma_f32_16x16x32_bf16 v[126:129], v[170:173], v[6:9], v[126:129]
	v_mfma_f32_16x16x32_bf16 v[74:77], v[162:165], v[228:231], v[2:5]
	s_setprio 0
	s_barrier
; #define PG8_SB(B) __builtin_amdgcn_rcpf(1.f + expneg(B))
; #define PG8_SB(B) __builtin_amdgcn_rcpf(1.f + expneg(B))
; #define PG8_STAGE(bufoff, gbase, voff) do { _Pragma("unroll") for (int _i = 0; _i < 2; ++_i) \
;         __builtin_amdgcn_global_load_lds((const unsigned*)((const char*)(gbase) + (size_t)_i * qstep + (voff)[0]), (PG8_LAS unsigned*)(lds + (bufoff) + ldsw + _i * 8192), 16, 0, 0); } while (0)
; #define PG8_LDA(dst, b, h) do { _Pragma("unroll") for (int m = 0; m < 4; ++m) _Pragma("unroll") for (int k = 0; k < 2; ++k) dst[m][k] = *(const PG8_LAS bf16x8*)(lds + PG8_SA(b, h) + aoff + m * 2048 + k * 1024); } while (0)
; #define PG8_MMA(ai, bj, At, Bt) do { __builtin_amdgcn_s_setprio(1); _Pragma("unroll") for (int m = 0; m < 4; ++m) _Pragma("unroll") for (int n = 0; n < 2; ++n) _Pragma("unroll") for (int k = 0; k < 2; ++k) \
;         acc[ai][bj][m][n] = __builtin_amdgcn_mfma_f32_16x16x32_bf16(Bt[n][k], At[m][k], acc[ai][bj][m][n], 0, 0, 0); __builtin_amdgcn_s_setprio(0); } while (0)
; #define PG8_WAIT_V89() do { if constexpr (SLIVER) PG8_WAIT_V(9); else PG8_WAIT_V(8); } while (0)
; #define PG8_LDS_S(b) do { if constexpr (SLIVER) { Sf[0] = *(const PG8_LAS bf16x8*)(lds + STAGE_BYTES + (b) * 2048 + soff0); Sf[1] = *(const PG8_LAS bf16x8*)(lds + STAGE_BYTES + (b) * 2048 + (soff0 ^ 64)); } } while (0)
; #define PG8_WAIT_L(n) asm volatile("s_waitcnt lgkmcnt(" #n ")" ::: "memory")
; #define PG8_BAR __builtin_amdgcn_s_barrier()
; #define PG8_SCHED __builtin_amdgcn_sched_barrier(0)
; template <class Epi, class Sched, bool ALIGN_EPI = false, bool SP2 = false, bool SLIVER = false>
; __device__ __forceinline__ void gemm_phase(PG8_LAS unsigned char* lds, const Gemm g, const Sched& S, const Epi& E) {
;     ...
;             PG8_LDA(At, 1, 1); PG8_LDS_S(1); PG8_STAGE(PG8_SB(1, 0), b3, voffB); PG8_STAGE(PG8_SB(1, 1), b3 + hstep, voffB); PG8_STAGE(PG8_SA(1, 0), a3, voffA);
;             PG8_WAIT_V89(); PG8_WAIT_L(0); PG8_BAR; PG8_MMA(1, 0, At, B0); PG8_MMA(1, 1, At, B1); PG8_MMA_S(); PG8_BAR; PG8_SCHED;
	s_add_i32 s78, 0, 0x20800
	s_add_i32 s77, s77, s18
	v_add_u32_e32 v178, s78, v213
	v_add_u32_e32 v184, s78, v214
	v_lshl_add_u64 v[208:209], v[202:203], 0, s[26:27]
	s_mov_b32 m0, s77
	ds_read_b128 v[2:5], v215 offset:49152
	ds_read_b128 v[6:9], v215 offset:50176
	ds_read_b128 v[216:219], v215 offset:51200
	ds_read_b128 v[220:223], v215 offset:52224
	ds_read_b128 v[224:227], v215 offset:53248
	ds_read_b128 v[228:231], v215 offset:54272
	ds_read_b128 v[232:235], v215 offset:55296
	ds_read_b128 v[240:243], v215 offset:56320
	ds_read_b128 v[180:183], v178
	ds_read_b128 v[184:187], v184
	global_load_lds_dwordx4 v[208:209], off
	v_lshl_add_u64 v[208:209], v[202:203], 0, s[28:29]
	s_add_i32 m0, s77, 0x2000
	s_add_i32 s77, s80, s18
	global_load_lds_dwordx4 v[208:209], off
	v_lshl_add_u64 v[208:209], v[202:203], 0, s[30:31]
	s_mov_b32 m0, s77
	v_lshl_add_u64 v[202:203], v[202:203], 0, s[34:35]
	global_load_lds_dwordx4 v[208:209], off
	s_add_i32 m0, s77, 0x2000
	s_nop 0
	global_load_lds_dwordx4 v[202:203], off
	v_lshl_add_u64 v[202:203], v[210:211], 0, s[26:27]
	s_mov_b32 m0, s10
	s_nop 0
	global_load_lds_dwordx4 v[202:203], off
	v_lshl_add_u64 v[202:203], v[210:211], 0, s[28:29]
	s_mov_b32 m0, s2
	s_nop 0
	global_load_lds_dwordx4 v[202:203], off
	s_waitcnt vmcnt(9)
	s_waitcnt lgkmcnt(0)
	s_setprio 1
	s_barrier
	v_mfma_f32_16x16x32_bf16 v[70:73], v[146:149], v[2:5], v[70:73]
	v_mfma_f32_16x16x32_bf16 v[66:69], v[154:157], v[2:5], v[66:69]
	v_mfma_f32_16x16x32_bf16 v[54:57], v[146:149], v[216:219], v[54:57]
	v_mfma_f32_16x16x32_bf16 v[50:53], v[154:157], v[216:219], v[50:53]
	v_mfma_f32_16x16x32_bf16 v[38:41], v[146:149], v[224:227], v[38:41]
	v_mfma_f32_16x16x32_bf16 v[34:37], v[154:157], v[224:227], v[34:37]
	v_mfma_f32_16x16x32_bf16 v[22:25], v[146:149], v[232:235], v[22:25]
	v_mfma_f32_16x16x32_bf16 v[18:21], v[154:157], v[232:235], v[18:21]
	v_mfma_f32_16x16x32_bf16 v[70:73], v[150:153], v[6:9], v[70:73]
	v_mfma_f32_16x16x32_bf16 v[66:69], v[158:161], v[6:9], v[66:69]
	v_mfma_f32_16x16x32_bf16 v[54:57], v[150:153], v[220:223], v[54:57]
	v_mfma_f32_16x16x32_bf16 v[50:53], v[158:161], v[220:223], v[50:53]
	v_mfma_f32_16x16x32_bf16 v[38:41], v[150:153], v[228:231], v[38:41]
	v_mfma_f32_16x16x32_bf16 v[34:37], v[158:161], v[228:231], v[34:37]
	v_mfma_f32_16x16x32_bf16 v[22:25], v[150:153], v[240:243], v[22:25]
	v_mfma_f32_16x16x32_bf16 v[18:21], v[158:161], v[240:243], v[18:21]
	s_setprio 0
	s_setprio 1
	v_mfma_f32_16x16x32_bf16 v[62:65], v[166:169], v[2:5], v[62:65]
	v_mfma_f32_16x16x32_bf16 v[2:5], v[174:177], v[2:5], v[58:61]
	v_mfma_f32_16x16x32_bf16 v[58:61], v[162:165], v[6:9], v[2:5]
	v_mfma_f32_16x16x32_bf16 v[2:5], v[166:169], v[216:219], v[46:49]
	v_mfma_f32_16x16x32_bf16 v[46:49], v[170:173], v[220:223], v[2:5]
	v_mfma_f32_16x16x32_bf16 v[2:5], v[174:177], v[216:219], v[42:45]
	v_mfma_f32_16x16x32_bf16 v[42:45], v[162:165], v[220:223], v[2:5]
	v_mfma_f32_16x16x32_bf16 v[2:5], v[166:169], v[224:227], v[30:33]
	v_mfma_f32_16x16x32_bf16 v[30:33], v[170:173], v[228:231], v[2:5]
	v_mfma_f32_16x16x32_bf16 v[2:5], v[174:177], v[224:227], v[26:29]
	v_mfma_f32_16x16x32_bf16 v[26:29], v[162:165], v[228:231], v[2:5]
	v_mfma_f32_16x16x32_bf16 v[2:5], v[166:169], v[232:235], v[14:17]
	v_mfma_f32_16x16x32_bf16 v[14:17], v[170:173], v[240:243], v[2:5]
	v_mfma_f32_16x16x32_bf16 v[2:5], v[174:177], v[232:235], v[10:13]
	v_mfma_f32_16x16x32_bf16 v[62:65], v[170:173], v[6:9], v[62:65]
	v_mfma_f32_16x16x32_bf16 v[10:13], v[162:165], v[240:243], v[2:5]
	s_setprio 0
	s_setprio 1
	s_and_b64 vcc, exec, s[40:41]
	s_mov_b64 s[40:41], -1
	s_cbranch_vccnz .LBB0_604
	v_mfma_f32_16x16x32_bf16 v[2:5], v[166:169], v[180:183], v[138:141]
	s_mov_b64 s[40:41], 0
	v_mfma_f32_16x16x32_bf16 v[6:9], v[170:173], v[184:187], v[2:5]
	v_mfma_f32_16x16x32_bf16 v[2:5], v[174:177], v[180:183], v[142:145]
	v_mfma_f32_16x16x32_bf16 v[2:5], v[162:165], v[184:187], v[2:5]

; #define PG8_SB(B) __builtin_amdgcn_rcpf(1.f + expneg(B))
; #define PG8_SB(B) __builtin_amdgcn_rcpf(1.f + expneg(B))
; #define PG8_STAGE(bufoff, gbase, voff) do { _Pragma("unroll") for (int _i = 0; _i < 2; ++_i) \
;         __builtin_amdgcn_global_load_lds((const unsigned*)((const char*)(gbase) + (size_t)_i * qstep + (voff)[0]), (PG8_LAS unsigned*)(lds + (bufoff) + ldsw + _i * 8192), 16, 0, 0); } while (0)
; #define PG8_LDA(dst, b, h) do { _Pragma("unroll") for (int m = 0; m < 4; ++m) _Pragma("unroll") for (int k = 0; k < 2; ++k) dst[m][k] = *(const PG8_LAS bf16x8*)(lds + PG8_SA(b, h) + aoff + m * 2048 + k * 1024); } while (0)
; #define PG8_LDB(dst, b, h) do { _Pragma("unroll") for (int n = 0; n < 2; ++n) _Pragma("unroll") for (int k = 0; k < 2; ++k) dst[n][k] = *(const PG8_LAS bf16x8*)(lds + PG8_SB(b, h) + boff + n * 2048 + k * 1024); } while (0)
; #define PG8_MMA(ai, bj, At, Bt) do { __builtin_amdgcn_s_setprio(1); _Pragma("unroll") for (int m = 0; m < 4; ++m) _Pragma("unroll") for (int n = 0; n < 2; ++n) _Pragma("unroll") for (int k = 0; k < 2; ++k) \
;         acc[ai][bj][m][n] = __builtin_amdgcn_mfma_f32_16x16x32_bf16(Bt[n][k], At[m][k], acc[ai][bj][m][n], 0, 0, 0); __builtin_amdgcn_s_setprio(0); } while (0)
; #define PG8_WAIT_V89() do { if constexpr (SLIVER) PG8_WAIT_V(9); else PG8_WAIT_V(8); } while (0)
; #define PG8_STAGE_S(b, gbase) do { if constexpr (SLIVER) __builtin_amdgcn_global_load_lds((const unsigned*)((const char*)(gbase) + voffS), (PG8_LAS unsigned*)(lds + STAGE_BYTES + (b) * 2048 + wid * 256), 4, 0, 0); } while (0)
; #define PG8_BAR __builtin_amdgcn_s_barrier()
; template <class Epi, class Sched, bool ALIGN_EPI = false, bool SP2 = false, bool SLIVER = false>
; __device__ __forceinline__ void gemm_phase(PG8_LAS unsigned char* lds, const Gemm g, const Sched& S, const Epi& E) {
;     ...
;             PG8_LDB(B0, 0, 0); PG8_LDB(B1, 0, 1); PG8_SCHED; PG8_LDA(At, 0, 0); PG8_STAGE(PG8_SA(1, 1), a1 + hstep, voffA); PG8_STAGE_S(1, s1);
;             PG8_WAIT_V89(); PG8_WAIT_L(0); PG8_BAR; PG8_MMA(0, 0, At, B0); PG8_MMA(0, 1, At, B1); PG8_BAR; PG8_SCHED;
;             PG8_LDA(At, 0, 1); PG8_LDS_S(0); PG8_STAGE(PG8_SB(0, 0), b2, voffB); PG8_STAGE(PG8_SB(0, 1), b2 + hstep, voffB); PG8_STAGE(PG8_SA(0, 0), a2, voffA);
;             PG8_WAIT_V89(); PG8_WAIT_L(0); PG8_BAR; PG8_MMA(1, 0, At, B0); PG8_MMA(1, 1, At, B1); PG8_MMA_S(); PG8_BAR; PG8_SCHED;
.Lgup_skipw0:
	s_waitcnt lgkmcnt(0)
	s_setprio 1
	s_barrier
	v_mfma_f32_16x16x32_bf16 v[126:129], v[130:133], v[172:175], v[126:129]
	v_mfma_f32_16x16x32_bf16 v[118:121], v[148:151], v[172:175], v[118:121]
	v_mfma_f32_16x16x32_bf16 v[110:113], v[130:133], v[184:187], v[110:113]
	v_mfma_f32_16x16x32_bf16 v[102:105], v[148:151], v[184:187], v[102:105]
	v_mfma_f32_16x16x32_bf16 v[94:97], v[130:133], v[192:195], v[94:97]
	v_mfma_f32_16x16x32_bf16 v[86:89], v[148:151], v[192:195], v[86:89]
	v_mfma_f32_16x16x32_bf16 v[78:81], v[130:133], v[200:203], v[78:81]
	v_mfma_f32_16x16x32_bf16 v[70:73], v[148:151], v[200:203], v[70:73]
	v_mfma_f32_16x16x32_bf16 v[126:129], v[138:141], v[180:183], v[126:129]
	v_mfma_f32_16x16x32_bf16 v[118:121], v[152:155], v[180:183], v[118:121]
	v_mfma_f32_16x16x32_bf16 v[110:113], v[138:141], v[188:191], v[110:113]
	v_mfma_f32_16x16x32_bf16 v[102:105], v[152:155], v[188:191], v[102:105]
	v_mfma_f32_16x16x32_bf16 v[94:97], v[138:141], v[196:199], v[94:97]
	v_mfma_f32_16x16x32_bf16 v[86:89], v[152:155], v[196:199], v[86:89]
	v_mfma_f32_16x16x32_bf16 v[78:81], v[138:141], v[210:213], v[78:81]
	v_mfma_f32_16x16x32_bf16 v[70:73], v[152:155], v[210:213], v[70:73]
	s_setprio 0
	s_setprio 1
	v_mfma_f32_16x16x32_bf16 v[122:125], v[156:159], v[172:175], v[122:125]
	v_mfma_f32_16x16x32_bf16 v[114:117], v[164:167], v[172:175], v[114:117]
	v_mfma_f32_16x16x32_bf16 v[106:109], v[156:159], v[184:187], v[106:109]
	v_mfma_f32_16x16x32_bf16 v[98:101], v[164:167], v[184:187], v[98:101]
	v_mfma_f32_16x16x32_bf16 v[90:93], v[156:159], v[192:195], v[90:93]
	v_mfma_f32_16x16x32_bf16 v[82:85], v[164:167], v[192:195], v[82:85]
	v_mfma_f32_16x16x32_bf16 v[74:77], v[156:159], v[200:203], v[74:77]
	v_mfma_f32_16x16x32_bf16 v[66:69], v[164:167], v[200:203], v[66:69]
	v_mfma_f32_16x16x32_bf16 v[122:125], v[160:163], v[180:183], v[122:125]
	v_mfma_f32_16x16x32_bf16 v[114:117], v[168:171], v[180:183], v[114:117]
	v_mfma_f32_16x16x32_bf16 v[106:109], v[160:163], v[188:191], v[106:109]
	v_mfma_f32_16x16x32_bf16 v[98:101], v[168:171], v[188:191], v[98:101]
	v_mfma_f32_16x16x32_bf16 v[90:93], v[160:163], v[196:199], v[90:93]
	v_mfma_f32_16x16x32_bf16 v[82:85], v[168:171], v[196:199], v[82:85]
	v_mfma_f32_16x16x32_bf16 v[74:77], v[160:163], v[210:213], v[74:77]
	v_mfma_f32_16x16x32_bf16 v[66:69], v[168:171], v[210:213], v[66:69]
	s_setprio 0
	s_barrier
	v_lshl_add_u64 v[144:145], s[76:77], 0, v[178:179]
	s_add_i32 s76, s78, s88
	s_mov_b32 m0, s76
	ds_read_b128 v[172:175], v147 offset:16384
	ds_read_b128 v[180:183], v147 offset:17408
	ds_read_b128 v[184:187], v147 offset:18432
	ds_read_b128 v[188:191], v147 offset:19456
	ds_read_b128 v[192:195], v147 offset:20480
	ds_read_b128 v[196:199], v147 offset:21504
	ds_read_b128 v[200:203], v147 offset:22528
	ds_read_b128 v[210:213], v147 offset:23552
	global_load_lds_dwordx4 v[144:145], off
	v_lshl_add_u64 v[176:177], v[144:145], 0, s[20:21]
	s_add_i32 m0, s76, 0x2000
	s_add_i32 s76, s79, s88
	global_load_lds_dwordx4 v[176:177], off
	v_lshl_add_u64 v[176:177], v[144:145], 0, s[22:23]
	s_mov_b32 m0, s76
	s_nop 0
	global_load_lds_dwordx4 v[176:177], off
	v_lshl_add_u64 v[176:177], v[144:145], 0, s[24:25]
	s_add_i32 m0, s76, 0x2000
	s_nop 0
	global_load_lds_dwordx4 v[176:177], off
	v_lshl_add_u64 v[176:177], s[80:81], 0, v[134:135]
	s_mov_b32 m0, s45
	v_lshl_add_u64 v[208:209], v[176:177], 0, s[20:21]
	global_load_lds_dwordx4 v[176:177], off
	s_mov_b32 m0, s83
	s_nop 0
	global_load_lds_dwordx4 v[208:209], off
	s_cmp_eq_u32 s69, s101
	s_cbranch_scc1 .Lgup_skipw1
	s_waitcnt vmcnt(8)
.Lgup_skipw1:
	s_waitcnt lgkmcnt(0)
	s_setprio 1
	s_barrier
	v_mfma_f32_16x16x32_bf16 v[62:65], v[130:133], v[172:175], v[62:65]
	v_mfma_f32_16x16x32_bf16 v[54:57], v[148:151], v[172:175], v[54:57]
	v_mfma_f32_16x16x32_bf16 v[46:49], v[130:133], v[184:187], v[46:49]
	v_mfma_f32_16x16x32_bf16 v[38:41], v[148:151], v[184:187], v[38:41]
	v_mfma_f32_16x16x32_bf16 v[30:33], v[130:133], v[192:195], v[30:33]
	v_mfma_f32_16x16x32_bf16 v[22:25], v[148:151], v[192:195], v[22:25]
	v_mfma_f32_16x16x32_bf16 v[14:17], v[130:133], v[200:203], v[14:17]
	v_mfma_f32_16x16x32_bf16 v[6:9], v[148:151], v[200:203], v[6:9]
	v_mfma_f32_16x16x32_bf16 v[62:65], v[138:141], v[180:183], v[62:65]
	v_mfma_f32_16x16x32_bf16 v[54:57], v[152:155], v[180:183], v[54:57]
	v_mfma_f32_16x16x32_bf16 v[46:49], v[138:141], v[188:191], v[46:49]
	v_mfma_f32_16x16x32_bf16 v[38:41], v[152:155], v[188:191], v[38:41]
	v_mfma_f32_16x16x32_bf16 v[30:33], v[138:141], v[196:199], v[30:33]
	v_mfma_f32_16x16x32_bf16 v[22:25], v[152:155], v[196:199], v[22:25]
	v_mfma_f32_16x16x32_bf16 v[14:17], v[138:141], v[210:213], v[14:17]
	v_mfma_f32_16x16x32_bf16 v[6:9], v[152:155], v[210:213], v[6:9]
	s_setprio 0
	s_setprio 1
	v_mfma_f32_16x16x32_bf16 v[58:61], v[156:159], v[172:175], v[58:61]
	v_mfma_f32_16x16x32_bf16 v[50:53], v[164:167], v[172:175], v[50:53]
	v_mfma_f32_16x16x32_bf16 v[42:45], v[156:159], v[184:187], v[42:45]
	v_mfma_f32_16x16x32_bf16 v[34:37], v[164:167], v[184:187], v[34:37]
	v_mfma_f32_16x16x32_bf16 v[26:29], v[156:159], v[192:195], v[26:29]
	v_mfma_f32_16x16x32_bf16 v[18:21], v[164:167], v[192:195], v[18:21]
	v_mfma_f32_16x16x32_bf16 v[10:13], v[156:159], v[200:203], v[10:13]
	v_mfma_f32_16x16x32_bf16 v[2:5], v[164:167], v[200:203], v[2:5]
	v_mfma_f32_16x16x32_bf16 v[58:61], v[160:163], v[180:183], v[58:61]
	v_mfma_f32_16x16x32_bf16 v[50:53], v[168:171], v[180:183], v[50:53]
	v_mfma_f32_16x16x32_bf16 v[42:45], v[160:163], v[188:191], v[42:45]
	v_mfma_f32_16x16x32_bf16 v[34:37], v[168:171], v[188:191], v[34:37]
	v_mfma_f32_16x16x32_bf16 v[26:29], v[160:163], v[196:199], v[26:29]
	v_mfma_f32_16x16x32_bf16 v[18:21], v[168:171], v[196:199], v[18:21]
	v_mfma_f32_16x16x32_bf16 v[10:13], v[160:163], v[210:213], v[10:13]
	v_mfma_f32_16x16x32_bf16 v[2:5], v[168:171], v[210:213], v[2:5]
	s_setprio 0
	s_barrier
; #define PG8_STAGE(bufoff, gbase, voff) do { _Pragma("unroll") for (int _i = 0; _i < 2; ++_i) \
;         __builtin_amdgcn_global_load_lds((const unsigned*)((const char*)(gbase) + (size_t)_i * qstep + (voff)[0]), (PG8_LAS unsigned*)(lds + (bufoff) + ldsw + _i * 8192), 16, 0, 0); } while (0)
; #define PG8_LDA(dst, b, h) do { _Pragma("unroll") for (int m = 0; m < 4; ++m) _Pragma("unroll") for (int k = 0; k < 2; ++k) dst[m][k] = *(const PG8_LAS bf16x8*)(lds + PG8_SA(b, h) + aoff + m * 2048 + k * 1024); } while (0)
; #define PG8_LDB(dst, b, h) do { _Pragma("unroll") for (int n = 0; n < 2; ++n) _Pragma("unroll") for (int k = 0; k < 2; ++k) dst[n][k] = *(const PG8_LAS bf16x8*)(lds + PG8_SB(b, h) + boff + n * 2048 + k * 1024); } while (0)
; #define PG8_MMA(ai, bj, At, Bt) do { __builtin_amdgcn_s_setprio(1); _Pragma("unroll") for (int m = 0; m < 4; ++m) _Pragma("unroll") for (int n = 0; n < 2; ++n) _Pragma("unroll") for (int k = 0; k < 2; ++k) \
;         acc[ai][bj][m][n] = __builtin_amdgcn_mfma_f32_16x16x32_bf16(Bt[n][k], At[m][k], acc[ai][bj][m][n], 0, 0, 0); __builtin_amdgcn_s_setprio(0); } while (0)
; #define PG8_WAIT_V89() do { if constexpr (SLIVER) PG8_WAIT_V(9); else PG8_WAIT_V(8); } while (0)
; #define PG8_STAGE_S(b, gbase) do { if constexpr (SLIVER) __builtin_amdgcn_global_load_lds((const unsigned*)((const char*)(gbase) + voffS), (PG8_LAS unsigned*)(lds + STAGE_BYTES + (b) * 2048 + wid * 256), 4, 0, 0); } while (0)
; #define PG8_WAIT_L(n) asm volatile("s_waitcnt lgkmcnt(" #n ")" ::: "memory")
; #define PG8_BAR __builtin_amdgcn_s_barrier()
; #define PG8_SCHED __builtin_amdgcn_sched_barrier(0)
; template <class Epi, class Sched, bool ALIGN_EPI = false, bool SP2 = false, bool SLIVER = false>
; __device__ __forceinline__ void gemm_phase(PG8_LAS unsigned char* lds, const Gemm g, const Sched& S, const Epi& E) {
;     ...
;             PG8_LDB(B0, 1, 0); PG8_LDB(B1, 1, 1); PG8_SCHED; PG8_LDA(At, 1, 0); PG8_STAGE(PG8_SA(0, 1), a2 + hstep, voffA); PG8_STAGE_S(0, s2);
;             PG8_WAIT_V89(); PG8_WAIT_L(0); PG8_BAR; PG8_MMA(0, 0, At, B0); PG8_MMA(0, 1, At, B1); PG8_BAR; PG8_SCHED;
	s_add_i32 s76, 0, 0x18000
	v_add_u32_e32 v142, s76, v143
	s_add_i32 s77, 0, 0x1c000
	ds_read_b128 v[130:133], v142
	ds_read_b128 v[138:141], v142 offset:1024
	ds_read_b128 v[148:151], v142 offset:2048
	ds_read_b128 v[152:155], v142 offset:3072
	v_add_u32_e32 v142, s77, v143
	ds_read_b128 v[156:159], v142
	ds_read_b128 v[160:163], v142 offset:1024
	ds_read_b128 v[164:167], v142 offset:2048
	ds_read_b128 v[168:171], v142 offset:3072
	s_mov_b32 m0, s90
	v_lshl_add_u64 v[208:209], v[176:177], 0, s[22:23]
	ds_read_b128 v[172:175], v147 offset:32768
	ds_read_b128 v[180:183], v147 offset:33792
	ds_read_b128 v[184:187], v147 offset:34816
	ds_read_b128 v[188:191], v147 offset:35840
	ds_read_b128 v[192:195], v147 offset:36864
	ds_read_b128 v[196:199], v147 offset:37888
	ds_read_b128 v[200:203], v147 offset:38912
	ds_read_b128 v[210:213], v147 offset:39936
	global_load_lds_dwordx4 v[208:209], off
	v_lshl_add_u64 v[208:209], v[176:177], 0, s[24:25]
	s_mov_b32 m0, s91
	s_nop 0
	global_load_lds_dwordx4 v[208:209], off
	s_waitcnt vmcnt(8)
	s_waitcnt lgkmcnt(0)
	s_setprio 1
	s_barrier
	v_mfma_f32_16x16x32_bf16 v[126:129], v[130:133], v[172:175], v[126:129]
	v_mfma_f32_16x16x32_bf16 v[118:121], v[148:151], v[172:175], v[118:121]
	v_mfma_f32_16x16x32_bf16 v[110:113], v[130:133], v[184:187], v[110:113]
	v_mfma_f32_16x16x32_bf16 v[102:105], v[148:151], v[184:187], v[102:105]
	v_mfma_f32_16x16x32_bf16 v[94:97], v[130:133], v[192:195], v[94:97]
	v_mfma_f32_16x16x32_bf16 v[86:89], v[148:151], v[192:195], v[86:89]
	v_mfma_f32_16x16x32_bf16 v[78:81], v[130:133], v[200:203], v[78:81]
	v_mfma_f32_16x16x32_bf16 v[70:73], v[148:151], v[200:203], v[70:73]
	v_mfma_f32_16x16x32_bf16 v[126:129], v[138:141], v[180:183], v[126:129]
	v_mfma_f32_16x16x32_bf16 v[118:121], v[152:155], v[180:183], v[118:121]
	v_mfma_f32_16x16x32_bf16 v[110:113], v[138:141], v[188:191], v[110:113]
	v_mfma_f32_16x16x32_bf16 v[102:105], v[152:155], v[188:191], v[102:105]
	v_mfma_f32_16x16x32_bf16 v[94:97], v[138:141], v[196:199], v[94:97]
	v_mfma_f32_16x16x32_bf16 v[86:89], v[152:155], v[196:199], v[86:89]
	v_mfma_f32_16x16x32_bf16 v[78:81], v[138:141], v[210:213], v[78:81]
	v_mfma_f32_16x16x32_bf16 v[70:73], v[152:155], v[210:213], v[70:73]
	s_setprio 0
	s_setprio 1
	v_mfma_f32_16x16x32_bf16 v[122:125], v[156:159], v[172:175], v[122:125]
	v_mfma_f32_16x16x32_bf16 v[114:117], v[164:167], v[172:175], v[114:117]
	v_mfma_f32_16x16x32_bf16 v[106:109], v[156:159], v[184:187], v[106:109]
	v_mfma_f32_16x16x32_bf16 v[98:101], v[164:167], v[184:187], v[98:101]
	v_mfma_f32_16x16x32_bf16 v[90:93], v[156:159], v[192:195], v[90:93]
	v_mfma_f32_16x16x32_bf16 v[82:85], v[164:167], v[192:195], v[82:85]
	v_mfma_f32_16x16x32_bf16 v[74:77], v[156:159], v[200:203], v[74:77]
	v_mfma_f32_16x16x32_bf16 v[66:69], v[164:167], v[200:203], v[66:69]
	v_mfma_f32_16x16x32_bf16 v[122:125], v[160:163], v[180:183], v[122:125]
	v_mfma_f32_16x16x32_bf16 v[114:117], v[168:171], v[180:183], v[114:117]
	v_mfma_f32_16x16x32_bf16 v[106:109], v[160:163], v[188:191], v[106:109]
	v_mfma_f32_16x16x32_bf16 v[98:101], v[168:171], v[188:191], v[98:101]
	v_mfma_f32_16x16x32_bf16 v[90:93], v[160:163], v[196:199], v[90:93]
	v_mfma_f32_16x16x32_bf16 v[82:85], v[168:171], v[196:199], v[82:85]
	v_mfma_f32_16x16x32_bf16 v[74:77], v[160:163], v[210:213], v[74:77]
	v_mfma_f32_16x16x32_bf16 v[66:69], v[168:171], v[210:213], v[66:69]
	s_setprio 0
	s_barrier
; #define PG8_SB(B) __builtin_amdgcn_rcpf(1.f + expneg(B))
; #define PG8_SB(B) __builtin_amdgcn_rcpf(1.f + expneg(B))
; #define PG8_STAGE(bufoff, gbase, voff) do { _Pragma("unroll") for (int _i = 0; _i < 2; ++_i) \
;         __builtin_amdgcn_global_load_lds((const unsigned*)((const char*)(gbase) + (size_t)_i * qstep + (voff)[0]), (PG8_LAS unsigned*)(lds + (bufoff) + ldsw + _i * 8192), 16, 0, 0); } while (0)
; #define PG8_LDA(dst, b, h) do { _Pragma("unroll") for (int m = 0; m < 4; ++m) _Pragma("unroll") for (int k = 0; k < 2; ++k) dst[m][k] = *(const PG8_LAS bf16x8*)(lds + PG8_SA(b, h) + aoff + m * 2048 + k * 1024); } while (0)
; #define PG8_MMA(ai, bj, At, Bt) do { __builtin_amdgcn_s_setprio(1); _Pragma("unroll") for (int m = 0; m < 4; ++m) _Pragma("unroll") for (int n = 0; n < 2; ++n) _Pragma("unroll") for (int k = 0; k < 2; ++k) \
;         acc[ai][bj][m][n] = __builtin_amdgcn_mfma_f32_16x16x32_bf16(Bt[n][k], At[m][k], acc[ai][bj][m][n], 0, 0, 0); __builtin_amdgcn_s_setprio(0); } while (0)
; #define PG8_WAIT_V89() do { if constexpr (SLIVER) PG8_WAIT_V(9); else PG8_WAIT_V(8); } while (0)
; #define PG8_LDS_S(b) do { if constexpr (SLIVER) { Sf[0] = *(const PG8_LAS bf16x8*)(lds + STAGE_BYTES + (b) * 2048 + soff0); Sf[1] = *(const PG8_LAS bf16x8*)(lds + STAGE_BYTES + (b) * 2048 + (soff0 ^ 64)); } } while (0)
; #define PG8_WAIT_L(n) asm volatile("s_waitcnt lgkmcnt(" #n ")" ::: "memory")
; #define PG8_BAR __builtin_amdgcn_s_barrier()
; #define PG8_SCHED __builtin_amdgcn_sched_barrier(0)
; template <class Epi, class Sched, bool ALIGN_EPI = false, bool SP2 = false, bool SLIVER = false>
; __device__ __forceinline__ void gemm_phase(PG8_LAS unsigned char* lds, const Gemm g, const Sched& S, const Epi& E) {
;     ...
;         for (int t = 0; t < nt; t += 2) {
;     ...
;             PG8_LDA(At, 1, 1); PG8_LDS_S(1); PG8_STAGE(PG8_SB(1, 0), b3, voffB); PG8_STAGE(PG8_SB(1, 1), b3 + hstep, voffB); PG8_STAGE(PG8_SA(1, 0), a3, voffA);
;             PG8_WAIT_V89(); PG8_WAIT_L(0); PG8_BAR; PG8_MMA(1, 0, At, B0); PG8_MMA(1, 1, At, B1); PG8_MMA_S(); PG8_BAR; PG8_SCHED;
;     ...
;         if constexpr (ALIGN_EPI) { if (wr == 0) PG8_BAR; }
	s_add_i32 s76, s76, s88
	v_lshl_add_u64 v[208:209], v[144:145], 0, s[26:27]
	s_mov_b32 m0, s76
	ds_read_b128 v[172:175], v147 offset:49152
	ds_read_b128 v[180:183], v147 offset:50176
	ds_read_b128 v[184:187], v147 offset:51200
	ds_read_b128 v[188:191], v147 offset:52224
	ds_read_b128 v[192:195], v147 offset:53248
	ds_read_b128 v[196:199], v147 offset:54272
	ds_read_b128 v[200:203], v147 offset:55296
	ds_read_b128 v[210:213], v147 offset:56320
	global_load_lds_dwordx4 v[208:209], off
	v_lshl_add_u64 v[208:209], v[144:145], 0, s[28:29]
	s_add_i32 m0, s76, 0x2000
	s_add_i32 s76, s77, s88
	global_load_lds_dwordx4 v[208:209], off
	v_lshl_add_u64 v[208:209], v[144:145], 0, s[30:31]
	s_mov_b32 m0, s76
	v_lshl_add_u64 v[144:145], v[144:145], 0, s[34:35]
	global_load_lds_dwordx4 v[208:209], off
	s_add_i32 m0, s76, 0x2000
	s_nop 0
	global_load_lds_dwordx4 v[144:145], off
	v_lshl_add_u64 v[144:145], v[176:177], 0, s[26:27]
	s_mov_b32 m0, s93
	s_nop 0
	global_load_lds_dwordx4 v[144:145], off
	v_lshl_add_u64 v[144:145], v[176:177], 0, s[28:29]
	s_mov_b32 m0, s94
	s_nop 0
	global_load_lds_dwordx4 v[144:145], off
	s_waitcnt vmcnt(8)
	s_waitcnt lgkmcnt(0)
	s_setprio 1
	s_barrier
	v_mfma_f32_16x16x32_bf16 v[62:65], v[130:133], v[172:175], v[62:65]
	v_mfma_f32_16x16x32_bf16 v[54:57], v[148:151], v[172:175], v[54:57]
	v_mfma_f32_16x16x32_bf16 v[46:49], v[130:133], v[184:187], v[46:49]
	v_mfma_f32_16x16x32_bf16 v[38:41], v[148:151], v[184:187], v[38:41]
	v_mfma_f32_16x16x32_bf16 v[30:33], v[130:133], v[192:195], v[30:33]
	v_mfma_f32_16x16x32_bf16 v[22:25], v[148:151], v[192:195], v[22:25]
	v_mfma_f32_16x16x32_bf16 v[14:17], v[130:133], v[200:203], v[14:17]
	v_mfma_f32_16x16x32_bf16 v[6:9], v[148:151], v[200:203], v[6:9]
	v_mfma_f32_16x16x32_bf16 v[62:65], v[138:141], v[180:183], v[62:65]
	v_mfma_f32_16x16x32_bf16 v[54:57], v[152:155], v[180:183], v[54:57]
	v_mfma_f32_16x16x32_bf16 v[46:49], v[138:141], v[188:191], v[46:49]
	v_mfma_f32_16x16x32_bf16 v[38:41], v[152:155], v[188:191], v[38:41]
	v_mfma_f32_16x16x32_bf16 v[30:33], v[138:141], v[196:199], v[30:33]
	v_mfma_f32_16x16x32_bf16 v[22:25], v[152:155], v[196:199], v[22:25]
	v_mfma_f32_16x16x32_bf16 v[14:17], v[138:141], v[210:213], v[14:17]
	v_mfma_f32_16x16x32_bf16 v[6:9], v[152:155], v[210:213], v[6:9]
	s_setprio 0
	s_setprio 1
	v_mfma_f32_16x16x32_bf16 v[58:61], v[156:159], v[172:175], v[58:61]
	v_mfma_f32_16x16x32_bf16 v[50:53], v[164:167], v[172:175], v[50:53]
	v_mfma_f32_16x16x32_bf16 v[42:45], v[156:159], v[184:187], v[42:45]
	v_mfma_f32_16x16x32_bf16 v[34:37], v[164:167], v[184:187], v[34:37]
	v_mfma_f32_16x16x32_bf16 v[26:29], v[156:159], v[192:195], v[26:29]
	v_mfma_f32_16x16x32_bf16 v[18:21], v[164:167], v[192:195], v[18:21]
	v_mfma_f32_16x16x32_bf16 v[10:13], v[156:159], v[200:203], v[10:13]
	v_mfma_f32_16x16x32_bf16 v[2:5], v[164:167], v[200:203], v[2:5]
	v_mfma_f32_16x16x32_bf16 v[58:61], v[160:163], v[180:183], v[58:61]
	v_mfma_f32_16x16x32_bf16 v[50:53], v[168:171], v[180:183], v[50:53]
	v_mfma_f32_16x16x32_bf16 v[42:45], v[160:163], v[188:191], v[42:45]
	v_mfma_f32_16x16x32_bf16 v[34:37], v[168:171], v[188:191], v[34:37]
	v_mfma_f32_16x16x32_bf16 v[26:29], v[160:163], v[196:199], v[26:29]
	v_mfma_f32_16x16x32_bf16 v[18:21], v[168:171], v[196:199], v[18:21]
	v_mfma_f32_16x16x32_bf16 v[10:13], v[160:163], v[210:213], v[10:13]
	v_mfma_f32_16x16x32_bf16 v[2:5], v[168:171], v[210:213], v[2:5]
	s_setprio 0
	s_barrier
	s_add_i32 s69, s69, 2
	s_add_u32 s62, s62, 0x100
	s_addc_u32 s63, s63, 0
	s_add_u32 s67, s67, 0x100
	s_addc_u32 s68, s68, 0
	s_cmp_gt_u32 s69, 29
	s_cbranch_scc0 .LBB0_705
	s_and_b64 vcc, exec, s[42:43]
	s_cbranch_vccz .LBB0_708
	s_barrier

; #define PG8_STAGE(bufoff, gbase, voff) do { _Pragma("unroll") for (int _i = 0; _i < 2; ++_i) \
;         __builtin_amdgcn_global_load_lds((const unsigned*)((const char*)(gbase) + (size_t)_i * qstep + (voff)[0]), (PG8_LAS unsigned*)(lds + (bufoff) + ldsw + _i * 8192), 16, 0, 0); } while (0)
; #define PG8_LDA(dst, b, h) do { _Pragma("unroll") for (int m = 0; m < 4; ++m) _Pragma("unroll") for (int k = 0; k < 2; ++k) dst[m][k] = *(const PG8_LAS bf16x8*)(lds + PG8_SA(b, h) + aoff + m * 2048 + k * 1024); } while (0)
; #define PG8_LDB(dst, b, h) do { _Pragma("unroll") for (int n = 0; n < 2; ++n) _Pragma("unroll") for (int k = 0; k < 2; ++k) dst[n][k] = *(const PG8_LAS bf16x8*)(lds + PG8_SB(b, h) + boff + n * 2048 + k * 1024); } while (0)
; #define PG8_MMA(ai, bj, At, Bt) do { __builtin_amdgcn_s_setprio(1); _Pragma("unroll") for (int m = 0; m < 4; ++m) _Pragma("unroll") for (int n = 0; n < 2; ++n) _Pragma("unroll") for (int k = 0; k < 2; ++k) \
;         acc[ai][bj][m][n] = __builtin_amdgcn_mfma_f32_16x16x32_bf16(Bt[n][k], At[m][k], acc[ai][bj][m][n], 0, 0, 0); __builtin_amdgcn_s_setprio(0); } while (0)
; #define PG8_WAIT_V89() do { if constexpr (SLIVER) PG8_WAIT_V(9); else PG8_WAIT_V(8); } while (0)
; #define PG8_STAGE_S(b, gbase) do { if constexpr (SLIVER) __builtin_amdgcn_global_load_lds((const unsigned*)((const char*)(gbase) + voffS), (PG8_LAS unsigned*)(lds + STAGE_BYTES + (b) * 2048 + wid * 256), 4, 0, 0); } while (0)
; #define PG8_WAIT_L(n) asm volatile("s_waitcnt lgkmcnt(" #n ")" ::: "memory")
; #define PG8_BAR __builtin_amdgcn_s_barrier()
; #define PG8_SCHED __builtin_amdgcn_sched_barrier(0)
; template <class Epi, class Sched, bool ALIGN_EPI = false, bool SP2 = false, bool SLIVER = false>
; __device__ __forceinline__ void gemm_phase(PG8_LAS unsigned char* lds, const Gemm g, const Sched& S, const Epi& E) {
;     ...
;             PG8_LDB(B0, 0, 0); PG8_LDB(B1, 0, 1); PG8_SCHED; PG8_LDA(At, 0, 0); PG8_STAGE(PG8_SA(1, 1), a1 + hstep, voffA); PG8_STAGE_S(1, s1);
;             PG8_WAIT_V89(); PG8_WAIT_L(0); PG8_BAR; PG8_MMA(0, 0, At, B0); PG8_MMA(0, 1, At, B1); PG8_BAR; PG8_SCHED;
.LBB0_811:
	s_add_u32 s13, s90, s62
	s_addc_u32 s40, s91, s63
	s_add_u32 s13, s13, 0x100
	s_addc_u32 s66, s40, 0
	s_add_u32 s68, s2, s62
	s_addc_u32 s67, s3, s63
	s_add_i32 s69, 0, 0x10000
	s_cmpk_eq_i32 s62, 0x2b00
	s_cselect_b64 s[80:81], -1, 0
	s_and_b64 s[40:41], s[80:81], exec
	s_cselect_b32 s41, s85, s66
	s_cselect_b32 s40, s84, s13
	v_add_u32_e32 v66, s69, v220
	s_cselect_b32 s67, s87, s67
	s_cselect_b32 s66, s86, s68
	s_add_i32 s13, 0, 0x14000
	ds_read_b128 v[154:157], v66
	ds_read_b128 v[158:161], v66 offset:1024
	ds_read_b128 v[162:165], v66 offset:2048
	ds_read_b128 v[174:177], v66 offset:3072
	v_add_u32_e32 v66, s13, v220
	ds_read_b128 v[184:187], v66
	ds_read_b128 v[188:191], v66 offset:1024
	ds_read_b128 v[192:195], v66 offset:2048
	ds_read_b128 v[180:183], v66 offset:3072
	v_lshl_add_u64 v[146:147], v[214:215], 0, s[62:63]
	v_lshl_add_u64 v[148:149], v[146:147], 0, s[8:9]
	s_add_i32 m0, s19, 0xc000
	s_mov_b64 s[94:95], 0x210080
	ds_read_b128 v[66:69], v223
	ds_read_b128 v[70:73], v223 offset:1024
	ds_read_b128 v[74:77], v223 offset:2048
	ds_read_b128 v[78:81], v223 offset:3072
	ds_read_b128 v[216:219], v223 offset:4096
	ds_read_b128 v[224:227], v223 offset:5120
	ds_read_b128 v[228:231], v223 offset:6144
	ds_read_b128 v[232:235], v223 offset:7168
	global_load_lds_dwordx4 v[148:149], off
	v_lshl_add_u64 v[146:147], v[146:147], 0, s[94:95]
	s_add_i32 m0, s19, 0xe000
	s_nop 0
	global_load_lds_dwordx4 v[146:147], off
	v_lshl_add_u64 v[146:147], v[212:213], 0, s[62:63]
	s_add_i32 m0, s96, 0x20800
	s_nop 0
	global_load_lds_dword v[146:147], off
	s_waitcnt vmcnt(9)
	s_waitcnt lgkmcnt(0)
	s_setprio 1
	s_barrier
	v_mfma_f32_16x16x32_bf16 v[146:149], v[154:157], v[66:69], v[170:173]
	v_mfma_f32_16x16x32_bf16 v[150:153], v[162:165], v[66:69], v[166:169]
	v_mfma_f32_16x16x32_bf16 v[134:137], v[154:157], v[74:77], v[134:137]
	v_mfma_f32_16x16x32_bf16 v[130:133], v[162:165], v[74:77], v[130:133]
	v_mfma_f32_16x16x32_bf16 v[118:121], v[154:157], v[216:219], v[118:121]
	v_mfma_f32_16x16x32_bf16 v[114:117], v[162:165], v[216:219], v[114:117]
	v_mfma_f32_16x16x32_bf16 v[102:105], v[154:157], v[228:231], v[102:105]
	v_mfma_f32_16x16x32_bf16 v[98:101], v[162:165], v[228:231], v[98:101]
	v_mfma_f32_16x16x32_bf16 v[146:149], v[158:161], v[70:73], v[146:149]
	v_mfma_f32_16x16x32_bf16 v[150:153], v[174:177], v[70:73], v[150:153]
	v_mfma_f32_16x16x32_bf16 v[134:137], v[158:161], v[78:81], v[134:137]
	v_mfma_f32_16x16x32_bf16 v[130:133], v[174:177], v[78:81], v[130:133]
	v_mfma_f32_16x16x32_bf16 v[118:121], v[158:161], v[224:227], v[118:121]
	v_mfma_f32_16x16x32_bf16 v[114:117], v[174:177], v[224:227], v[114:117]
	v_mfma_f32_16x16x32_bf16 v[102:105], v[158:161], v[232:235], v[102:105]
	v_mfma_f32_16x16x32_bf16 v[98:101], v[174:177], v[232:235], v[98:101]
	s_setprio 0
	s_setprio 1
	v_mfma_f32_16x16x32_bf16 v[142:145], v[184:187], v[66:69], v[142:145]
	v_mfma_f32_16x16x32_bf16 v[66:69], v[192:195], v[66:69], v[138:141]
	v_mfma_f32_16x16x32_bf16 v[138:141], v[180:183], v[70:73], v[66:69]
	v_mfma_f32_16x16x32_bf16 v[66:69], v[184:187], v[74:77], v[126:129]
	v_mfma_f32_16x16x32_bf16 v[126:129], v[188:191], v[78:81], v[66:69]
	v_mfma_f32_16x16x32_bf16 v[66:69], v[192:195], v[74:77], v[122:125]
	v_mfma_f32_16x16x32_bf16 v[122:125], v[180:183], v[78:81], v[66:69]
	v_mfma_f32_16x16x32_bf16 v[66:69], v[184:187], v[216:219], v[110:113]
	v_mfma_f32_16x16x32_bf16 v[110:113], v[188:191], v[224:227], v[66:69]
	v_mfma_f32_16x16x32_bf16 v[66:69], v[192:195], v[216:219], v[106:109]
	v_mfma_f32_16x16x32_bf16 v[106:109], v[180:183], v[224:227], v[66:69]
	v_mfma_f32_16x16x32_bf16 v[66:69], v[184:187], v[228:231], v[94:97]
	v_mfma_f32_16x16x32_bf16 v[94:97], v[188:191], v[232:235], v[66:69]
	v_mfma_f32_16x16x32_bf16 v[66:69], v[192:195], v[228:231], v[90:93]
	v_mfma_f32_16x16x32_bf16 v[142:145], v[188:191], v[70:73], v[142:145]
	v_mfma_f32_16x16x32_bf16 v[90:93], v[180:183], v[232:235], v[66:69]
	s_setprio 0
	s_barrier
; #define PG8_SB(B) __builtin_amdgcn_rcpf(1.f + expneg(B))
; #define PG8_SB(B) __builtin_amdgcn_rcpf(1.f + expneg(B))
; #define PG8_STAGE(bufoff, gbase, voff) do { _Pragma("unroll") for (int _i = 0; _i < 2; ++_i) \
;         __builtin_amdgcn_global_load_lds((const unsigned*)((const char*)(gbase) + (size_t)_i * qstep + (voff)[0]), (PG8_LAS unsigned*)(lds + (bufoff) + ldsw + _i * 8192), 16, 0, 0); } while (0)
; #define PG8_LDA(dst, b, h) do { _Pragma("unroll") for (int m = 0; m < 4; ++m) _Pragma("unroll") for (int k = 0; k < 2; ++k) dst[m][k] = *(const PG8_LAS bf16x8*)(lds + PG8_SA(b, h) + aoff + m * 2048 + k * 1024); } while (0)
; #define PG8_MMA(ai, bj, At, Bt) do { __builtin_amdgcn_s_setprio(1); _Pragma("unroll") for (int m = 0; m < 4; ++m) _Pragma("unroll") for (int n = 0; n < 2; ++n) _Pragma("unroll") for (int k = 0; k < 2; ++k) \
;         acc[ai][bj][m][n] = __builtin_amdgcn_mfma_f32_16x16x32_bf16(Bt[n][k], At[m][k], acc[ai][bj][m][n], 0, 0, 0); __builtin_amdgcn_s_setprio(0); } while (0)
; #define PG8_WAIT_V89() do { if constexpr (SLIVER) PG8_WAIT_V(9); else PG8_WAIT_V(8); } while (0)
; #define PG8_LDS_S(b) do { if constexpr (SLIVER) { Sf[0] = *(const PG8_LAS bf16x8*)(lds + STAGE_BYTES + (b) * 2048 + soff0); Sf[1] = *(const PG8_LAS bf16x8*)(lds + STAGE_BYTES + (b) * 2048 + (soff0 ^ 64)); } } while (0)
; #define PG8_WAIT_L(n) asm volatile("s_waitcnt lgkmcnt(" #n ")" ::: "memory")
; #define PG8_BAR __builtin_amdgcn_s_barrier()
; #define PG8_SCHED __builtin_amdgcn_sched_barrier(0)
; template <class Epi, class Sched, bool ALIGN_EPI = false, bool SP2 = false, bool SLIVER = false>
; __device__ __forceinline__ void gemm_phase(PG8_LAS unsigned char* lds, const Gemm g, const Sched& S, const Epi& E) {
;     ...
;             PG8_LDA(At, 0, 1); PG8_LDS_S(0); PG8_STAGE(PG8_SB(0, 0), b2, voffB); PG8_STAGE(PG8_SB(0, 1), b2 + hstep, voffB); PG8_STAGE(PG8_SA(0, 0), a2, voffA);
;             PG8_WAIT_V89(); PG8_WAIT_L(0); PG8_BAR; PG8_MMA(1, 0, At, B0); PG8_MMA(1, 1, At, B1); PG8_MMA_S(); PG8_BAR; PG8_SCHED;
	s_add_i32 s68, 0, 0x20000
	v_lshl_add_u64 v[216:217], s[66:67], 0, v[198:199]
	s_add_i32 s66, s69, s18
	v_add_u32_e32 v74, s68, v221
	v_add_u32_e32 v75, s68, v222
	s_mov_b32 m0, s66
	ds_read_b128 v[66:69], v223 offset:16384
	ds_read_b128 v[70:73], v223 offset:17408
	ds_read_b128 v[224:227], v223 offset:18432
	ds_read_b128 v[228:231], v223 offset:19456
	ds_read_b128 v[232:235], v223 offset:20480
	ds_read_b128 v[240:243], v223 offset:21504
	ds_read_b128 v[244:247], v223 offset:22528
	ds_read_b128 v[248:251], v223 offset:23552
	ds_read_b128 v[166:169], v74
	ds_read_b128 v[170:173], v75
	global_load_lds_dwordx4 v[216:217], off
	v_lshl_add_u64 v[74:75], v[216:217], 0, s[64:65]
	s_add_i32 m0, s66, 0x2000
	s_add_i32 s13, s13, s18
	global_load_lds_dwordx4 v[74:75], off
	v_lshl_add_u64 v[74:75], v[216:217], 0, s[0:1]
	s_mov_b32 m0, s13
	v_lshl_add_u64 v[218:219], s[40:41], 0, v[196:197]
	global_load_lds_dwordx4 v[74:75], off
	v_lshl_add_u64 v[74:75], v[216:217], 0, s[74:75]
	s_add_i32 m0, s13, 0x2000
	s_nop 0
	global_load_lds_dwordx4 v[74:75], off
	s_mov_b32 m0, s19
	v_lshl_add_u64 v[74:75], v[218:219], 0, s[64:65]
	global_load_lds_dwordx4 v[218:219], off
	s_mov_b32 m0, s52
	s_nop 0
	global_load_lds_dwordx4 v[74:75], off
	s_waitcnt vmcnt(9)
	s_waitcnt lgkmcnt(0)
	s_setprio 1
	s_barrier
	v_mfma_f32_16x16x32_bf16 v[74:77], v[154:157], v[66:69], v[86:89]
	v_mfma_f32_16x16x32_bf16 v[78:81], v[162:165], v[66:69], v[82:85]
	v_mfma_f32_16x16x32_bf16 v[54:57], v[154:157], v[224:227], v[54:57]
	v_mfma_f32_16x16x32_bf16 v[50:53], v[162:165], v[224:227], v[50:53]
	v_mfma_f32_16x16x32_bf16 v[38:41], v[154:157], v[232:235], v[38:41]
	v_mfma_f32_16x16x32_bf16 v[34:37], v[162:165], v[232:235], v[34:37]
	v_mfma_f32_16x16x32_bf16 v[22:25], v[154:157], v[244:247], v[22:25]
	v_mfma_f32_16x16x32_bf16 v[18:21], v[162:165], v[244:247], v[18:21]
	v_mfma_f32_16x16x32_bf16 v[74:77], v[158:161], v[70:73], v[74:77]
	v_mfma_f32_16x16x32_bf16 v[78:81], v[174:177], v[70:73], v[78:81]
	v_mfma_f32_16x16x32_bf16 v[54:57], v[158:161], v[228:231], v[54:57]
	v_mfma_f32_16x16x32_bf16 v[50:53], v[174:177], v[228:231], v[50:53]
	v_mfma_f32_16x16x32_bf16 v[38:41], v[158:161], v[240:243], v[38:41]
	v_mfma_f32_16x16x32_bf16 v[34:37], v[174:177], v[240:243], v[34:37]
	v_mfma_f32_16x16x32_bf16 v[22:25], v[158:161], v[248:251], v[22:25]
	v_mfma_f32_16x16x32_bf16 v[18:21], v[174:177], v[248:251], v[18:21]
	s_setprio 0
	s_setprio 1
	v_mfma_f32_16x16x32_bf16 v[62:65], v[184:187], v[66:69], v[62:65]
	v_mfma_f32_16x16x32_bf16 v[58:61], v[192:195], v[66:69], v[58:61]
	v_mfma_f32_16x16x32_bf16 v[46:49], v[184:187], v[224:227], v[46:49]
	v_mfma_f32_16x16x32_bf16 v[42:45], v[192:195], v[224:227], v[42:45]
	v_mfma_f32_16x16x32_bf16 v[30:33], v[184:187], v[232:235], v[30:33]
	v_mfma_f32_16x16x32_bf16 v[26:29], v[192:195], v[232:235], v[26:29]
	v_mfma_f32_16x16x32_bf16 v[14:17], v[184:187], v[244:247], v[14:17]
	v_mfma_f32_16x16x32_bf16 v[10:13], v[192:195], v[244:247], v[10:13]
	v_mfma_f32_16x16x32_bf16 v[62:65], v[188:191], v[70:73], v[62:65]
	v_mfma_f32_16x16x32_bf16 v[58:61], v[180:183], v[70:73], v[58:61]
	v_mfma_f32_16x16x32_bf16 v[46:49], v[188:191], v[228:231], v[46:49]
	v_mfma_f32_16x16x32_bf16 v[42:45], v[180:183], v[228:231], v[42:45]
	v_mfma_f32_16x16x32_bf16 v[30:33], v[188:191], v[240:243], v[30:33]
	v_mfma_f32_16x16x32_bf16 v[26:29], v[180:183], v[240:243], v[26:29]
	v_mfma_f32_16x16x32_bf16 v[14:17], v[188:191], v[248:251], v[14:17]
	v_mfma_f32_16x16x32_bf16 v[10:13], v[180:183], v[248:251], v[10:13]
	s_setprio 0
	s_setprio 1
	v_cndmask_b32_e64 v66, 0, 1, s[82:83]
	v_cmp_ne_u32_e64 s[40:41], 1, v66
	s_andn2_b64 vcc, exec, s[82:83]
	s_mov_b64 s[94:95], -1
	s_cbranch_vccnz .LBB0_813
	v_mfma_f32_16x16x32_bf16 v[66:69], v[184:187], v[166:169], v[6:9]
	s_mov_b64 s[94:95], 0
	v_mfma_f32_16x16x32_bf16 v[70:73], v[192:195], v[166:169], v[2:5]
	v_mfma_f32_16x16x32_bf16 v[66:69], v[188:191], v[170:173], v[66:69]
	v_mfma_f32_16x16x32_bf16 v[70:73], v[180:183], v[170:173], v[70:73]

; #define PG8_STAGE(bufoff, gbase, voff) do { _Pragma("unroll") for (int _i = 0; _i < 2; ++_i) \
;         __builtin_amdgcn_global_load_lds((const unsigned*)((const char*)(gbase) + (size_t)_i * qstep + (voff)[0]), (PG8_LAS unsigned*)(lds + (bufoff) + ldsw + _i * 8192), 16, 0, 0); } while (0)
; #define PG8_LDA(dst, b, h) do { _Pragma("unroll") for (int m = 0; m < 4; ++m) _Pragma("unroll") for (int k = 0; k < 2; ++k) dst[m][k] = *(const PG8_LAS bf16x8*)(lds + PG8_SA(b, h) + aoff + m * 2048 + k * 1024); } while (0)
; #define PG8_LDB(dst, b, h) do { _Pragma("unroll") for (int n = 0; n < 2; ++n) _Pragma("unroll") for (int k = 0; k < 2; ++k) dst[n][k] = *(const PG8_LAS bf16x8*)(lds + PG8_SB(b, h) + boff + n * 2048 + k * 1024); } while (0)
; #define PG8_MMA(ai, bj, At, Bt) do { __builtin_amdgcn_s_setprio(1); _Pragma("unroll") for (int m = 0; m < 4; ++m) _Pragma("unroll") for (int n = 0; n < 2; ++n) _Pragma("unroll") for (int k = 0; k < 2; ++k) \
;         acc[ai][bj][m][n] = __builtin_amdgcn_mfma_f32_16x16x32_bf16(Bt[n][k], At[m][k], acc[ai][bj][m][n], 0, 0, 0); __builtin_amdgcn_s_setprio(0); } while (0)
; #define PG8_WAIT_V89() do { if constexpr (SLIVER) PG8_WAIT_V(9); else PG8_WAIT_V(8); } while (0)
; #define PG8_STAGE_S(b, gbase) do { if constexpr (SLIVER) __builtin_amdgcn_global_load_lds((const unsigned*)((const char*)(gbase) + voffS), (PG8_LAS unsigned*)(lds + STAGE_BYTES + (b) * 2048 + wid * 256), 4, 0, 0); } while (0)
; #define PG8_WAIT_L(n) asm volatile("s_waitcnt lgkmcnt(" #n ")" ::: "memory")
; #define PG8_BAR __builtin_amdgcn_s_barrier()
; #define PG8_SCHED __builtin_amdgcn_sched_barrier(0)
; template <class Epi, class Sched, bool ALIGN_EPI = false, bool SP2 = false, bool SLIVER = false>
; __device__ __forceinline__ void gemm_phase(PG8_LAS unsigned char* lds, const Gemm g, const Sched& S, const Epi& E) {
;     ...
;             PG8_LDB(B0, 1, 0); PG8_LDB(B1, 1, 1); PG8_SCHED; PG8_LDA(At, 1, 0); PG8_STAGE(PG8_SA(0, 1), a2 + hstep, voffA); PG8_STAGE_S(0, s2);
;             PG8_WAIT_V89(); PG8_WAIT_L(0); PG8_BAR; PG8_MMA(0, 0, At, B0); PG8_MMA(0, 1, At, B1); PG8_BAR; PG8_SCHED;
.LBB0_815:
	s_add_u32 s13, s92, s62
	s_addc_u32 s66, s93, s63
	s_add_u32 s13, s13, 0x100
	s_addc_u32 s68, s66, 0
	s_and_b64 s[66:67], s[80:81], exec
	s_cselect_b32 s67, s89, s68
	s_cselect_b32 s66, s88, s13
	s_setprio 0
	s_barrier
	s_add_i32 s13, 0, 0x18000
	v_add_u32_e32 v2, s13, v220
	s_add_i32 s68, 0, 0x1c000
	ds_read_b128 v[154:157], v2
	ds_read_b128 v[158:161], v2 offset:1024
	ds_read_b128 v[162:165], v2 offset:2048
	ds_read_b128 v[174:177], v2 offset:3072
	v_add_u32_e32 v2, s68, v220
	ds_read_b128 v[184:187], v2
	ds_read_b128 v[188:191], v2 offset:1024
	ds_read_b128 v[192:195], v2 offset:2048
	ds_read_b128 v[180:183], v2 offset:3072
	s_mov_b32 m0, s53
	v_lshl_add_u64 v[166:167], v[218:219], 0, s[0:1]
	ds_read_b128 v[2:5], v223 offset:32768
	ds_read_b128 v[6:9], v223 offset:33792
	ds_read_b128 v[82:85], v223 offset:34816
	ds_read_b128 v[86:89], v223 offset:35840
	ds_read_b128 v[224:227], v223 offset:36864
	ds_read_b128 v[228:231], v223 offset:37888
	ds_read_b128 v[232:235], v223 offset:38912
	ds_read_b128 v[240:243], v223 offset:39936
	global_load_lds_dwordx4 v[166:167], off
	v_lshl_add_u64 v[166:167], v[218:219], 0, s[74:75]
	s_mov_b32 m0, s54
	s_nop 0
	global_load_lds_dwordx4 v[166:167], off
	v_lshl_add_u64 v[166:167], s[66:67], 0, v[200:201]
	s_mov_b32 m0, s55
	s_nop 0
	global_load_lds_dword v[166:167], off
	s_waitcnt vmcnt(9)
	s_waitcnt lgkmcnt(0)
	s_setprio 1
	s_barrier
	v_mfma_f32_16x16x32_bf16 v[146:149], v[154:157], v[2:5], v[146:149]
	v_mfma_f32_16x16x32_bf16 v[170:173], v[158:161], v[6:9], v[146:149]
	v_mfma_f32_16x16x32_bf16 v[146:149], v[162:165], v[2:5], v[150:153]
	v_mfma_f32_16x16x32_bf16 v[134:137], v[154:157], v[82:85], v[134:137]
	v_mfma_f32_16x16x32_bf16 v[130:133], v[162:165], v[82:85], v[130:133]
	v_mfma_f32_16x16x32_bf16 v[118:121], v[154:157], v[224:227], v[118:121]
	v_mfma_f32_16x16x32_bf16 v[114:117], v[162:165], v[224:227], v[114:117]
	v_mfma_f32_16x16x32_bf16 v[102:105], v[154:157], v[232:235], v[102:105]
	v_mfma_f32_16x16x32_bf16 v[98:101], v[162:165], v[232:235], v[98:101]
	v_mfma_f32_16x16x32_bf16 v[166:169], v[174:177], v[6:9], v[146:149]
	v_mfma_f32_16x16x32_bf16 v[134:137], v[158:161], v[86:89], v[134:137]
	v_mfma_f32_16x16x32_bf16 v[130:133], v[174:177], v[86:89], v[130:133]
	v_mfma_f32_16x16x32_bf16 v[118:121], v[158:161], v[228:231], v[118:121]
	v_mfma_f32_16x16x32_bf16 v[114:117], v[174:177], v[228:231], v[114:117]
	v_mfma_f32_16x16x32_bf16 v[102:105], v[158:161], v[240:243], v[102:105]
	v_mfma_f32_16x16x32_bf16 v[98:101], v[174:177], v[240:243], v[98:101]
	s_setprio 0
	s_setprio 1
	v_mfma_f32_16x16x32_bf16 v[142:145], v[184:187], v[2:5], v[142:145]
	v_mfma_f32_16x16x32_bf16 v[2:5], v[192:195], v[2:5], v[138:141]
	v_mfma_f32_16x16x32_bf16 v[138:141], v[180:183], v[6:9], v[2:5]
	v_mfma_f32_16x16x32_bf16 v[2:5], v[184:187], v[82:85], v[126:129]
	v_mfma_f32_16x16x32_bf16 v[126:129], v[188:191], v[86:89], v[2:5]
	v_mfma_f32_16x16x32_bf16 v[2:5], v[192:195], v[82:85], v[122:125]
	v_mfma_f32_16x16x32_bf16 v[122:125], v[180:183], v[86:89], v[2:5]
	v_mfma_f32_16x16x32_bf16 v[2:5], v[184:187], v[224:227], v[110:113]
	v_mfma_f32_16x16x32_bf16 v[110:113], v[188:191], v[228:231], v[2:5]
	v_mfma_f32_16x16x32_bf16 v[2:5], v[192:195], v[224:227], v[106:109]
	v_mfma_f32_16x16x32_bf16 v[106:109], v[180:183], v[228:231], v[2:5]
	v_mfma_f32_16x16x32_bf16 v[2:5], v[184:187], v[232:235], v[94:97]
	v_mfma_f32_16x16x32_bf16 v[94:97], v[188:191], v[240:243], v[2:5]
	v_mfma_f32_16x16x32_bf16 v[2:5], v[192:195], v[232:235], v[90:93]
	v_mfma_f32_16x16x32_bf16 v[142:145], v[188:191], v[6:9], v[142:145]
	v_mfma_f32_16x16x32_bf16 v[90:93], v[180:183], v[240:243], v[2:5]
	s_setprio 0
	s_barrier
; #define PG8_SB(B) __builtin_amdgcn_rcpf(1.f + expneg(B))
; #define PG8_SB(B) __builtin_amdgcn_rcpf(1.f + expneg(B))
; #define PG8_STAGE(bufoff, gbase, voff) do { _Pragma("unroll") for (int _i = 0; _i < 2; ++_i) \
;         __builtin_amdgcn_global_load_lds((const unsigned*)((const char*)(gbase) + (size_t)_i * qstep + (voff)[0]), (PG8_LAS unsigned*)(lds + (bufoff) + ldsw + _i * 8192), 16, 0, 0); } while (0)
; #define PG8_LDA(dst, b, h) do { _Pragma("unroll") for (int m = 0; m < 4; ++m) _Pragma("unroll") for (int k = 0; k < 2; ++k) dst[m][k] = *(const PG8_LAS bf16x8*)(lds + PG8_SA(b, h) + aoff + m * 2048 + k * 1024); } while (0)
; #define PG8_MMA(ai, bj, At, Bt) do { __builtin_amdgcn_s_setprio(1); _Pragma("unroll") for (int m = 0; m < 4; ++m) _Pragma("unroll") for (int n = 0; n < 2; ++n) _Pragma("unroll") for (int k = 0; k < 2; ++k) \
;         acc[ai][bj][m][n] = __builtin_amdgcn_mfma_f32_16x16x32_bf16(Bt[n][k], At[m][k], acc[ai][bj][m][n], 0, 0, 0); __builtin_amdgcn_s_setprio(0); } while (0)
; #define PG8_WAIT_V89() do { if constexpr (SLIVER) PG8_WAIT_V(9); else PG8_WAIT_V(8); } while (0)
; #define PG8_LDS_S(b) do { if constexpr (SLIVER) { Sf[0] = *(const PG8_LAS bf16x8*)(lds + STAGE_BYTES + (b) * 2048 + soff0); Sf[1] = *(const PG8_LAS bf16x8*)(lds + STAGE_BYTES + (b) * 2048 + (soff0 ^ 64)); } } while (0)
; #define PG8_WAIT_L(n) asm volatile("s_waitcnt lgkmcnt(" #n ")" ::: "memory")
; #define PG8_BAR __builtin_amdgcn_s_barrier()
; #define PG8_SCHED __builtin_amdgcn_sched_barrier(0)
; template <class Epi, class Sched, bool ALIGN_EPI = false, bool SP2 = false, bool SLIVER = false>
; __device__ __forceinline__ void gemm_phase(PG8_LAS unsigned char* lds, const Gemm g, const Sched& S, const Epi& E) {
;     ...
;             PG8_LDA(At, 1, 1); PG8_LDS_S(1); PG8_STAGE(PG8_SB(1, 0), b3, voffB); PG8_STAGE(PG8_SB(1, 1), b3 + hstep, voffB); PG8_STAGE(PG8_SA(1, 0), a3, voffA);
;             PG8_WAIT_V89(); PG8_WAIT_L(0); PG8_BAR; PG8_MMA(1, 0, At, B0); PG8_MMA(1, 1, At, B1); PG8_MMA_S(); PG8_BAR; PG8_SCHED;
	s_add_i32 s66, 0, 0x20800
	v_add_u32_e32 v82, s66, v221
	v_add_u32_e32 v83, s66, v222
	s_add_i32 s13, s13, s18
	ds_read_b128 v[2:5], v223 offset:49152
	ds_read_b128 v[6:9], v223 offset:50176
	ds_read_b128 v[224:227], v223 offset:51200
	ds_read_b128 v[228:231], v223 offset:52224
	ds_read_b128 v[232:235], v223 offset:53248
	ds_read_b128 v[240:243], v223 offset:54272
	ds_read_b128 v[244:247], v223 offset:55296
	ds_read_b128 v[248:251], v223 offset:56320
	ds_read_b128 v[146:149], v82
	ds_read_b128 v[150:153], v83
	v_lshl_add_u64 v[82:83], v[216:217], 0, s[26:27]
	s_mov_b32 m0, s13
	s_mov_b64 s[66:67], 0x210080
	global_load_lds_dwordx4 v[82:83], off
	v_lshl_add_u64 v[82:83], v[216:217], 0, s[60:61]
	s_add_i32 m0, s13, 0x2000
	s_add_i32 s13, s68, s18
	global_load_lds_dwordx4 v[82:83], off
	v_lshl_add_u64 v[82:83], v[216:217], 0, s[8:9]
	s_mov_b32 m0, s13
	s_nop 0
	global_load_lds_dwordx4 v[82:83], off
	v_lshl_add_u64 v[82:83], v[216:217], 0, s[66:67]
	s_add_i32 m0, s13, 0x2000
	s_nop 0
	global_load_lds_dwordx4 v[82:83], off
	v_lshl_add_u64 v[82:83], v[218:219], 0, s[26:27]
	s_mov_b32 m0, s10
	s_nop 0
	global_load_lds_dwordx4 v[82:83], off
	v_lshl_add_u64 v[82:83], v[218:219], 0, s[60:61]
	s_mov_b32 m0, s48
	s_nop 0
	global_load_lds_dwordx4 v[82:83], off
	s_waitcnt vmcnt(9)
	s_waitcnt lgkmcnt(0)
	s_setprio 1
	s_barrier
	v_mfma_f32_16x16x32_bf16 v[74:77], v[154:157], v[2:5], v[74:77]
	v_mfma_f32_16x16x32_bf16 v[86:89], v[158:161], v[6:9], v[74:77]
	v_mfma_f32_16x16x32_bf16 v[74:77], v[162:165], v[2:5], v[78:81]
	v_mfma_f32_16x16x32_bf16 v[54:57], v[154:157], v[224:227], v[54:57]
	v_mfma_f32_16x16x32_bf16 v[50:53], v[162:165], v[224:227], v[50:53]
	v_mfma_f32_16x16x32_bf16 v[38:41], v[154:157], v[232:235], v[38:41]
	v_mfma_f32_16x16x32_bf16 v[34:37], v[162:165], v[232:235], v[34:37]
	v_mfma_f32_16x16x32_bf16 v[22:25], v[154:157], v[244:247], v[22:25]
	v_mfma_f32_16x16x32_bf16 v[18:21], v[162:165], v[244:247], v[18:21]
	v_mfma_f32_16x16x32_bf16 v[82:85], v[174:177], v[6:9], v[74:77]
	v_mfma_f32_16x16x32_bf16 v[54:57], v[158:161], v[228:231], v[54:57]
	v_mfma_f32_16x16x32_bf16 v[50:53], v[174:177], v[228:231], v[50:53]
	v_mfma_f32_16x16x32_bf16 v[38:41], v[158:161], v[240:243], v[38:41]
	v_mfma_f32_16x16x32_bf16 v[34:37], v[174:177], v[240:243], v[34:37]
	v_mfma_f32_16x16x32_bf16 v[22:25], v[158:161], v[248:251], v[22:25]
	v_mfma_f32_16x16x32_bf16 v[18:21], v[174:177], v[248:251], v[18:21]
	s_setprio 0
	s_setprio 1
	v_mfma_f32_16x16x32_bf16 v[62:65], v[184:187], v[2:5], v[62:65]
	v_mfma_f32_16x16x32_bf16 v[2:5], v[192:195], v[2:5], v[58:61]
	v_mfma_f32_16x16x32_bf16 v[58:61], v[180:183], v[6:9], v[2:5]
	v_mfma_f32_16x16x32_bf16 v[2:5], v[184:187], v[224:227], v[46:49]
	v_mfma_f32_16x16x32_bf16 v[46:49], v[188:191], v[228:231], v[2:5]
	v_mfma_f32_16x16x32_bf16 v[2:5], v[192:195], v[224:227], v[42:45]
	v_mfma_f32_16x16x32_bf16 v[42:45], v[180:183], v[228:231], v[2:5]
	v_mfma_f32_16x16x32_bf16 v[2:5], v[184:187], v[232:235], v[30:33]
	v_mfma_f32_16x16x32_bf16 v[30:33], v[188:191], v[240:243], v[2:5]
	v_mfma_f32_16x16x32_bf16 v[2:5], v[192:195], v[232:235], v[26:29]
	v_mfma_f32_16x16x32_bf16 v[26:29], v[180:183], v[240:243], v[2:5]
	v_mfma_f32_16x16x32_bf16 v[2:5], v[184:187], v[244:247], v[14:17]
	v_mfma_f32_16x16x32_bf16 v[14:17], v[188:191], v[248:251], v[2:5]
	v_mfma_f32_16x16x32_bf16 v[2:5], v[192:195], v[244:247], v[10:13]
	v_mfma_f32_16x16x32_bf16 v[62:65], v[188:191], v[6:9], v[62:65]
	v_mfma_f32_16x16x32_bf16 v[10:13], v[180:183], v[248:251], v[2:5]
	s_setprio 0
	s_setprio 1
	s_and_b64 vcc, exec, s[40:41]
	s_mov_b64 s[40:41], -1
	s_cbranch_vccnz .LBB0_817
	v_mfma_f32_16x16x32_bf16 v[2:5], v[184:187], v[146:149], v[66:69]
	s_mov_b64 s[40:41], 0
	v_mfma_f32_16x16x32_bf16 v[6:9], v[188:191], v[150:153], v[2:5]
	v_mfma_f32_16x16x32_bf16 v[2:5], v[192:195], v[146:149], v[70:73]
	v_mfma_f32_16x16x32_bf16 v[2:5], v[180:183], v[150:153], v[2:5]

; #define PG8_STAGE(bufoff, gbase, voff) do { _Pragma("unroll") for (int _i = 0; _i < 2; ++_i) \
;         __builtin_amdgcn_global_load_lds((const unsigned*)((const char*)(gbase) + (size_t)_i * qstep + (voff)[0]), (PG8_LAS unsigned*)(lds + (bufoff) + ldsw + _i * 8192), 16, 0, 0); } while (0)
; #define PG8_LDA(dst, b, h) do { _Pragma("unroll") for (int m = 0; m < 4; ++m) _Pragma("unroll") for (int k = 0; k < 2; ++k) dst[m][k] = *(const PG8_LAS bf16x8*)(lds + PG8_SA(b, h) + aoff + m * 2048 + k * 1024); } while (0)
; #define PG8_LDB(dst, b, h) do { _Pragma("unroll") for (int n = 0; n < 2; ++n) _Pragma("unroll") for (int k = 0; k < 2; ++k) dst[n][k] = *(const PG8_LAS bf16x8*)(lds + PG8_SB(b, h) + boff + n * 2048 + k * 1024); } while (0)
; #define PG8_MMA(ai, bj, At, Bt) do { __builtin_amdgcn_s_setprio(1); _Pragma("unroll") for (int m = 0; m < 4; ++m) _Pragma("unroll") for (int n = 0; n < 2; ++n) _Pragma("unroll") for (int k = 0; k < 2; ++k) \
;         acc[ai][bj][m][n] = __builtin_amdgcn_mfma_f32_16x16x32_bf16(Bt[n][k], At[m][k], acc[ai][bj][m][n], 0, 0, 0); __builtin_amdgcn_s_setprio(0); } while (0)
; #define PG8_WAIT_V89() do { if constexpr (SLIVER) PG8_WAIT_V(9); else PG8_WAIT_V(8); } while (0)
; #define PG8_STAGE_S(b, gbase) do { if constexpr (SLIVER) __builtin_amdgcn_global_load_lds((const unsigned*)((const char*)(gbase) + voffS), (PG8_LAS unsigned*)(lds + STAGE_BYTES + (b) * 2048 + wid * 256), 4, 0, 0); } while (0)
; #define PG8_WAIT_L(n) asm volatile("s_waitcnt lgkmcnt(" #n ")" ::: "memory")
; #define PG8_BAR __builtin_amdgcn_s_barrier()
; #define PG8_SCHED __builtin_amdgcn_sched_barrier(0)
; template <class Epi, class Sched, bool ALIGN_EPI = false, bool SP2 = false, bool SLIVER = false>
; __device__ __forceinline__ void gemm_phase(PG8_LAS unsigned char* lds, const Gemm g, const Sched& S, const Epi& E) {
;     ...
;             PG8_LDB(B0, 0, 0); PG8_LDB(B1, 0, 1); PG8_SCHED; PG8_LDA(At, 0, 0); PG8_STAGE(PG8_SA(1, 1), a1 + hstep, voffA); PG8_STAGE_S(1, s1);
;             PG8_WAIT_V89(); PG8_WAIT_L(0); PG8_BAR; PG8_MMA(0, 0, At, B0); PG8_MMA(0, 1, At, B1); PG8_BAR; PG8_SCHED;
.LBB0_934:
	s_cmp_eq_u32 s66, s62
	s_cselect_b64 s[80:81], -1, 0
	s_add_u32 s12, s42, s62
	s_addc_u32 s13, s43, s63
	s_add_u32 s40, s12, 0x100
	s_addc_u32 s41, s13, 0
	s_and_b64 s[12:13], s[80:81], exec
	s_cselect_b32 s41, s95, s41
	s_cselect_b32 s40, s94, s40
	s_add_u32 s68, s17, s62
	s_addc_u32 s69, s45, s63
	s_add_i32 s76, 0, 0x10000
	s_and_b64 s[12:13], s[80:81], exec
	v_add_u32_e32 v138, s76, v212
	s_cselect_b32 s13, s97, s69
	s_cselect_b32 s12, s96, s68
	s_add_i32 s68, 0, 0x14000
	ds_read_b128 v[146:149], v138
	ds_read_b128 v[150:153], v138 offset:1024
	ds_read_b128 v[154:157], v138 offset:2048
	ds_read_b128 v[158:161], v138 offset:3072
	v_add_u32_e32 v138, s68, v212
	ds_read_b128 v[166:169], v138
	ds_read_b128 v[170:173], v138 offset:1024
	ds_read_b128 v[174:177], v138 offset:2048
	ds_read_b128 v[162:165], v138 offset:3072
	v_lshl_add_u64 v[202:203], v[198:199], 0, s[62:63]
	s_mov_b64 vcc, 0x90080
	v_lshl_add_u64 v[208:209], v[202:203], 0, vcc
	s_add_i32 m0, s93, 0xc000
	s_mov_b64 vcc, 0xd8080
	ds_read_b128 v[138:141], v215
	ds_read_b128 v[142:145], v215 offset:1024
	ds_read_b128 v[180:183], v215 offset:2048
	ds_read_b128 v[184:187], v215 offset:3072
	ds_read_b128 v[216:219], v215 offset:4096
	ds_read_b128 v[220:223], v215 offset:5120
	ds_read_b128 v[224:227], v215 offset:6144
	ds_read_b128 v[228:231], v215 offset:7168
	global_load_lds_dwordx4 v[208:209], off
	v_lshl_add_u64 v[202:203], v[202:203], 0, vcc
	s_add_i32 m0, s93, 0xe000
	s_nop 0
	global_load_lds_dwordx4 v[202:203], off
	v_lshl_add_u64 v[202:203], v[200:201], 0, s[62:63]
	s_add_i32 m0, s50, 0x20800
	s_nop 0
	global_load_lds_dword v[202:203], off
	s_waitcnt vmcnt(9)
	s_waitcnt lgkmcnt(0)
	s_setprio 1
	s_barrier
	v_mfma_f32_16x16x32_bf16 v[134:137], v[146:149], v[138:141], v[134:137]
	v_mfma_f32_16x16x32_bf16 v[130:133], v[154:157], v[138:141], v[130:133]
	v_mfma_f32_16x16x32_bf16 v[126:129], v[146:149], v[180:183], v[126:129]
	v_mfma_f32_16x16x32_bf16 v[122:125], v[154:157], v[180:183], v[122:125]
	v_mfma_f32_16x16x32_bf16 v[114:117], v[146:149], v[216:219], v[114:117]
	v_mfma_f32_16x16x32_bf16 v[106:109], v[154:157], v[216:219], v[106:109]
	v_mfma_f32_16x16x32_bf16 v[98:101], v[146:149], v[224:227], v[98:101]
	v_mfma_f32_16x16x32_bf16 v[90:93], v[154:157], v[224:227], v[90:93]
	v_mfma_f32_16x16x32_bf16 v[134:137], v[150:153], v[142:145], v[134:137]
	v_mfma_f32_16x16x32_bf16 v[130:133], v[158:161], v[142:145], v[130:133]
	v_mfma_f32_16x16x32_bf16 v[126:129], v[150:153], v[184:187], v[126:129]
	v_mfma_f32_16x16x32_bf16 v[122:125], v[158:161], v[184:187], v[122:125]
	v_mfma_f32_16x16x32_bf16 v[114:117], v[150:153], v[220:223], v[114:117]
	v_mfma_f32_16x16x32_bf16 v[106:109], v[158:161], v[220:223], v[106:109]
	v_mfma_f32_16x16x32_bf16 v[98:101], v[150:153], v[228:231], v[98:101]
	v_mfma_f32_16x16x32_bf16 v[90:93], v[158:161], v[228:231], v[90:93]
	s_setprio 0
	s_setprio 1
	v_mfma_f32_16x16x32_bf16 v[118:121], v[166:169], v[138:141], v[118:121]
	v_mfma_f32_16x16x32_bf16 v[110:113], v[174:177], v[138:141], v[110:113]
	v_mfma_f32_16x16x32_bf16 v[102:105], v[166:169], v[180:183], v[102:105]
	v_mfma_f32_16x16x32_bf16 v[94:97], v[174:177], v[180:183], v[94:97]
	v_mfma_f32_16x16x32_bf16 v[86:89], v[166:169], v[216:219], v[86:89]
	v_mfma_f32_16x16x32_bf16 v[82:85], v[174:177], v[216:219], v[82:85]
	v_mfma_f32_16x16x32_bf16 v[78:81], v[166:169], v[224:227], v[78:81]
	v_mfma_f32_16x16x32_bf16 v[74:77], v[174:177], v[224:227], v[74:77]
	v_mfma_f32_16x16x32_bf16 v[118:121], v[170:173], v[142:145], v[118:121]
	v_mfma_f32_16x16x32_bf16 v[110:113], v[162:165], v[142:145], v[110:113]
	v_mfma_f32_16x16x32_bf16 v[102:105], v[170:173], v[184:187], v[102:105]
	v_mfma_f32_16x16x32_bf16 v[94:97], v[162:165], v[184:187], v[94:97]
	v_mfma_f32_16x16x32_bf16 v[86:89], v[170:173], v[220:223], v[86:89]
	v_mfma_f32_16x16x32_bf16 v[82:85], v[162:165], v[220:223], v[82:85]
	v_mfma_f32_16x16x32_bf16 v[78:81], v[170:173], v[228:231], v[78:81]
	v_mfma_f32_16x16x32_bf16 v[74:77], v[162:165], v[228:231], v[74:77]
	s_setprio 0
	s_barrier
; #define PG8_SB(B) __builtin_amdgcn_rcpf(1.f + expneg(B))
; #define PG8_SB(B) __builtin_amdgcn_rcpf(1.f + expneg(B))
; #define PG8_STAGE(bufoff, gbase, voff) do { _Pragma("unroll") for (int _i = 0; _i < 2; ++_i) \
;         __builtin_amdgcn_global_load_lds((const unsigned*)((const char*)(gbase) + (size_t)_i * qstep + (voff)[0]), (PG8_LAS unsigned*)(lds + (bufoff) + ldsw + _i * 8192), 16, 0, 0); } while (0)
; #define PG8_LDA(dst, b, h) do { _Pragma("unroll") for (int m = 0; m < 4; ++m) _Pragma("unroll") for (int k = 0; k < 2; ++k) dst[m][k] = *(const PG8_LAS bf16x8*)(lds + PG8_SA(b, h) + aoff + m * 2048 + k * 1024); } while (0)
; #define PG8_MMA(ai, bj, At, Bt) do { __builtin_amdgcn_s_setprio(1); _Pragma("unroll") for (int m = 0; m < 4; ++m) _Pragma("unroll") for (int n = 0; n < 2; ++n) _Pragma("unroll") for (int k = 0; k < 2; ++k) \
;         acc[ai][bj][m][n] = __builtin_amdgcn_mfma_f32_16x16x32_bf16(Bt[n][k], At[m][k], acc[ai][bj][m][n], 0, 0, 0); __builtin_amdgcn_s_setprio(0); } while (0)
; #define PG8_WAIT_V89() do { if constexpr (SLIVER) PG8_WAIT_V(9); else PG8_WAIT_V(8); } while (0)
; #define PG8_LDS_S(b) do { if constexpr (SLIVER) { Sf[0] = *(const PG8_LAS bf16x8*)(lds + STAGE_BYTES + (b) * 2048 + soff0); Sf[1] = *(const PG8_LAS bf16x8*)(lds + STAGE_BYTES + (b) * 2048 + (soff0 ^ 64)); } } while (0)
; #define PG8_WAIT_L(n) asm volatile("s_waitcnt lgkmcnt(" #n ")" ::: "memory")
; #define PG8_BAR __builtin_amdgcn_s_barrier()
; #define PG8_SCHED __builtin_amdgcn_sched_barrier(0)
; template <class Epi, class Sched, bool ALIGN_EPI = false, bool SP2 = false, bool SLIVER = false>
; __device__ __forceinline__ void gemm_phase(PG8_LAS unsigned char* lds, const Gemm g, const Sched& S, const Epi& E) {
;     ...
;             PG8_LDA(At, 0, 1); PG8_LDS_S(0); PG8_STAGE(PG8_SB(0, 0), b2, voffB); PG8_STAGE(PG8_SB(0, 1), b2 + hstep, voffB); PG8_STAGE(PG8_SA(0, 0), a2, voffA);
;             PG8_WAIT_V89(); PG8_WAIT_L(0); PG8_BAR; PG8_MMA(1, 0, At, B0); PG8_MMA(1, 1, At, B1); PG8_MMA_S(); PG8_BAR; PG8_SCHED;
	s_add_i32 s69, 0, 0x20000
	v_lshl_add_u64 v[202:203], s[12:13], 0, v[190:191]
	s_add_i32 s12, s76, s92
	v_add_u32_e32 v178, s69, v213
	v_add_u32_e32 v184, s69, v214
	s_mov_b32 m0, s12
	ds_read_b128 v[138:141], v215 offset:16384
	ds_read_b128 v[142:145], v215 offset:17408
	ds_read_b128 v[216:219], v215 offset:18432
	ds_read_b128 v[220:223], v215 offset:19456
	ds_read_b128 v[224:227], v215 offset:20480
	ds_read_b128 v[228:231], v215 offset:21504
	ds_read_b128 v[232:235], v215 offset:22528
	ds_read_b128 v[240:243], v215 offset:23552
	ds_read_b128 v[180:183], v178
	ds_read_b128 v[184:187], v184
	global_load_lds_dwordx4 v[202:203], off
	v_lshl_add_u64 v[208:209], v[202:203], 0, s[70:71]
	s_add_i32 m0, s12, 0x2000
	s_add_i32 s12, s68, s92
	global_load_lds_dwordx4 v[208:209], off
	v_lshl_add_u64 v[208:209], v[202:203], 0, s[46:47]
	s_mov_b32 m0, s12
	v_lshl_add_u64 v[210:211], s[40:41], 0, v[188:189]
	global_load_lds_dwordx4 v[208:209], off
	v_lshl_add_u64 v[208:209], v[202:203], 0, s[6:7]
	s_add_i32 m0, s12, 0x2000
	s_nop 0
	global_load_lds_dwordx4 v[208:209], off
	s_mov_b32 m0, s93
	v_lshl_add_u64 v[208:209], v[210:211], 0, s[70:71]
	global_load_lds_dwordx4 v[210:211], off
	s_mov_b32 m0, s48
	s_nop 0
	global_load_lds_dwordx4 v[208:209], off
	s_waitcnt vmcnt(9)
	s_waitcnt lgkmcnt(0)
	s_setprio 1
	s_barrier
	v_mfma_f32_16x16x32_bf16 v[70:73], v[146:149], v[138:141], v[70:73]
	v_mfma_f32_16x16x32_bf16 v[66:69], v[154:157], v[138:141], v[66:69]
	v_mfma_f32_16x16x32_bf16 v[62:65], v[146:149], v[216:219], v[62:65]
	v_mfma_f32_16x16x32_bf16 v[58:61], v[154:157], v[216:219], v[58:61]
	v_mfma_f32_16x16x32_bf16 v[50:53], v[146:149], v[224:227], v[50:53]
	v_mfma_f32_16x16x32_bf16 v[42:45], v[154:157], v[224:227], v[42:45]
	v_mfma_f32_16x16x32_bf16 v[34:37], v[146:149], v[232:235], v[34:37]
	v_mfma_f32_16x16x32_bf16 v[26:29], v[154:157], v[232:235], v[26:29]
	v_mfma_f32_16x16x32_bf16 v[70:73], v[150:153], v[142:145], v[70:73]
	v_mfma_f32_16x16x32_bf16 v[66:69], v[158:161], v[142:145], v[66:69]
	v_mfma_f32_16x16x32_bf16 v[62:65], v[150:153], v[220:223], v[62:65]
	v_mfma_f32_16x16x32_bf16 v[58:61], v[158:161], v[220:223], v[58:61]
	v_mfma_f32_16x16x32_bf16 v[50:53], v[150:153], v[228:231], v[50:53]
	v_mfma_f32_16x16x32_bf16 v[42:45], v[158:161], v[228:231], v[42:45]
	v_mfma_f32_16x16x32_bf16 v[34:37], v[150:153], v[240:243], v[34:37]
	v_mfma_f32_16x16x32_bf16 v[26:29], v[158:161], v[240:243], v[26:29]
	s_setprio 0
	s_setprio 1
	v_mfma_f32_16x16x32_bf16 v[54:57], v[166:169], v[138:141], v[54:57]
	v_mfma_f32_16x16x32_bf16 v[46:49], v[174:177], v[138:141], v[46:49]
	v_mfma_f32_16x16x32_bf16 v[38:41], v[166:169], v[216:219], v[38:41]
	v_mfma_f32_16x16x32_bf16 v[30:33], v[174:177], v[216:219], v[30:33]
	v_mfma_f32_16x16x32_bf16 v[22:25], v[166:169], v[224:227], v[22:25]
	v_mfma_f32_16x16x32_bf16 v[18:21], v[174:177], v[224:227], v[18:21]
	v_mfma_f32_16x16x32_bf16 v[14:17], v[166:169], v[232:235], v[14:17]
	v_mfma_f32_16x16x32_bf16 v[10:13], v[174:177], v[232:235], v[10:13]
	v_mfma_f32_16x16x32_bf16 v[54:57], v[170:173], v[142:145], v[54:57]
	v_mfma_f32_16x16x32_bf16 v[46:49], v[162:165], v[142:145], v[46:49]
	v_mfma_f32_16x16x32_bf16 v[38:41], v[170:173], v[220:223], v[38:41]
	v_mfma_f32_16x16x32_bf16 v[30:33], v[162:165], v[220:223], v[30:33]
	v_mfma_f32_16x16x32_bf16 v[22:25], v[170:173], v[228:231], v[22:25]
	v_mfma_f32_16x16x32_bf16 v[18:21], v[162:165], v[228:231], v[18:21]
	v_mfma_f32_16x16x32_bf16 v[14:17], v[170:173], v[240:243], v[14:17]
	v_mfma_f32_16x16x32_bf16 v[10:13], v[162:165], v[240:243], v[10:13]
	s_setprio 0
	s_setprio 1
	v_cndmask_b32_e64 v138, 0, 1, s[90:91]
	v_cmp_ne_u32_e64 s[40:41], 1, v138
	s_andn2_b64 vcc, exec, s[90:91]
	s_mov_b64 s[12:13], -1
	s_cbranch_vccnz .LBB0_936
	v_mfma_f32_16x16x32_bf16 v[138:141], v[166:169], v[180:183], v[6:9]
	s_mov_b64 s[12:13], 0
	v_mfma_f32_16x16x32_bf16 v[142:145], v[174:177], v[180:183], v[2:5]
	v_mfma_f32_16x16x32_bf16 v[138:141], v[170:173], v[184:187], v[138:141]
	v_mfma_f32_16x16x32_bf16 v[142:145], v[162:165], v[184:187], v[142:145]

; #define PG8_STAGE(bufoff, gbase, voff) do { _Pragma("unroll") for (int _i = 0; _i < 2; ++_i) \
;         __builtin_amdgcn_global_load_lds((const unsigned*)((const char*)(gbase) + (size_t)_i * qstep + (voff)[0]), (PG8_LAS unsigned*)(lds + (bufoff) + ldsw + _i * 8192), 16, 0, 0); } while (0)
; #define PG8_LDA(dst, b, h) do { _Pragma("unroll") for (int m = 0; m < 4; ++m) _Pragma("unroll") for (int k = 0; k < 2; ++k) dst[m][k] = *(const PG8_LAS bf16x8*)(lds + PG8_SA(b, h) + aoff + m * 2048 + k * 1024); } while (0)
; #define PG8_LDB(dst, b, h) do { _Pragma("unroll") for (int n = 0; n < 2; ++n) _Pragma("unroll") for (int k = 0; k < 2; ++k) dst[n][k] = *(const PG8_LAS bf16x8*)(lds + PG8_SB(b, h) + boff + n * 2048 + k * 1024); } while (0)
; #define PG8_MMA(ai, bj, At, Bt) do { __builtin_amdgcn_s_setprio(1); _Pragma("unroll") for (int m = 0; m < 4; ++m) _Pragma("unroll") for (int n = 0; n < 2; ++n) _Pragma("unroll") for (int k = 0; k < 2; ++k) \
;         acc[ai][bj][m][n] = __builtin_amdgcn_mfma_f32_16x16x32_bf16(Bt[n][k], At[m][k], acc[ai][bj][m][n], 0, 0, 0); __builtin_amdgcn_s_setprio(0); } while (0)
; #define PG8_WAIT_V89() do { if constexpr (SLIVER) PG8_WAIT_V(9); else PG8_WAIT_V(8); } while (0)
; #define PG8_STAGE_S(b, gbase) do { if constexpr (SLIVER) __builtin_amdgcn_global_load_lds((const unsigned*)((const char*)(gbase) + voffS), (PG8_LAS unsigned*)(lds + STAGE_BYTES + (b) * 2048 + wid * 256), 4, 0, 0); } while (0)
; #define PG8_WAIT_L(n) asm volatile("s_waitcnt lgkmcnt(" #n ")" ::: "memory")
; #define PG8_BAR __builtin_amdgcn_s_barrier()
; #define PG8_SCHED __builtin_amdgcn_sched_barrier(0)
; template <class Epi, class Sched, bool ALIGN_EPI = false, bool SP2 = false, bool SLIVER = false>
; __device__ __forceinline__ void gemm_phase(PG8_LAS unsigned char* lds, const Gemm g, const Sched& S, const Epi& E) {
;     ...
;             PG8_LDB(B0, 1, 0); PG8_LDB(B1, 1, 1); PG8_SCHED; PG8_LDA(At, 1, 0); PG8_STAGE(PG8_SA(0, 1), a2 + hstep, voffA); PG8_STAGE_S(0, s2);
;             PG8_WAIT_V89(); PG8_WAIT_L(0); PG8_BAR; PG8_MMA(0, 0, At, B0); PG8_MMA(0, 1, At, B1); PG8_BAR; PG8_SCHED;
.LBB0_938:
	s_add_u32 s12, s54, s62
	s_addc_u32 s13, s55, s63
	s_add_u32 s68, s12, 0x100
	s_addc_u32 s69, s13, 0
	s_and_b64 s[12:13], s[80:81], exec
	s_cselect_b32 s13, s19, s69
	s_cselect_b32 s12, s18, s68
	s_setprio 0
	s_barrier
	s_add_i32 s68, 0, 0x18000
	v_add_u32_e32 v2, s68, v212
	s_add_i32 s69, 0, 0x1c000
	ds_read_b128 v[146:149], v2
	ds_read_b128 v[150:153], v2 offset:1024
	ds_read_b128 v[154:157], v2 offset:2048
	ds_read_b128 v[158:161], v2 offset:3072
	v_add_u32_e32 v2, s69, v212
	ds_read_b128 v[166:169], v2
	ds_read_b128 v[170:173], v2 offset:1024
	ds_read_b128 v[174:177], v2 offset:2048
	ds_read_b128 v[162:165], v2 offset:3072
	s_mov_b32 m0, s49
	v_lshl_add_u64 v[208:209], v[210:211], 0, s[46:47]
	ds_read_b128 v[2:5], v215 offset:32768
	ds_read_b128 v[6:9], v215 offset:33792
	ds_read_b128 v[180:183], v215 offset:34816
	ds_read_b128 v[184:187], v215 offset:35840
	ds_read_b128 v[216:219], v215 offset:36864
	ds_read_b128 v[220:223], v215 offset:37888
	ds_read_b128 v[224:227], v215 offset:38912
	ds_read_b128 v[228:231], v215 offset:39936
	global_load_lds_dwordx4 v[208:209], off
	v_lshl_add_u64 v[208:209], v[210:211], 0, s[6:7]
	s_mov_b32 m0, s88
	s_nop 0
	global_load_lds_dwordx4 v[208:209], off
	v_lshl_add_u64 v[208:209], s[12:13], 0, v[192:193]
	s_mov_b32 m0, s89
	s_nop 0
	global_load_lds_dword v[208:209], off
	s_waitcnt vmcnt(9)
	s_waitcnt lgkmcnt(0)
	s_setprio 1
	s_barrier
	v_mfma_f32_16x16x32_bf16 v[134:137], v[146:149], v[2:5], v[134:137]
	v_mfma_f32_16x16x32_bf16 v[130:133], v[154:157], v[2:5], v[130:133]
	v_mfma_f32_16x16x32_bf16 v[126:129], v[146:149], v[180:183], v[126:129]
	v_mfma_f32_16x16x32_bf16 v[122:125], v[154:157], v[180:183], v[122:125]
	v_mfma_f32_16x16x32_bf16 v[114:117], v[146:149], v[216:219], v[114:117]
	v_mfma_f32_16x16x32_bf16 v[106:109], v[154:157], v[216:219], v[106:109]
	v_mfma_f32_16x16x32_bf16 v[98:101], v[146:149], v[224:227], v[98:101]
	v_mfma_f32_16x16x32_bf16 v[90:93], v[154:157], v[224:227], v[90:93]
	v_mfma_f32_16x16x32_bf16 v[134:137], v[150:153], v[6:9], v[134:137]
	v_mfma_f32_16x16x32_bf16 v[130:133], v[158:161], v[6:9], v[130:133]
	v_mfma_f32_16x16x32_bf16 v[126:129], v[150:153], v[184:187], v[126:129]
	v_mfma_f32_16x16x32_bf16 v[122:125], v[158:161], v[184:187], v[122:125]
	v_mfma_f32_16x16x32_bf16 v[114:117], v[150:153], v[220:223], v[114:117]
	v_mfma_f32_16x16x32_bf16 v[106:109], v[158:161], v[220:223], v[106:109]
	v_mfma_f32_16x16x32_bf16 v[98:101], v[150:153], v[228:231], v[98:101]
	v_mfma_f32_16x16x32_bf16 v[90:93], v[158:161], v[228:231], v[90:93]
	s_setprio 0
	s_setprio 1
	v_mfma_f32_16x16x32_bf16 v[118:121], v[166:169], v[2:5], v[118:121]
	v_mfma_f32_16x16x32_bf16 v[2:5], v[174:177], v[2:5], v[110:113]
	v_mfma_f32_16x16x32_bf16 v[110:113], v[162:165], v[6:9], v[2:5]
	v_mfma_f32_16x16x32_bf16 v[2:5], v[166:169], v[180:183], v[102:105]
	v_mfma_f32_16x16x32_bf16 v[102:105], v[170:173], v[184:187], v[2:5]
	v_mfma_f32_16x16x32_bf16 v[2:5], v[174:177], v[180:183], v[94:97]
	v_mfma_f32_16x16x32_bf16 v[94:97], v[162:165], v[184:187], v[2:5]
	v_mfma_f32_16x16x32_bf16 v[2:5], v[166:169], v[216:219], v[86:89]
	v_mfma_f32_16x16x32_bf16 v[86:89], v[170:173], v[220:223], v[2:5]
	v_mfma_f32_16x16x32_bf16 v[2:5], v[174:177], v[216:219], v[82:85]
	v_mfma_f32_16x16x32_bf16 v[82:85], v[162:165], v[220:223], v[2:5]
	v_mfma_f32_16x16x32_bf16 v[2:5], v[166:169], v[224:227], v[78:81]
	v_mfma_f32_16x16x32_bf16 v[78:81], v[170:173], v[228:231], v[2:5]
	v_mfma_f32_16x16x32_bf16 v[2:5], v[174:177], v[224:227], v[74:77]
	v_mfma_f32_16x16x32_bf16 v[118:121], v[170:173], v[6:9], v[118:121]
	v_mfma_f32_16x16x32_bf16 v[74:77], v[162:165], v[228:231], v[2:5]
	s_setprio 0
	s_barrier
; #define PG8_SB(B) __builtin_amdgcn_rcpf(1.f + expneg(B))
; #define PG8_SB(B) __builtin_amdgcn_rcpf(1.f + expneg(B))
; #define PG8_STAGE(bufoff, gbase, voff) do { _Pragma("unroll") for (int _i = 0; _i < 2; ++_i) \
;         __builtin_amdgcn_global_load_lds((const unsigned*)((const char*)(gbase) + (size_t)_i * qstep + (voff)[0]), (PG8_LAS unsigned*)(lds + (bufoff) + ldsw + _i * 8192), 16, 0, 0); } while (0)
; #define PG8_LDA(dst, b, h) do { _Pragma("unroll") for (int m = 0; m < 4; ++m) _Pragma("unroll") for (int k = 0; k < 2; ++k) dst[m][k] = *(const PG8_LAS bf16x8*)(lds + PG8_SA(b, h) + aoff + m * 2048 + k * 1024); } while (0)
; #define PG8_MMA(ai, bj, At, Bt) do { __builtin_amdgcn_s_setprio(1); _Pragma("unroll") for (int m = 0; m < 4; ++m) _Pragma("unroll") for (int n = 0; n < 2; ++n) _Pragma("unroll") for (int k = 0; k < 2; ++k) \
;         acc[ai][bj][m][n] = __builtin_amdgcn_mfma_f32_16x16x32_bf16(Bt[n][k], At[m][k], acc[ai][bj][m][n], 0, 0, 0); __builtin_amdgcn_s_setprio(0); } while (0)
; #define PG8_WAIT_V89() do { if constexpr (SLIVER) PG8_WAIT_V(9); else PG8_WAIT_V(8); } while (0)
; #define PG8_LDS_S(b) do { if constexpr (SLIVER) { Sf[0] = *(const PG8_LAS bf16x8*)(lds + STAGE_BYTES + (b) * 2048 + soff0); Sf[1] = *(const PG8_LAS bf16x8*)(lds + STAGE_BYTES + (b) * 2048 + (soff0 ^ 64)); } } while (0)
; #define PG8_WAIT_L(n) asm volatile("s_waitcnt lgkmcnt(" #n ")" ::: "memory")
; #define PG8_BAR __builtin_amdgcn_s_barrier()
; #define PG8_SCHED __builtin_amdgcn_sched_barrier(0)
; template <class Epi, class Sched, bool ALIGN_EPI = false, bool SP2 = false, bool SLIVER = false>
; __device__ __forceinline__ void gemm_phase(PG8_LAS unsigned char* lds, const Gemm g, const Sched& S, const Epi& E) {
;     ...
;             PG8_LDA(At, 1, 1); PG8_LDS_S(1); PG8_STAGE(PG8_SB(1, 0), b3, voffB); PG8_STAGE(PG8_SB(1, 1), b3 + hstep, voffB); PG8_STAGE(PG8_SA(1, 0), a3, voffA);
;             PG8_WAIT_V89(); PG8_WAIT_L(0); PG8_BAR; PG8_MMA(1, 0, At, B0); PG8_MMA(1, 1, At, B1); PG8_MMA_S(); PG8_BAR; PG8_SCHED;
	s_add_i32 s12, 0, 0x20800
	v_add_u32_e32 v178, s12, v213
	v_add_u32_e32 v184, s12, v214
	s_add_i32 s12, s68, s92
	v_lshl_add_u64 v[208:209], v[202:203], 0, s[26:27]
	s_mov_b32 m0, s12
	ds_read_b128 v[2:5], v215 offset:49152
	ds_read_b128 v[6:9], v215 offset:50176
	ds_read_b128 v[216:219], v215 offset:51200
	ds_read_b128 v[220:223], v215 offset:52224
	ds_read_b128 v[224:227], v215 offset:53248
	ds_read_b128 v[228:231], v215 offset:54272
	ds_read_b128 v[232:235], v215 offset:55296
	ds_read_b128 v[240:243], v215 offset:56320
	ds_read_b128 v[180:183], v178
	ds_read_b128 v[184:187], v184
	global_load_lds_dwordx4 v[208:209], off
	v_lshl_add_u64 v[208:209], v[202:203], 0, s[58:59]
	s_add_i32 m0, s12, 0x2000
	s_mov_b64 s[12:13], 0x90080
	global_load_lds_dwordx4 v[208:209], off
	v_lshl_add_u64 v[208:209], v[202:203], 0, s[12:13]
	s_add_i32 s12, s69, s92
	s_mov_b32 m0, s12
	s_mov_b64 s[68:69], 0xd8080
	global_load_lds_dwordx4 v[208:209], off
	v_lshl_add_u64 v[202:203], v[202:203], 0, s[68:69]
	s_add_i32 m0, s12, 0x2000
	s_nop 0
	global_load_lds_dwordx4 v[202:203], off
	v_lshl_add_u64 v[202:203], v[210:211], 0, s[26:27]
	s_mov_b32 m0, s51
	s_nop 0
	global_load_lds_dwordx4 v[202:203], off
	v_lshl_add_u64 v[202:203], v[210:211], 0, s[58:59]
	s_mov_b32 m0, s53
	s_nop 0
	global_load_lds_dwordx4 v[202:203], off
	s_waitcnt vmcnt(9)
	s_waitcnt lgkmcnt(0)
	s_setprio 1
	s_barrier
	v_mfma_f32_16x16x32_bf16 v[70:73], v[146:149], v[2:5], v[70:73]
	v_mfma_f32_16x16x32_bf16 v[66:69], v[154:157], v[2:5], v[66:69]
	v_mfma_f32_16x16x32_bf16 v[62:65], v[146:149], v[216:219], v[62:65]
	v_mfma_f32_16x16x32_bf16 v[58:61], v[154:157], v[216:219], v[58:61]
	v_mfma_f32_16x16x32_bf16 v[50:53], v[146:149], v[224:227], v[50:53]
	v_mfma_f32_16x16x32_bf16 v[42:45], v[154:157], v[224:227], v[42:45]
	v_mfma_f32_16x16x32_bf16 v[34:37], v[146:149], v[232:235], v[34:37]
	v_mfma_f32_16x16x32_bf16 v[26:29], v[154:157], v[232:235], v[26:29]
	v_mfma_f32_16x16x32_bf16 v[70:73], v[150:153], v[6:9], v[70:73]
	v_mfma_f32_16x16x32_bf16 v[66:69], v[158:161], v[6:9], v[66:69]
	v_mfma_f32_16x16x32_bf16 v[62:65], v[150:153], v[220:223], v[62:65]
	v_mfma_f32_16x16x32_bf16 v[58:61], v[158:161], v[220:223], v[58:61]
	v_mfma_f32_16x16x32_bf16 v[50:53], v[150:153], v[228:231], v[50:53]
	v_mfma_f32_16x16x32_bf16 v[42:45], v[158:161], v[228:231], v[42:45]
	v_mfma_f32_16x16x32_bf16 v[34:37], v[150:153], v[240:243], v[34:37]
	v_mfma_f32_16x16x32_bf16 v[26:29], v[158:161], v[240:243], v[26:29]
	s_setprio 0
	s_setprio 1
	v_mfma_f32_16x16x32_bf16 v[54:57], v[166:169], v[2:5], v[54:57]
	v_mfma_f32_16x16x32_bf16 v[2:5], v[174:177], v[2:5], v[46:49]
	v_mfma_f32_16x16x32_bf16 v[46:49], v[162:165], v[6:9], v[2:5]
	v_mfma_f32_16x16x32_bf16 v[2:5], v[166:169], v[216:219], v[38:41]
	v_mfma_f32_16x16x32_bf16 v[38:41], v[170:173], v[220:223], v[2:5]
	v_mfma_f32_16x16x32_bf16 v[2:5], v[174:177], v[216:219], v[30:33]
	v_mfma_f32_16x16x32_bf16 v[30:33], v[162:165], v[220:223], v[2:5]
	v_mfma_f32_16x16x32_bf16 v[2:5], v[166:169], v[224:227], v[22:25]
	v_mfma_f32_16x16x32_bf16 v[22:25], v[170:173], v[228:231], v[2:5]
	v_mfma_f32_16x16x32_bf16 v[2:5], v[174:177], v[224:227], v[18:21]
	v_mfma_f32_16x16x32_bf16 v[18:21], v[162:165], v[228:231], v[2:5]
	v_mfma_f32_16x16x32_bf16 v[2:5], v[166:169], v[232:235], v[14:17]
	v_mfma_f32_16x16x32_bf16 v[14:17], v[170:173], v[240:243], v[2:5]
	v_mfma_f32_16x16x32_bf16 v[2:5], v[174:177], v[232:235], v[10:13]
	v_mfma_f32_16x16x32_bf16 v[54:57], v[170:173], v[6:9], v[54:57]
	v_mfma_f32_16x16x32_bf16 v[10:13], v[162:165], v[240:243], v[2:5]
	s_setprio 0
	s_setprio 1
	s_and_b64 vcc, exec, s[40:41]
	s_mov_b64 s[12:13], -1
	s_cbranch_vccnz .LBB0_940
	v_mfma_f32_16x16x32_bf16 v[2:5], v[166:169], v[180:183], v[138:141]
	s_mov_b64 s[12:13], 0
	v_mfma_f32_16x16x32_bf16 v[6:9], v[170:173], v[184:187], v[2:5]
	v_mfma_f32_16x16x32_bf16 v[2:5], v[174:177], v[180:183], v[142:145]
	v_mfma_f32_16x16x32_bf16 v[2:5], v[162:165], v[184:187], v[2:5]
